# GEMM loops: phase-1 LDS-DMA loads also in SGPR-base form (no VALU left in the K-loops except KV)
# speedup vs baseline: 1.0268x; 1.0040x over previous
.LBB0_252:
	s_add_u32 s0, s0, 0x80
	s_addc_u32 s1, s1, 0
	s_add_u32 s47, s4, 0x100
	s_addc_u32 s48, s5, 0
	s_mov_b32 s4, 0
	s_waitcnt lgkmcnt(0)
	s_waitcnt vmcnt(0)
	s_add_i32 s49, s4, 2
	s_add_u32 s16, s0, 0x80
	s_addc_u32 s5, s1, 0
	s_add_i32 s65, 0, 0x10000
	ds_read_b128 v[148:151], v248
	ds_read_b128 v[152:155], v248 offset:1024
	ds_read_b128 v[156:159], v248 offset:2048
	ds_read_b128 v[160:163], v248 offset:3072
	s_cmp_eq_u32 s41, s4
	s_cselect_b32 s4, s10, s16
	s_cselect_b32 s5, s11, s5
	s_cselect_b32 s17, s13, s48
	s_cselect_b32 s16, s12, s47
	s_add_i32 m0, s26, 0xc000
	ds_read_b128 v[164:167], v146
	ds_read_b128 v[168:171], v146 offset:1024
	ds_read_b128 v[172:175], v146 offset:2048
	ds_read_b128 v[176:179], v146 offset:3072
	ds_read_b128 v[180:183], v146 offset:4096
	ds_read_b128 v[204:207], v146 offset:5120
	ds_read_b128 v[208:211], v146 offset:6144
	ds_read_b128 v[212:215], v146 offset:7168
	global_load_lds_dwordx4 v138, s[0:1]
	s_add_i32 m0, s26, 0xe000
	s_nop 0
	global_load_lds_dwordx4 v140, s[0:1]
	s_waitcnt lgkmcnt(8)
	s_barrier
	s_waitcnt lgkmcnt(0)
	v_mfma_f32_16x16x32_bf16 v[126:129], v[148:151], v[164:167], 0
	v_mfma_f32_16x16x32_bf16 v[122:125], v[156:159], v[164:167], 0
	v_mfma_f32_16x16x32_bf16 v[110:113], v[148:151], v[172:175], 0
	v_mfma_f32_16x16x32_bf16 v[106:109], v[156:159], v[172:175], 0
	v_mfma_f32_16x16x32_bf16 v[94:97], v[148:151], v[180:183], 0
	v_mfma_f32_16x16x32_bf16 v[90:93], v[156:159], v[180:183], 0
	v_mfma_f32_16x16x32_bf16 v[78:81], v[148:151], v[208:211], 0
	v_mfma_f32_16x16x32_bf16 v[74:77], v[156:159], v[208:211], 0
	v_mfma_f32_16x16x32_bf16 v[126:129], v[152:155], v[168:171], v[126:129]
	v_mfma_f32_16x16x32_bf16 v[122:125], v[160:163], v[168:171], v[122:125]
	v_mfma_f32_16x16x32_bf16 v[110:113], v[152:155], v[176:179], v[110:113]
	v_mfma_f32_16x16x32_bf16 v[106:109], v[160:163], v[176:179], v[106:109]
	v_mfma_f32_16x16x32_bf16 v[94:97], v[152:155], v[204:207], v[94:97]
	v_mfma_f32_16x16x32_bf16 v[90:93], v[160:163], v[204:207], v[90:93]
	v_mfma_f32_16x16x32_bf16 v[78:81], v[152:155], v[212:215], v[78:81]
	v_mfma_f32_16x16x32_bf16 v[74:77], v[160:163], v[212:215], v[74:77]
	s_barrier
	s_add_i32 s66, 0, 0x14000
	s_add_i32 s65, s65, s24
	ds_read_b128 v[216:219], v248 offset:16384
	ds_read_b128 v[220:223], v248 offset:17408
	ds_read_b128 v[224:227], v248 offset:18432
	ds_read_b128 v[228:231], v248 offset:19456
	s_add_u32 s70, s16, s6
	s_addc_u32 s71, s17, s7
	s_mov_b32 m0, s65
	s_nop 0
	global_load_lds_dwordx4 v132, s[16:17]
	s_add_i32 m0, s65, 0x2000
	s_nop 0
	global_load_lds_dwordx4 v136, s[16:17]
	s_barrier
	s_waitcnt lgkmcnt(0)
	v_mfma_f32_16x16x32_bf16 v[114:117], v[216:219], v[164:167], 0
	v_mfma_f32_16x16x32_bf16 v[118:121], v[224:227], v[164:167], 0
	v_mfma_f32_16x16x32_bf16 v[98:101], v[216:219], v[172:175], 0
	v_mfma_f32_16x16x32_bf16 v[102:105], v[224:227], v[172:175], 0
	v_mfma_f32_16x16x32_bf16 v[82:85], v[216:219], v[180:183], 0
	v_mfma_f32_16x16x32_bf16 v[86:89], v[224:227], v[180:183], 0
	v_mfma_f32_16x16x32_bf16 v[66:69], v[216:219], v[208:211], 0
	v_mfma_f32_16x16x32_bf16 v[70:73], v[224:227], v[208:211], 0
	v_mfma_f32_16x16x32_bf16 v[114:117], v[220:223], v[168:171], v[114:117]
	v_mfma_f32_16x16x32_bf16 v[118:121], v[228:231], v[168:171], v[118:121]
	v_mfma_f32_16x16x32_bf16 v[98:101], v[220:223], v[176:179], v[98:101]
	v_mfma_f32_16x16x32_bf16 v[102:105], v[228:231], v[176:179], v[102:105]
	v_mfma_f32_16x16x32_bf16 v[82:85], v[220:223], v[204:207], v[82:85]
	v_mfma_f32_16x16x32_bf16 v[86:89], v[228:231], v[204:207], v[86:89]
	v_mfma_f32_16x16x32_bf16 v[66:69], v[220:223], v[212:215], v[66:69]
	v_mfma_f32_16x16x32_bf16 v[70:73], v[228:231], v[212:215], v[70:73]
	s_barrier
	s_mov_b32 m0, s26
	s_add_u32 s72, s4, s6
	s_addc_u32 s73, s5, s7
	ds_read_b128 v[164:167], v146 offset:16384
	ds_read_b128 v[168:171], v146 offset:17408
	ds_read_b128 v[172:175], v146 offset:18432
	ds_read_b128 v[176:179], v146 offset:19456
	ds_read_b128 v[180:183], v146 offset:20480
	ds_read_b128 v[204:207], v146 offset:21504
	ds_read_b128 v[208:211], v146 offset:22528
	ds_read_b128 v[212:215], v146 offset:23552
	global_load_lds_dwordx4 v130, s[4:5]
	s_mov_b32 m0, s27
	s_nop 0
	global_load_lds_dwordx4 v134, s[4:5]
	s_barrier
	s_waitcnt lgkmcnt(0)
	v_mfma_f32_16x16x32_bf16 v[62:65], v[148:151], v[164:167], 0
	v_mfma_f32_16x16x32_bf16 v[58:61], v[156:159], v[164:167], 0
	v_mfma_f32_16x16x32_bf16 v[46:49], v[148:151], v[172:175], 0
	v_mfma_f32_16x16x32_bf16 v[42:45], v[156:159], v[172:175], 0
	v_mfma_f32_16x16x32_bf16 v[30:33], v[148:151], v[180:183], 0
	v_mfma_f32_16x16x32_bf16 v[26:29], v[156:159], v[180:183], 0
	v_mfma_f32_16x16x32_bf16 v[14:17], v[148:151], v[208:211], 0
	v_mfma_f32_16x16x32_bf16 v[10:13], v[156:159], v[208:211], 0
	v_mfma_f32_16x16x32_bf16 v[62:65], v[152:155], v[168:171], v[62:65]
	v_mfma_f32_16x16x32_bf16 v[58:61], v[160:163], v[168:171], v[58:61]
	v_mfma_f32_16x16x32_bf16 v[46:49], v[152:155], v[176:179], v[46:49]
	v_mfma_f32_16x16x32_bf16 v[42:45], v[160:163], v[176:179], v[42:45]
	v_mfma_f32_16x16x32_bf16 v[30:33], v[152:155], v[204:207], v[30:33]
	v_mfma_f32_16x16x32_bf16 v[26:29], v[160:163], v[204:207], v[26:29]
	v_mfma_f32_16x16x32_bf16 v[14:17], v[152:155], v[212:215], v[14:17]
	v_mfma_f32_16x16x32_bf16 v[10:13], v[160:163], v[212:215], v[10:13]
	s_barrier
	s_add_u32 s16, s16, s92
	s_addc_u32 s17, s17, 0
	s_add_i32 s65, s66, s24
	s_add_u32 s76, s16, s6
	s_addc_u32 s77, s17, s7
	s_mov_b32 m0, s65
	s_nop 0
	global_load_lds_dwordx4 v132, s[16:17]
	s_add_i32 m0, s65, 0x2000
	s_nop 0
	global_load_lds_dwordx4 v136, s[16:17]
	s_waitcnt vmcnt(6)
	s_barrier
	v_mfma_f32_16x16x32_bf16 v[50:53], v[216:219], v[164:167], 0
	v_mfma_f32_16x16x32_bf16 v[54:57], v[224:227], v[164:167], 0
	v_mfma_f32_16x16x32_bf16 v[34:37], v[216:219], v[172:175], 0
	v_mfma_f32_16x16x32_bf16 v[38:41], v[224:227], v[172:175], 0
	v_mfma_f32_16x16x32_bf16 v[18:21], v[216:219], v[180:183], 0
	v_mfma_f32_16x16x32_bf16 v[22:25], v[224:227], v[180:183], 0
	v_mfma_f32_16x16x32_bf16 v[6:9], v[216:219], v[208:211], 0
	v_mfma_f32_16x16x32_bf16 v[2:5], v[224:227], v[208:211], 0
	v_mfma_f32_16x16x32_bf16 v[50:53], v[220:223], v[168:171], v[50:53]
	v_mfma_f32_16x16x32_bf16 v[54:57], v[228:231], v[168:171], v[54:57]
	v_mfma_f32_16x16x32_bf16 v[34:37], v[220:223], v[176:179], v[34:37]
	v_mfma_f32_16x16x32_bf16 v[38:41], v[228:231], v[176:179], v[38:41]
	v_mfma_f32_16x16x32_bf16 v[18:21], v[220:223], v[204:207], v[18:21]
	v_mfma_f32_16x16x32_bf16 v[22:25], v[228:231], v[204:207], v[22:25]
	v_mfma_f32_16x16x32_bf16 v[6:9], v[220:223], v[212:215], v[6:9]
	v_mfma_f32_16x16x32_bf16 v[2:5], v[228:231], v[212:215], v[2:5]
	s_barrier
	s_add_i32 s16, 0, 0x18000
	ds_read_b128 v[148:151], v248 offset:32768
	ds_read_b128 v[152:155], v248 offset:33792
	ds_read_b128 v[156:159], v248 offset:34816
	ds_read_b128 v[160:163], v248 offset:35840
	s_add_u32 s4, s4, s92
	s_addc_u32 s5, s5, 0
	s_mov_b32 m0, s28
	ds_read_b128 v[164:167], v146 offset:32768
	ds_read_b128 v[168:171], v146 offset:33792
	ds_read_b128 v[172:175], v146 offset:34816
	ds_read_b128 v[176:179], v146 offset:35840
	ds_read_b128 v[180:183], v146 offset:36864
	ds_read_b128 v[204:207], v146 offset:37888
	ds_read_b128 v[208:211], v146 offset:38912
	ds_read_b128 v[212:215], v146 offset:39936
	global_load_lds_dwordx4 v130, s[4:5]
	s_mov_b32 m0, s29
	s_nop 0
	global_load_lds_dwordx4 v134, s[4:5]
	s_waitcnt lgkmcnt(8)
	s_barrier
	s_waitcnt lgkmcnt(0)
	v_mfma_f32_16x16x32_bf16 v[126:129], v[148:151], v[164:167], v[126:129]
	v_mfma_f32_16x16x32_bf16 v[122:125], v[156:159], v[164:167], v[122:125]
	v_mfma_f32_16x16x32_bf16 v[110:113], v[148:151], v[172:175], v[110:113]
	v_mfma_f32_16x16x32_bf16 v[106:109], v[156:159], v[172:175], v[106:109]
	v_mfma_f32_16x16x32_bf16 v[94:97], v[148:151], v[180:183], v[94:97]
	v_mfma_f32_16x16x32_bf16 v[90:93], v[156:159], v[180:183], v[90:93]
	v_mfma_f32_16x16x32_bf16 v[78:81], v[148:151], v[208:211], v[78:81]
	v_mfma_f32_16x16x32_bf16 v[74:77], v[156:159], v[208:211], v[74:77]
	v_mfma_f32_16x16x32_bf16 v[126:129], v[152:155], v[168:171], v[126:129]
	v_mfma_f32_16x16x32_bf16 v[122:125], v[160:163], v[168:171], v[122:125]
	v_mfma_f32_16x16x32_bf16 v[110:113], v[152:155], v[176:179], v[110:113]
	v_mfma_f32_16x16x32_bf16 v[106:109], v[160:163], v[176:179], v[106:109]
	v_mfma_f32_16x16x32_bf16 v[94:97], v[152:155], v[204:207], v[94:97]
	v_mfma_f32_16x16x32_bf16 v[90:93], v[160:163], v[204:207], v[90:93]
	v_mfma_f32_16x16x32_bf16 v[78:81], v[152:155], v[212:215], v[78:81]
	v_mfma_f32_16x16x32_bf16 v[74:77], v[160:163], v[212:215], v[74:77]
	s_barrier
	s_add_i32 s4, 0, 0x1c000
	s_add_i32 s5, s16, s24
	s_mov_b32 m0, s5
	ds_read_b128 v[216:219], v248 offset:49152
	ds_read_b128 v[220:223], v248 offset:50176
	ds_read_b128 v[224:227], v248 offset:51200
	ds_read_b128 v[228:231], v248 offset:52224
	global_load_lds_dwordx4 v132, s[70:71]
	s_add_i32 m0, s5, 0x2000
	s_nop 0
	global_load_lds_dwordx4 v136, s[70:71]
	s_barrier
	s_waitcnt lgkmcnt(0)
	v_mfma_f32_16x16x32_bf16 v[114:117], v[216:219], v[164:167], v[114:117]
	v_mfma_f32_16x16x32_bf16 v[118:121], v[224:227], v[164:167], v[118:121]
	v_mfma_f32_16x16x32_bf16 v[98:101], v[216:219], v[172:175], v[98:101]
	v_mfma_f32_16x16x32_bf16 v[102:105], v[224:227], v[172:175], v[102:105]
	v_mfma_f32_16x16x32_bf16 v[82:85], v[216:219], v[180:183], v[82:85]
	v_mfma_f32_16x16x32_bf16 v[86:89], v[224:227], v[180:183], v[86:89]
	v_mfma_f32_16x16x32_bf16 v[66:69], v[216:219], v[208:211], v[66:69]
	v_mfma_f32_16x16x32_bf16 v[70:73], v[224:227], v[208:211], v[70:73]
	v_mfma_f32_16x16x32_bf16 v[114:117], v[220:223], v[168:171], v[114:117]
	v_mfma_f32_16x16x32_bf16 v[118:121], v[228:231], v[168:171], v[118:121]
	v_mfma_f32_16x16x32_bf16 v[98:101], v[220:223], v[176:179], v[98:101]
	v_mfma_f32_16x16x32_bf16 v[102:105], v[228:231], v[176:179], v[102:105]
	v_mfma_f32_16x16x32_bf16 v[82:85], v[220:223], v[204:207], v[82:85]
	v_mfma_f32_16x16x32_bf16 v[86:89], v[228:231], v[204:207], v[86:89]
	v_mfma_f32_16x16x32_bf16 v[66:69], v[220:223], v[212:215], v[66:69]
	v_mfma_f32_16x16x32_bf16 v[70:73], v[228:231], v[212:215], v[70:73]
	s_barrier
	s_mov_b32 m0, s35
	ds_read_b128 v[164:167], v146 offset:49152
	ds_read_b128 v[168:171], v146 offset:50176
	ds_read_b128 v[172:175], v146 offset:51200
	ds_read_b128 v[176:179], v146 offset:52224
	ds_read_b128 v[180:183], v146 offset:53248
	ds_read_b128 v[204:207], v146 offset:54272
	ds_read_b128 v[208:211], v146 offset:55296
	ds_read_b128 v[212:215], v146 offset:56320
	global_load_lds_dwordx4 v130, s[72:73]
	s_mov_b32 m0, s40
	s_nop 0
	global_load_lds_dwordx4 v134, s[72:73]
	s_barrier
	s_waitcnt lgkmcnt(0)
	v_mfma_f32_16x16x32_bf16 v[62:65], v[148:151], v[164:167], v[62:65]
	v_mfma_f32_16x16x32_bf16 v[58:61], v[156:159], v[164:167], v[58:61]
	v_mfma_f32_16x16x32_bf16 v[46:49], v[148:151], v[172:175], v[46:49]
	v_mfma_f32_16x16x32_bf16 v[42:45], v[156:159], v[172:175], v[42:45]
	v_mfma_f32_16x16x32_bf16 v[30:33], v[148:151], v[180:183], v[30:33]
	v_mfma_f32_16x16x32_bf16 v[26:29], v[156:159], v[180:183], v[26:29]
	v_mfma_f32_16x16x32_bf16 v[14:17], v[148:151], v[208:211], v[14:17]
	v_mfma_f32_16x16x32_bf16 v[10:13], v[156:159], v[208:211], v[10:13]
	v_mfma_f32_16x16x32_bf16 v[62:65], v[152:155], v[168:171], v[62:65]
	v_mfma_f32_16x16x32_bf16 v[58:61], v[160:163], v[168:171], v[58:61]
	v_mfma_f32_16x16x32_bf16 v[46:49], v[152:155], v[176:179], v[46:49]
	v_mfma_f32_16x16x32_bf16 v[42:45], v[160:163], v[176:179], v[42:45]
	v_mfma_f32_16x16x32_bf16 v[30:33], v[152:155], v[204:207], v[30:33]
	v_mfma_f32_16x16x32_bf16 v[26:29], v[160:163], v[204:207], v[26:29]
	v_mfma_f32_16x16x32_bf16 v[14:17], v[152:155], v[212:215], v[14:17]
	v_mfma_f32_16x16x32_bf16 v[10:13], v[160:163], v[212:215], v[10:13]
	s_barrier
	s_add_i32 s4, s4, s24
	s_mov_b32 m0, s4
	s_nop 0
	global_load_lds_dwordx4 v132, s[76:77]
	s_add_i32 m0, s4, 0x2000
	s_nop 0
	global_load_lds_dwordx4 v136, s[76:77]
	s_add_u32 s0, s0, 0x100
	s_addc_u32 s1, s1, 0
	s_add_u32 s47, s47, 0x100
	s_addc_u32 s48, s48, 0
	s_cmp_ge_u32 s49, s30
	s_mov_b32 s4, s49
	s_waitcnt vmcnt(6)
	s_barrier
	v_mfma_f32_16x16x32_bf16 v[50:53], v[216:219], v[164:167], v[50:53]
	v_mfma_f32_16x16x32_bf16 v[54:57], v[224:227], v[164:167], v[54:57]
	v_mfma_f32_16x16x32_bf16 v[34:37], v[216:219], v[172:175], v[34:37]
	v_mfma_f32_16x16x32_bf16 v[38:41], v[224:227], v[172:175], v[38:41]
	v_mfma_f32_16x16x32_bf16 v[18:21], v[216:219], v[180:183], v[18:21]
	v_mfma_f32_16x16x32_bf16 v[22:25], v[224:227], v[180:183], v[22:25]
	v_mfma_f32_16x16x32_bf16 v[6:9], v[216:219], v[208:211], v[6:9]
	v_mfma_f32_16x16x32_bf16 v[2:5], v[224:227], v[208:211], v[2:5]
	v_mfma_f32_16x16x32_bf16 v[50:53], v[220:223], v[168:171], v[50:53]
	v_mfma_f32_16x16x32_bf16 v[54:57], v[228:231], v[168:171], v[54:57]
	v_mfma_f32_16x16x32_bf16 v[34:37], v[220:223], v[176:179], v[34:37]
	v_mfma_f32_16x16x32_bf16 v[38:41], v[228:231], v[176:179], v[38:41]
	v_mfma_f32_16x16x32_bf16 v[18:21], v[220:223], v[204:207], v[18:21]
	v_mfma_f32_16x16x32_bf16 v[22:25], v[228:231], v[204:207], v[22:25]
	v_mfma_f32_16x16x32_bf16 v[6:9], v[220:223], v[212:215], v[6:9]
	v_mfma_f32_16x16x32_bf16 v[2:5], v[228:231], v[212:215], v[2:5]
	s_barrier
	s_cbranch_scc1 .Lkexit_253
.LBB0_253:
	s_add_i32 s49, s4, 2
	s_add_u32 s16, s0, 0x80
	s_addc_u32 s5, s1, 0
	s_add_i32 s65, 0, 0x10000
	ds_read_b128 v[148:151], v248
	ds_read_b128 v[152:155], v248 offset:1024
	ds_read_b128 v[156:159], v248 offset:2048
	ds_read_b128 v[160:163], v248 offset:3072
	s_cmp_eq_u32 s41, s4
	s_cselect_b32 s4, s10, s16
	s_cselect_b32 s5, s11, s5
	s_cselect_b32 s17, s13, s48
	s_cselect_b32 s16, s12, s47
	s_add_i32 m0, s26, 0xc000
	ds_read_b128 v[164:167], v146
	ds_read_b128 v[168:171], v146 offset:1024
	ds_read_b128 v[172:175], v146 offset:2048
	ds_read_b128 v[176:179], v146 offset:3072
	ds_read_b128 v[180:183], v146 offset:4096
	ds_read_b128 v[204:207], v146 offset:5120
	ds_read_b128 v[208:211], v146 offset:6144
	ds_read_b128 v[212:215], v146 offset:7168
	global_load_lds_dwordx4 v138, s[0:1]
	s_add_i32 m0, s26, 0xe000
	s_nop 0
	global_load_lds_dwordx4 v140, s[0:1]
	s_waitcnt lgkmcnt(8)
	s_barrier
	s_waitcnt lgkmcnt(0)
	v_mfma_f32_16x16x32_bf16 v[126:129], v[148:151], v[164:167], v[126:129]
	v_mfma_f32_16x16x32_bf16 v[122:125], v[156:159], v[164:167], v[122:125]
	v_mfma_f32_16x16x32_bf16 v[110:113], v[148:151], v[172:175], v[110:113]
	v_mfma_f32_16x16x32_bf16 v[106:109], v[156:159], v[172:175], v[106:109]
	v_mfma_f32_16x16x32_bf16 v[94:97], v[148:151], v[180:183], v[94:97]
	v_mfma_f32_16x16x32_bf16 v[90:93], v[156:159], v[180:183], v[90:93]
	v_mfma_f32_16x16x32_bf16 v[78:81], v[148:151], v[208:211], v[78:81]
	v_mfma_f32_16x16x32_bf16 v[74:77], v[156:159], v[208:211], v[74:77]
	v_mfma_f32_16x16x32_bf16 v[126:129], v[152:155], v[168:171], v[126:129]
	v_mfma_f32_16x16x32_bf16 v[122:125], v[160:163], v[168:171], v[122:125]
	v_mfma_f32_16x16x32_bf16 v[110:113], v[152:155], v[176:179], v[110:113]
	v_mfma_f32_16x16x32_bf16 v[106:109], v[160:163], v[176:179], v[106:109]
	v_mfma_f32_16x16x32_bf16 v[94:97], v[152:155], v[204:207], v[94:97]
	v_mfma_f32_16x16x32_bf16 v[90:93], v[160:163], v[204:207], v[90:93]
	v_mfma_f32_16x16x32_bf16 v[78:81], v[152:155], v[212:215], v[78:81]
	v_mfma_f32_16x16x32_bf16 v[74:77], v[160:163], v[212:215], v[74:77]
	s_barrier
	s_add_i32 s66, 0, 0x14000
	s_add_i32 s65, s65, s24
	ds_read_b128 v[216:219], v248 offset:16384
	ds_read_b128 v[220:223], v248 offset:17408
	ds_read_b128 v[224:227], v248 offset:18432
	ds_read_b128 v[228:231], v248 offset:19456
	s_add_u32 s70, s16, s6
	s_addc_u32 s71, s17, s7
	s_mov_b32 m0, s65
	s_nop 0
	global_load_lds_dwordx4 v132, s[16:17]
	s_add_i32 m0, s65, 0x2000
	s_nop 0
	global_load_lds_dwordx4 v136, s[16:17]
	s_barrier
	s_waitcnt lgkmcnt(0)
	v_mfma_f32_16x16x32_bf16 v[114:117], v[216:219], v[164:167], v[114:117]
	v_mfma_f32_16x16x32_bf16 v[118:121], v[224:227], v[164:167], v[118:121]
	v_mfma_f32_16x16x32_bf16 v[98:101], v[216:219], v[172:175], v[98:101]
	v_mfma_f32_16x16x32_bf16 v[102:105], v[224:227], v[172:175], v[102:105]
	v_mfma_f32_16x16x32_bf16 v[82:85], v[216:219], v[180:183], v[82:85]
	v_mfma_f32_16x16x32_bf16 v[86:89], v[224:227], v[180:183], v[86:89]
	v_mfma_f32_16x16x32_bf16 v[66:69], v[216:219], v[208:211], v[66:69]
	v_mfma_f32_16x16x32_bf16 v[70:73], v[224:227], v[208:211], v[70:73]
	v_mfma_f32_16x16x32_bf16 v[114:117], v[220:223], v[168:171], v[114:117]
	v_mfma_f32_16x16x32_bf16 v[118:121], v[228:231], v[168:171], v[118:121]
	v_mfma_f32_16x16x32_bf16 v[98:101], v[220:223], v[176:179], v[98:101]
	v_mfma_f32_16x16x32_bf16 v[102:105], v[228:231], v[176:179], v[102:105]
	v_mfma_f32_16x16x32_bf16 v[82:85], v[220:223], v[204:207], v[82:85]
	v_mfma_f32_16x16x32_bf16 v[86:89], v[228:231], v[204:207], v[86:89]
	v_mfma_f32_16x16x32_bf16 v[66:69], v[220:223], v[212:215], v[66:69]
	v_mfma_f32_16x16x32_bf16 v[70:73], v[228:231], v[212:215], v[70:73]
	s_barrier
	s_mov_b32 m0, s26
	s_add_u32 s72, s4, s6
	s_addc_u32 s73, s5, s7
	ds_read_b128 v[164:167], v146 offset:16384
	ds_read_b128 v[168:171], v146 offset:17408
	ds_read_b128 v[172:175], v146 offset:18432
	ds_read_b128 v[176:179], v146 offset:19456
	ds_read_b128 v[180:183], v146 offset:20480
	ds_read_b128 v[204:207], v146 offset:21504
	ds_read_b128 v[208:211], v146 offset:22528
	ds_read_b128 v[212:215], v146 offset:23552
	global_load_lds_dwordx4 v130, s[4:5]
	s_mov_b32 m0, s27
	s_nop 0
	global_load_lds_dwordx4 v134, s[4:5]
	s_barrier
	s_waitcnt lgkmcnt(0)
	v_mfma_f32_16x16x32_bf16 v[62:65], v[148:151], v[164:167], v[62:65]
	v_mfma_f32_16x16x32_bf16 v[58:61], v[156:159], v[164:167], v[58:61]
	v_mfma_f32_16x16x32_bf16 v[46:49], v[148:151], v[172:175], v[46:49]
	v_mfma_f32_16x16x32_bf16 v[42:45], v[156:159], v[172:175], v[42:45]
	v_mfma_f32_16x16x32_bf16 v[30:33], v[148:151], v[180:183], v[30:33]
	v_mfma_f32_16x16x32_bf16 v[26:29], v[156:159], v[180:183], v[26:29]
	v_mfma_f32_16x16x32_bf16 v[14:17], v[148:151], v[208:211], v[14:17]
	v_mfma_f32_16x16x32_bf16 v[10:13], v[156:159], v[208:211], v[10:13]
	v_mfma_f32_16x16x32_bf16 v[62:65], v[152:155], v[168:171], v[62:65]
	v_mfma_f32_16x16x32_bf16 v[58:61], v[160:163], v[168:171], v[58:61]
	v_mfma_f32_16x16x32_bf16 v[46:49], v[152:155], v[176:179], v[46:49]
	v_mfma_f32_16x16x32_bf16 v[42:45], v[160:163], v[176:179], v[42:45]
	v_mfma_f32_16x16x32_bf16 v[30:33], v[152:155], v[204:207], v[30:33]
	v_mfma_f32_16x16x32_bf16 v[26:29], v[160:163], v[204:207], v[26:29]
	v_mfma_f32_16x16x32_bf16 v[14:17], v[152:155], v[212:215], v[14:17]
	v_mfma_f32_16x16x32_bf16 v[10:13], v[160:163], v[212:215], v[10:13]
	s_barrier
	s_add_u32 s16, s16, s92
	s_addc_u32 s17, s17, 0
	s_add_i32 s65, s66, s24
	s_add_u32 s76, s16, s6
	s_addc_u32 s77, s17, s7
	s_mov_b32 m0, s65
	s_nop 0
	global_load_lds_dwordx4 v132, s[16:17]
	s_add_i32 m0, s65, 0x2000
	s_nop 0
	global_load_lds_dwordx4 v136, s[16:17]
	s_waitcnt vmcnt(6)
	s_barrier
	v_mfma_f32_16x16x32_bf16 v[50:53], v[216:219], v[164:167], v[50:53]
	v_mfma_f32_16x16x32_bf16 v[54:57], v[224:227], v[164:167], v[54:57]
	v_mfma_f32_16x16x32_bf16 v[34:37], v[216:219], v[172:175], v[34:37]
	v_mfma_f32_16x16x32_bf16 v[38:41], v[224:227], v[172:175], v[38:41]
	v_mfma_f32_16x16x32_bf16 v[18:21], v[216:219], v[180:183], v[18:21]
	v_mfma_f32_16x16x32_bf16 v[22:25], v[224:227], v[180:183], v[22:25]
	v_mfma_f32_16x16x32_bf16 v[6:9], v[216:219], v[208:211], v[6:9]
	v_mfma_f32_16x16x32_bf16 v[2:5], v[224:227], v[208:211], v[2:5]
	v_mfma_f32_16x16x32_bf16 v[50:53], v[220:223], v[168:171], v[50:53]
	v_mfma_f32_16x16x32_bf16 v[54:57], v[228:231], v[168:171], v[54:57]
	v_mfma_f32_16x16x32_bf16 v[34:37], v[220:223], v[176:179], v[34:37]
	v_mfma_f32_16x16x32_bf16 v[38:41], v[228:231], v[176:179], v[38:41]
	v_mfma_f32_16x16x32_bf16 v[18:21], v[220:223], v[204:207], v[18:21]
	v_mfma_f32_16x16x32_bf16 v[22:25], v[228:231], v[204:207], v[22:25]
	v_mfma_f32_16x16x32_bf16 v[6:9], v[220:223], v[212:215], v[6:9]
	v_mfma_f32_16x16x32_bf16 v[2:5], v[228:231], v[212:215], v[2:5]
	s_barrier
	s_add_i32 s16, 0, 0x18000
	ds_read_b128 v[148:151], v248 offset:32768
	ds_read_b128 v[152:155], v248 offset:33792
	ds_read_b128 v[156:159], v248 offset:34816
	ds_read_b128 v[160:163], v248 offset:35840
	s_add_u32 s4, s4, s92
	s_addc_u32 s5, s5, 0
	s_mov_b32 m0, s28
	ds_read_b128 v[164:167], v146 offset:32768
	ds_read_b128 v[168:171], v146 offset:33792
	ds_read_b128 v[172:175], v146 offset:34816
	ds_read_b128 v[176:179], v146 offset:35840
	ds_read_b128 v[180:183], v146 offset:36864
	ds_read_b128 v[204:207], v146 offset:37888
	ds_read_b128 v[208:211], v146 offset:38912
	ds_read_b128 v[212:215], v146 offset:39936
	global_load_lds_dwordx4 v130, s[4:5]
	s_mov_b32 m0, s29
	s_nop 0
	global_load_lds_dwordx4 v134, s[4:5]
	s_waitcnt lgkmcnt(8)
	s_barrier
	s_waitcnt lgkmcnt(0)
	v_mfma_f32_16x16x32_bf16 v[126:129], v[148:151], v[164:167], v[126:129]
	v_mfma_f32_16x16x32_bf16 v[122:125], v[156:159], v[164:167], v[122:125]
	v_mfma_f32_16x16x32_bf16 v[110:113], v[148:151], v[172:175], v[110:113]
	v_mfma_f32_16x16x32_bf16 v[106:109], v[156:159], v[172:175], v[106:109]
	v_mfma_f32_16x16x32_bf16 v[94:97], v[148:151], v[180:183], v[94:97]
	v_mfma_f32_16x16x32_bf16 v[90:93], v[156:159], v[180:183], v[90:93]
	v_mfma_f32_16x16x32_bf16 v[78:81], v[148:151], v[208:211], v[78:81]
	v_mfma_f32_16x16x32_bf16 v[74:77], v[156:159], v[208:211], v[74:77]
	v_mfma_f32_16x16x32_bf16 v[126:129], v[152:155], v[168:171], v[126:129]
	v_mfma_f32_16x16x32_bf16 v[122:125], v[160:163], v[168:171], v[122:125]
	v_mfma_f32_16x16x32_bf16 v[110:113], v[152:155], v[176:179], v[110:113]
	v_mfma_f32_16x16x32_bf16 v[106:109], v[160:163], v[176:179], v[106:109]
	v_mfma_f32_16x16x32_bf16 v[94:97], v[152:155], v[204:207], v[94:97]
	v_mfma_f32_16x16x32_bf16 v[90:93], v[160:163], v[204:207], v[90:93]
	v_mfma_f32_16x16x32_bf16 v[78:81], v[152:155], v[212:215], v[78:81]
	v_mfma_f32_16x16x32_bf16 v[74:77], v[160:163], v[212:215], v[74:77]
	s_barrier
	s_add_i32 s4, 0, 0x1c000
	s_add_i32 s5, s16, s24
	s_mov_b32 m0, s5
	ds_read_b128 v[216:219], v248 offset:49152
	ds_read_b128 v[220:223], v248 offset:50176
	ds_read_b128 v[224:227], v248 offset:51200
	ds_read_b128 v[228:231], v248 offset:52224
	global_load_lds_dwordx4 v132, s[70:71]
	s_add_i32 m0, s5, 0x2000
	s_nop 0
	global_load_lds_dwordx4 v136, s[70:71]
	s_barrier
	s_waitcnt lgkmcnt(0)
	v_mfma_f32_16x16x32_bf16 v[114:117], v[216:219], v[164:167], v[114:117]
	v_mfma_f32_16x16x32_bf16 v[118:121], v[224:227], v[164:167], v[118:121]
	v_mfma_f32_16x16x32_bf16 v[98:101], v[216:219], v[172:175], v[98:101]
	v_mfma_f32_16x16x32_bf16 v[102:105], v[224:227], v[172:175], v[102:105]
	v_mfma_f32_16x16x32_bf16 v[82:85], v[216:219], v[180:183], v[82:85]
	v_mfma_f32_16x16x32_bf16 v[86:89], v[224:227], v[180:183], v[86:89]
	v_mfma_f32_16x16x32_bf16 v[66:69], v[216:219], v[208:211], v[66:69]
	v_mfma_f32_16x16x32_bf16 v[70:73], v[224:227], v[208:211], v[70:73]
	v_mfma_f32_16x16x32_bf16 v[114:117], v[220:223], v[168:171], v[114:117]
	v_mfma_f32_16x16x32_bf16 v[118:121], v[228:231], v[168:171], v[118:121]
	v_mfma_f32_16x16x32_bf16 v[98:101], v[220:223], v[176:179], v[98:101]
	v_mfma_f32_16x16x32_bf16 v[102:105], v[228:231], v[176:179], v[102:105]
	v_mfma_f32_16x16x32_bf16 v[82:85], v[220:223], v[204:207], v[82:85]
	v_mfma_f32_16x16x32_bf16 v[86:89], v[228:231], v[204:207], v[86:89]
	v_mfma_f32_16x16x32_bf16 v[66:69], v[220:223], v[212:215], v[66:69]
	v_mfma_f32_16x16x32_bf16 v[70:73], v[228:231], v[212:215], v[70:73]
	s_barrier
	s_mov_b32 m0, s35
	ds_read_b128 v[164:167], v146 offset:49152
	ds_read_b128 v[168:171], v146 offset:50176
	ds_read_b128 v[172:175], v146 offset:51200
	ds_read_b128 v[176:179], v146 offset:52224
	ds_read_b128 v[180:183], v146 offset:53248
	ds_read_b128 v[204:207], v146 offset:54272
	ds_read_b128 v[208:211], v146 offset:55296
	ds_read_b128 v[212:215], v146 offset:56320
	global_load_lds_dwordx4 v130, s[72:73]
	s_mov_b32 m0, s40
	s_nop 0
	global_load_lds_dwordx4 v134, s[72:73]
	s_barrier
	s_waitcnt lgkmcnt(0)
	v_mfma_f32_16x16x32_bf16 v[62:65], v[148:151], v[164:167], v[62:65]
	v_mfma_f32_16x16x32_bf16 v[58:61], v[156:159], v[164:167], v[58:61]
	v_mfma_f32_16x16x32_bf16 v[46:49], v[148:151], v[172:175], v[46:49]
	v_mfma_f32_16x16x32_bf16 v[42:45], v[156:159], v[172:175], v[42:45]
	v_mfma_f32_16x16x32_bf16 v[30:33], v[148:151], v[180:183], v[30:33]
	v_mfma_f32_16x16x32_bf16 v[26:29], v[156:159], v[180:183], v[26:29]
	v_mfma_f32_16x16x32_bf16 v[14:17], v[148:151], v[208:211], v[14:17]
	v_mfma_f32_16x16x32_bf16 v[10:13], v[156:159], v[208:211], v[10:13]
	v_mfma_f32_16x16x32_bf16 v[62:65], v[152:155], v[168:171], v[62:65]
	v_mfma_f32_16x16x32_bf16 v[58:61], v[160:163], v[168:171], v[58:61]
	v_mfma_f32_16x16x32_bf16 v[46:49], v[152:155], v[176:179], v[46:49]
	v_mfma_f32_16x16x32_bf16 v[42:45], v[160:163], v[176:179], v[42:45]
	v_mfma_f32_16x16x32_bf16 v[30:33], v[152:155], v[204:207], v[30:33]
	v_mfma_f32_16x16x32_bf16 v[26:29], v[160:163], v[204:207], v[26:29]
	v_mfma_f32_16x16x32_bf16 v[14:17], v[152:155], v[212:215], v[14:17]
	v_mfma_f32_16x16x32_bf16 v[10:13], v[160:163], v[212:215], v[10:13]
	s_barrier
	s_add_i32 s4, s4, s24
	s_mov_b32 m0, s4
	s_nop 0
	global_load_lds_dwordx4 v132, s[76:77]
	s_add_i32 m0, s4, 0x2000
	s_nop 0
	global_load_lds_dwordx4 v136, s[76:77]
	s_add_u32 s0, s0, 0x100
	s_addc_u32 s1, s1, 0
	s_add_u32 s47, s47, 0x100
	s_addc_u32 s48, s48, 0
	s_cmp_ge_u32 s49, s30
	s_mov_b32 s4, s49
	s_waitcnt vmcnt(6)
	s_barrier
	v_mfma_f32_16x16x32_bf16 v[50:53], v[216:219], v[164:167], v[50:53]
	v_mfma_f32_16x16x32_bf16 v[54:57], v[224:227], v[164:167], v[54:57]
	v_mfma_f32_16x16x32_bf16 v[34:37], v[216:219], v[172:175], v[34:37]
	v_mfma_f32_16x16x32_bf16 v[38:41], v[224:227], v[172:175], v[38:41]
	v_mfma_f32_16x16x32_bf16 v[18:21], v[216:219], v[180:183], v[18:21]
	v_mfma_f32_16x16x32_bf16 v[22:25], v[224:227], v[180:183], v[22:25]
	v_mfma_f32_16x16x32_bf16 v[6:9], v[216:219], v[208:211], v[6:9]
	v_mfma_f32_16x16x32_bf16 v[2:5], v[224:227], v[208:211], v[2:5]
	v_mfma_f32_16x16x32_bf16 v[50:53], v[220:223], v[168:171], v[50:53]
	v_mfma_f32_16x16x32_bf16 v[54:57], v[228:231], v[168:171], v[54:57]
	v_mfma_f32_16x16x32_bf16 v[34:37], v[220:223], v[176:179], v[34:37]
	v_mfma_f32_16x16x32_bf16 v[38:41], v[228:231], v[176:179], v[38:41]
	v_mfma_f32_16x16x32_bf16 v[18:21], v[220:223], v[204:207], v[18:21]
	v_mfma_f32_16x16x32_bf16 v[22:25], v[228:231], v[204:207], v[22:25]
	v_mfma_f32_16x16x32_bf16 v[6:9], v[220:223], v[212:215], v[6:9]
	v_mfma_f32_16x16x32_bf16 v[2:5], v[228:231], v[212:215], v[2:5]
	s_barrier
	s_cbranch_scc0 .LBB0_253

.LBB0_281:
	s_add_u32 s0, s0, 0x80
	s_addc_u32 s1, s1, 0
	s_add_u32 s20, s4, 0x100
	s_addc_u32 s21, s5, 0
	s_mov_b32 s4, 0
	s_waitcnt lgkmcnt(0)
	s_add_i32 s22, s4, 2
	s_add_u32 s10, s0, 0x80
	s_addc_u32 s5, s1, 0
	s_add_i32 s23, 0, 0x10000
	ds_read_b128 v[142:145], v248
	ds_read_b128 v[146:149], v248 offset:1024
	ds_read_b128 v[150:153], v248 offset:2048
	ds_read_b128 v[154:157], v248 offset:3072
	s_cmp_eq_u32 s44, s4
	s_cselect_b32 s4, s16, s10
	s_cselect_b32 s5, s17, s5
	s_cselect_b32 s11, s13, s21
	s_cselect_b32 s10, s12, s20
	s_add_i32 m0, s29, 0xc000
	ds_read_b128 v[158:161], v166
	ds_read_b128 v[168:171], v166 offset:1024
	ds_read_b128 v[172:175], v166 offset:2048
	ds_read_b128 v[176:179], v166 offset:3072
	ds_read_b128 v[180:183], v166 offset:4096
	ds_read_b128 v[204:207], v166 offset:5120
	ds_read_b128 v[208:211], v166 offset:6144
	ds_read_b128 v[212:215], v166 offset:7168
	global_load_lds_dwordx4 v138, s[0:1]
	s_add_i32 m0, s29, 0xe000
	s_nop 0
	global_load_lds_dwordx4 v140, s[0:1]
	s_waitcnt lgkmcnt(8)
	s_barrier
	s_waitcnt lgkmcnt(0)
	v_mfma_f32_16x16x32_bf16 v[126:129], v[142:145], v[158:161], 0
	v_mfma_f32_16x16x32_bf16 v[122:125], v[150:153], v[158:161], 0
	v_mfma_f32_16x16x32_bf16 v[110:113], v[142:145], v[172:175], 0
	v_mfma_f32_16x16x32_bf16 v[106:109], v[150:153], v[172:175], 0
	v_mfma_f32_16x16x32_bf16 v[94:97], v[142:145], v[180:183], 0
	v_mfma_f32_16x16x32_bf16 v[90:93], v[150:153], v[180:183], 0
	v_mfma_f32_16x16x32_bf16 v[78:81], v[142:145], v[208:211], 0
	v_mfma_f32_16x16x32_bf16 v[74:77], v[150:153], v[208:211], 0
	v_mfma_f32_16x16x32_bf16 v[126:129], v[146:149], v[168:171], v[126:129]
	v_mfma_f32_16x16x32_bf16 v[122:125], v[154:157], v[168:171], v[122:125]
	v_mfma_f32_16x16x32_bf16 v[110:113], v[146:149], v[176:179], v[110:113]
	v_mfma_f32_16x16x32_bf16 v[106:109], v[154:157], v[176:179], v[106:109]
	v_mfma_f32_16x16x32_bf16 v[94:97], v[146:149], v[204:207], v[94:97]
	v_mfma_f32_16x16x32_bf16 v[90:93], v[154:157], v[204:207], v[90:93]
	v_mfma_f32_16x16x32_bf16 v[78:81], v[146:149], v[212:215], v[78:81]
	v_mfma_f32_16x16x32_bf16 v[74:77], v[154:157], v[212:215], v[74:77]
	s_barrier
	s_add_i32 s24, 0, 0x14000
	s_add_i32 s23, s23, s28
	ds_read_b128 v[216:219], v248 offset:16384
	ds_read_b128 v[220:223], v248 offset:17408
	ds_read_b128 v[224:227], v248 offset:18432
	ds_read_b128 v[228:231], v248 offset:19456
	s_add_u32 s70, s10, s6
	s_addc_u32 s71, s11, s7
	s_mov_b32 m0, s23
	s_nop 0
	global_load_lds_dwordx4 v132, s[10:11]
	s_add_i32 m0, s23, 0x2000
	s_nop 0
	global_load_lds_dwordx4 v136, s[10:11]
	s_barrier
	s_waitcnt lgkmcnt(0)
	v_mfma_f32_16x16x32_bf16 v[118:121], v[216:219], v[158:161], 0
	v_mfma_f32_16x16x32_bf16 v[114:117], v[224:227], v[158:161], 0
	v_mfma_f32_16x16x32_bf16 v[102:105], v[216:219], v[172:175], 0
	v_mfma_f32_16x16x32_bf16 v[98:101], v[224:227], v[172:175], 0
	v_mfma_f32_16x16x32_bf16 v[86:89], v[216:219], v[180:183], 0
	v_mfma_f32_16x16x32_bf16 v[82:85], v[224:227], v[180:183], 0
	v_mfma_f32_16x16x32_bf16 v[70:73], v[216:219], v[208:211], 0
	v_mfma_f32_16x16x32_bf16 v[66:69], v[224:227], v[208:211], 0
	v_mfma_f32_16x16x32_bf16 v[118:121], v[220:223], v[168:171], v[118:121]
	v_mfma_f32_16x16x32_bf16 v[114:117], v[228:231], v[168:171], v[114:117]
	v_mfma_f32_16x16x32_bf16 v[102:105], v[220:223], v[176:179], v[102:105]
	v_mfma_f32_16x16x32_bf16 v[98:101], v[228:231], v[176:179], v[98:101]
	v_mfma_f32_16x16x32_bf16 v[86:89], v[220:223], v[204:207], v[86:89]
	v_mfma_f32_16x16x32_bf16 v[82:85], v[228:231], v[204:207], v[82:85]
	v_mfma_f32_16x16x32_bf16 v[70:73], v[220:223], v[212:215], v[70:73]
	v_mfma_f32_16x16x32_bf16 v[66:69], v[228:231], v[212:215], v[66:69]
	s_barrier
	s_mov_b32 m0, s29
	s_add_u32 s72, s4, s6
	s_addc_u32 s73, s5, s7
	ds_read_b128 v[158:161], v166 offset:16384
	ds_read_b128 v[168:171], v166 offset:17408
	ds_read_b128 v[172:175], v166 offset:18432
	ds_read_b128 v[176:179], v166 offset:19456
	ds_read_b128 v[180:183], v166 offset:20480
	ds_read_b128 v[204:207], v166 offset:21504
	ds_read_b128 v[208:211], v166 offset:22528
	ds_read_b128 v[212:215], v166 offset:23552
	global_load_lds_dwordx4 v130, s[4:5]
	s_mov_b32 m0, s30
	s_nop 0
	global_load_lds_dwordx4 v134, s[4:5]
	s_barrier
	s_waitcnt lgkmcnt(0)
	v_mfma_f32_16x16x32_bf16 v[62:65], v[142:145], v[158:161], 0
	v_mfma_f32_16x16x32_bf16 v[58:61], v[150:153], v[158:161], 0
	v_mfma_f32_16x16x32_bf16 v[46:49], v[142:145], v[172:175], 0
	v_mfma_f32_16x16x32_bf16 v[42:45], v[150:153], v[172:175], 0
	v_mfma_f32_16x16x32_bf16 v[30:33], v[142:145], v[180:183], 0
	v_mfma_f32_16x16x32_bf16 v[26:29], v[150:153], v[180:183], 0
	v_mfma_f32_16x16x32_bf16 v[14:17], v[142:145], v[208:211], 0
	v_mfma_f32_16x16x32_bf16 v[10:13], v[150:153], v[208:211], 0
	v_mfma_f32_16x16x32_bf16 v[62:65], v[146:149], v[168:171], v[62:65]
	v_mfma_f32_16x16x32_bf16 v[58:61], v[154:157], v[168:171], v[58:61]
	v_mfma_f32_16x16x32_bf16 v[46:49], v[146:149], v[176:179], v[46:49]
	v_mfma_f32_16x16x32_bf16 v[42:45], v[154:157], v[176:179], v[42:45]
	v_mfma_f32_16x16x32_bf16 v[30:33], v[146:149], v[204:207], v[30:33]
	v_mfma_f32_16x16x32_bf16 v[26:29], v[154:157], v[204:207], v[26:29]
	v_mfma_f32_16x16x32_bf16 v[14:17], v[146:149], v[212:215], v[14:17]
	v_mfma_f32_16x16x32_bf16 v[10:13], v[154:157], v[212:215], v[10:13]
	s_barrier
	s_add_u32 s10, s10, s92
	s_addc_u32 s11, s11, 0
	s_add_i32 s23, s24, s28
	s_add_u32 s80, s10, s6
	s_addc_u32 s81, s11, s7
	s_mov_b32 m0, s23
	s_nop 0
	global_load_lds_dwordx4 v132, s[10:11]
	s_add_i32 m0, s23, 0x2000
	s_nop 0
	global_load_lds_dwordx4 v136, s[10:11]
	s_waitcnt vmcnt(6)
	s_barrier
	v_mfma_f32_16x16x32_bf16 v[54:57], v[216:219], v[158:161], 0
	v_mfma_f32_16x16x32_bf16 v[50:53], v[224:227], v[158:161], 0
	v_mfma_f32_16x16x32_bf16 v[38:41], v[216:219], v[172:175], 0
	v_mfma_f32_16x16x32_bf16 v[34:37], v[224:227], v[172:175], 0
	v_mfma_f32_16x16x32_bf16 v[22:25], v[216:219], v[180:183], 0
	v_mfma_f32_16x16x32_bf16 v[18:21], v[224:227], v[180:183], 0
	v_mfma_f32_16x16x32_bf16 v[6:9], v[216:219], v[208:211], 0
	v_mfma_f32_16x16x32_bf16 v[2:5], v[224:227], v[208:211], 0
	v_mfma_f32_16x16x32_bf16 v[54:57], v[220:223], v[168:171], v[54:57]
	v_mfma_f32_16x16x32_bf16 v[50:53], v[228:231], v[168:171], v[50:53]
	v_mfma_f32_16x16x32_bf16 v[38:41], v[220:223], v[176:179], v[38:41]
	v_mfma_f32_16x16x32_bf16 v[34:37], v[228:231], v[176:179], v[34:37]
	v_mfma_f32_16x16x32_bf16 v[22:25], v[220:223], v[204:207], v[22:25]
	v_mfma_f32_16x16x32_bf16 v[18:21], v[228:231], v[204:207], v[18:21]
	v_mfma_f32_16x16x32_bf16 v[6:9], v[220:223], v[212:215], v[6:9]
	v_mfma_f32_16x16x32_bf16 v[2:5], v[228:231], v[212:215], v[2:5]
	s_barrier
	s_add_i32 s10, 0, 0x18000
	ds_read_b128 v[142:145], v248 offset:32768
	ds_read_b128 v[146:149], v248 offset:33792
	ds_read_b128 v[150:153], v248 offset:34816
	ds_read_b128 v[154:157], v248 offset:35840
	s_add_u32 s4, s4, s92
	s_addc_u32 s5, s5, 0
	s_mov_b32 m0, s31
	ds_read_b128 v[158:161], v166 offset:32768
	ds_read_b128 v[168:171], v166 offset:33792
	ds_read_b128 v[172:175], v166 offset:34816
	ds_read_b128 v[176:179], v166 offset:35840
	ds_read_b128 v[180:183], v166 offset:36864
	ds_read_b128 v[204:207], v166 offset:37888
	ds_read_b128 v[208:211], v166 offset:38912
	ds_read_b128 v[212:215], v166 offset:39936
	global_load_lds_dwordx4 v130, s[4:5]
	s_mov_b32 m0, s34
	s_nop 0
	global_load_lds_dwordx4 v134, s[4:5]
	s_waitcnt lgkmcnt(8)
	s_barrier
	s_waitcnt lgkmcnt(0)
	v_mfma_f32_16x16x32_bf16 v[126:129], v[142:145], v[158:161], v[126:129]
	v_mfma_f32_16x16x32_bf16 v[122:125], v[150:153], v[158:161], v[122:125]
	v_mfma_f32_16x16x32_bf16 v[110:113], v[142:145], v[172:175], v[110:113]
	v_mfma_f32_16x16x32_bf16 v[106:109], v[150:153], v[172:175], v[106:109]
	v_mfma_f32_16x16x32_bf16 v[94:97], v[142:145], v[180:183], v[94:97]
	v_mfma_f32_16x16x32_bf16 v[90:93], v[150:153], v[180:183], v[90:93]
	v_mfma_f32_16x16x32_bf16 v[78:81], v[142:145], v[208:211], v[78:81]
	v_mfma_f32_16x16x32_bf16 v[74:77], v[150:153], v[208:211], v[74:77]
	v_mfma_f32_16x16x32_bf16 v[126:129], v[146:149], v[168:171], v[126:129]
	v_mfma_f32_16x16x32_bf16 v[122:125], v[154:157], v[168:171], v[122:125]
	v_mfma_f32_16x16x32_bf16 v[110:113], v[146:149], v[176:179], v[110:113]
	v_mfma_f32_16x16x32_bf16 v[106:109], v[154:157], v[176:179], v[106:109]
	v_mfma_f32_16x16x32_bf16 v[94:97], v[146:149], v[204:207], v[94:97]
	v_mfma_f32_16x16x32_bf16 v[90:93], v[154:157], v[204:207], v[90:93]
	v_mfma_f32_16x16x32_bf16 v[78:81], v[146:149], v[212:215], v[78:81]
	v_mfma_f32_16x16x32_bf16 v[74:77], v[154:157], v[212:215], v[74:77]
	s_barrier
	s_add_i32 s4, 0, 0x1c000
	s_add_i32 s5, s10, s28
	s_mov_b32 m0, s5
	ds_read_b128 v[216:219], v248 offset:49152
	ds_read_b128 v[220:223], v248 offset:50176
	ds_read_b128 v[224:227], v248 offset:51200
	ds_read_b128 v[228:231], v248 offset:52224
	global_load_lds_dwordx4 v132, s[70:71]
	s_add_i32 m0, s5, 0x2000
	s_nop 0
	global_load_lds_dwordx4 v136, s[70:71]
	s_barrier
	s_waitcnt lgkmcnt(0)
	v_mfma_f32_16x16x32_bf16 v[118:121], v[216:219], v[158:161], v[118:121]
	v_mfma_f32_16x16x32_bf16 v[114:117], v[224:227], v[158:161], v[114:117]
	v_mfma_f32_16x16x32_bf16 v[102:105], v[216:219], v[172:175], v[102:105]
	v_mfma_f32_16x16x32_bf16 v[98:101], v[224:227], v[172:175], v[98:101]
	v_mfma_f32_16x16x32_bf16 v[86:89], v[216:219], v[180:183], v[86:89]
	v_mfma_f32_16x16x32_bf16 v[82:85], v[224:227], v[180:183], v[82:85]
	v_mfma_f32_16x16x32_bf16 v[70:73], v[216:219], v[208:211], v[70:73]
	v_mfma_f32_16x16x32_bf16 v[66:69], v[224:227], v[208:211], v[66:69]
	v_mfma_f32_16x16x32_bf16 v[118:121], v[220:223], v[168:171], v[118:121]
	v_mfma_f32_16x16x32_bf16 v[114:117], v[228:231], v[168:171], v[114:117]
	v_mfma_f32_16x16x32_bf16 v[102:105], v[220:223], v[176:179], v[102:105]
	v_mfma_f32_16x16x32_bf16 v[98:101], v[228:231], v[176:179], v[98:101]
	v_mfma_f32_16x16x32_bf16 v[86:89], v[220:223], v[204:207], v[86:89]
	v_mfma_f32_16x16x32_bf16 v[82:85], v[228:231], v[204:207], v[82:85]
	v_mfma_f32_16x16x32_bf16 v[70:73], v[220:223], v[212:215], v[70:73]
	v_mfma_f32_16x16x32_bf16 v[66:69], v[228:231], v[212:215], v[66:69]
	s_barrier
	s_mov_b32 m0, s42
	ds_read_b128 v[158:161], v166 offset:49152
	ds_read_b128 v[168:171], v166 offset:50176
	ds_read_b128 v[172:175], v166 offset:51200
	ds_read_b128 v[176:179], v166 offset:52224
	ds_read_b128 v[180:183], v166 offset:53248
	ds_read_b128 v[204:207], v166 offset:54272
	ds_read_b128 v[208:211], v166 offset:55296
	ds_read_b128 v[212:215], v166 offset:56320
	global_load_lds_dwordx4 v130, s[72:73]
	s_mov_b32 m0, s43
	s_nop 0
	global_load_lds_dwordx4 v134, s[72:73]
	s_barrier
	s_waitcnt lgkmcnt(0)
	v_mfma_f32_16x16x32_bf16 v[62:65], v[142:145], v[158:161], v[62:65]
	v_mfma_f32_16x16x32_bf16 v[58:61], v[150:153], v[158:161], v[58:61]
	v_mfma_f32_16x16x32_bf16 v[46:49], v[142:145], v[172:175], v[46:49]
	v_mfma_f32_16x16x32_bf16 v[42:45], v[150:153], v[172:175], v[42:45]
	v_mfma_f32_16x16x32_bf16 v[30:33], v[142:145], v[180:183], v[30:33]
	v_mfma_f32_16x16x32_bf16 v[26:29], v[150:153], v[180:183], v[26:29]
	v_mfma_f32_16x16x32_bf16 v[14:17], v[142:145], v[208:211], v[14:17]
	v_mfma_f32_16x16x32_bf16 v[10:13], v[150:153], v[208:211], v[10:13]
	v_mfma_f32_16x16x32_bf16 v[62:65], v[146:149], v[168:171], v[62:65]
	v_mfma_f32_16x16x32_bf16 v[58:61], v[154:157], v[168:171], v[58:61]
	v_mfma_f32_16x16x32_bf16 v[46:49], v[146:149], v[176:179], v[46:49]
	v_mfma_f32_16x16x32_bf16 v[42:45], v[154:157], v[176:179], v[42:45]
	v_mfma_f32_16x16x32_bf16 v[30:33], v[146:149], v[204:207], v[30:33]
	v_mfma_f32_16x16x32_bf16 v[26:29], v[154:157], v[204:207], v[26:29]
	v_mfma_f32_16x16x32_bf16 v[14:17], v[146:149], v[212:215], v[14:17]
	v_mfma_f32_16x16x32_bf16 v[10:13], v[154:157], v[212:215], v[10:13]
	s_barrier
	s_add_i32 s4, s4, s28
	s_mov_b32 m0, s4
	s_nop 0
	global_load_lds_dwordx4 v132, s[80:81]
	s_add_i32 m0, s4, 0x2000
	s_nop 0
	global_load_lds_dwordx4 v136, s[80:81]
	s_add_u32 s0, s0, 0x100
	s_addc_u32 s1, s1, 0
	s_add_u32 s20, s20, 0x100
	s_addc_u32 s21, s21, 0
	s_cmp_ge_u32 s22, s35
	s_mov_b32 s4, s22
	s_waitcnt vmcnt(6)
	s_barrier
	v_mfma_f32_16x16x32_bf16 v[54:57], v[216:219], v[158:161], v[54:57]
	v_mfma_f32_16x16x32_bf16 v[50:53], v[224:227], v[158:161], v[50:53]
	v_mfma_f32_16x16x32_bf16 v[38:41], v[216:219], v[172:175], v[38:41]
	v_mfma_f32_16x16x32_bf16 v[34:37], v[224:227], v[172:175], v[34:37]
	v_mfma_f32_16x16x32_bf16 v[22:25], v[216:219], v[180:183], v[22:25]
	v_mfma_f32_16x16x32_bf16 v[18:21], v[224:227], v[180:183], v[18:21]
	v_mfma_f32_16x16x32_bf16 v[6:9], v[216:219], v[208:211], v[6:9]
	v_mfma_f32_16x16x32_bf16 v[2:5], v[224:227], v[208:211], v[2:5]
	v_mfma_f32_16x16x32_bf16 v[54:57], v[220:223], v[168:171], v[54:57]
	v_mfma_f32_16x16x32_bf16 v[50:53], v[228:231], v[168:171], v[50:53]
	v_mfma_f32_16x16x32_bf16 v[38:41], v[220:223], v[176:179], v[38:41]
	v_mfma_f32_16x16x32_bf16 v[34:37], v[228:231], v[176:179], v[34:37]
	v_mfma_f32_16x16x32_bf16 v[22:25], v[220:223], v[204:207], v[22:25]
	v_mfma_f32_16x16x32_bf16 v[18:21], v[228:231], v[204:207], v[18:21]
	v_mfma_f32_16x16x32_bf16 v[6:9], v[220:223], v[212:215], v[6:9]
	v_mfma_f32_16x16x32_bf16 v[2:5], v[228:231], v[212:215], v[2:5]
	s_barrier
	s_cbranch_scc1 .Lkexit_282
.LBB0_282:
	s_add_i32 s22, s4, 2
	s_add_u32 s10, s0, 0x80
	s_addc_u32 s5, s1, 0
	s_add_i32 s23, 0, 0x10000
	ds_read_b128 v[142:145], v248
	ds_read_b128 v[146:149], v248 offset:1024
	ds_read_b128 v[150:153], v248 offset:2048
	ds_read_b128 v[154:157], v248 offset:3072
	s_cmp_eq_u32 s44, s4
	s_cselect_b32 s4, s16, s10
	s_cselect_b32 s5, s17, s5
	s_cselect_b32 s11, s13, s21
	s_cselect_b32 s10, s12, s20
	s_add_i32 m0, s29, 0xc000
	ds_read_b128 v[158:161], v166
	ds_read_b128 v[168:171], v166 offset:1024
	ds_read_b128 v[172:175], v166 offset:2048
	ds_read_b128 v[176:179], v166 offset:3072
	ds_read_b128 v[180:183], v166 offset:4096
	ds_read_b128 v[204:207], v166 offset:5120
	ds_read_b128 v[208:211], v166 offset:6144
	ds_read_b128 v[212:215], v166 offset:7168
	global_load_lds_dwordx4 v138, s[0:1]
	s_add_i32 m0, s29, 0xe000
	s_nop 0
	global_load_lds_dwordx4 v140, s[0:1]
	s_waitcnt lgkmcnt(8)
	s_barrier
	s_waitcnt lgkmcnt(0)
	v_mfma_f32_16x16x32_bf16 v[126:129], v[142:145], v[158:161], v[126:129]
	v_mfma_f32_16x16x32_bf16 v[122:125], v[150:153], v[158:161], v[122:125]
	v_mfma_f32_16x16x32_bf16 v[110:113], v[142:145], v[172:175], v[110:113]
	v_mfma_f32_16x16x32_bf16 v[106:109], v[150:153], v[172:175], v[106:109]
	v_mfma_f32_16x16x32_bf16 v[94:97], v[142:145], v[180:183], v[94:97]
	v_mfma_f32_16x16x32_bf16 v[90:93], v[150:153], v[180:183], v[90:93]
	v_mfma_f32_16x16x32_bf16 v[78:81], v[142:145], v[208:211], v[78:81]
	v_mfma_f32_16x16x32_bf16 v[74:77], v[150:153], v[208:211], v[74:77]
	v_mfma_f32_16x16x32_bf16 v[126:129], v[146:149], v[168:171], v[126:129]
	v_mfma_f32_16x16x32_bf16 v[122:125], v[154:157], v[168:171], v[122:125]
	v_mfma_f32_16x16x32_bf16 v[110:113], v[146:149], v[176:179], v[110:113]
	v_mfma_f32_16x16x32_bf16 v[106:109], v[154:157], v[176:179], v[106:109]
	v_mfma_f32_16x16x32_bf16 v[94:97], v[146:149], v[204:207], v[94:97]
	v_mfma_f32_16x16x32_bf16 v[90:93], v[154:157], v[204:207], v[90:93]
	v_mfma_f32_16x16x32_bf16 v[78:81], v[146:149], v[212:215], v[78:81]
	v_mfma_f32_16x16x32_bf16 v[74:77], v[154:157], v[212:215], v[74:77]
	s_barrier
	s_add_i32 s24, 0, 0x14000
	s_add_i32 s23, s23, s28
	ds_read_b128 v[216:219], v248 offset:16384
	ds_read_b128 v[220:223], v248 offset:17408
	ds_read_b128 v[224:227], v248 offset:18432
	ds_read_b128 v[228:231], v248 offset:19456
	s_add_u32 s70, s10, s6
	s_addc_u32 s71, s11, s7
	s_mov_b32 m0, s23
	s_nop 0
	global_load_lds_dwordx4 v132, s[10:11]
	s_add_i32 m0, s23, 0x2000
	s_nop 0
	global_load_lds_dwordx4 v136, s[10:11]
	s_barrier
	s_waitcnt lgkmcnt(0)
	v_mfma_f32_16x16x32_bf16 v[118:121], v[216:219], v[158:161], v[118:121]
	v_mfma_f32_16x16x32_bf16 v[114:117], v[224:227], v[158:161], v[114:117]
	v_mfma_f32_16x16x32_bf16 v[102:105], v[216:219], v[172:175], v[102:105]
	v_mfma_f32_16x16x32_bf16 v[98:101], v[224:227], v[172:175], v[98:101]
	v_mfma_f32_16x16x32_bf16 v[86:89], v[216:219], v[180:183], v[86:89]
	v_mfma_f32_16x16x32_bf16 v[82:85], v[224:227], v[180:183], v[82:85]
	v_mfma_f32_16x16x32_bf16 v[70:73], v[216:219], v[208:211], v[70:73]
	v_mfma_f32_16x16x32_bf16 v[66:69], v[224:227], v[208:211], v[66:69]
	v_mfma_f32_16x16x32_bf16 v[118:121], v[220:223], v[168:171], v[118:121]
	v_mfma_f32_16x16x32_bf16 v[114:117], v[228:231], v[168:171], v[114:117]
	v_mfma_f32_16x16x32_bf16 v[102:105], v[220:223], v[176:179], v[102:105]
	v_mfma_f32_16x16x32_bf16 v[98:101], v[228:231], v[176:179], v[98:101]
	v_mfma_f32_16x16x32_bf16 v[86:89], v[220:223], v[204:207], v[86:89]
	v_mfma_f32_16x16x32_bf16 v[82:85], v[228:231], v[204:207], v[82:85]
	v_mfma_f32_16x16x32_bf16 v[70:73], v[220:223], v[212:215], v[70:73]
	v_mfma_f32_16x16x32_bf16 v[66:69], v[228:231], v[212:215], v[66:69]
	s_barrier
	s_mov_b32 m0, s29
	s_add_u32 s72, s4, s6
	s_addc_u32 s73, s5, s7
	ds_read_b128 v[158:161], v166 offset:16384
	ds_read_b128 v[168:171], v166 offset:17408
	ds_read_b128 v[172:175], v166 offset:18432
	ds_read_b128 v[176:179], v166 offset:19456
	ds_read_b128 v[180:183], v166 offset:20480
	ds_read_b128 v[204:207], v166 offset:21504
	ds_read_b128 v[208:211], v166 offset:22528
	ds_read_b128 v[212:215], v166 offset:23552
	global_load_lds_dwordx4 v130, s[4:5]
	s_mov_b32 m0, s30
	s_nop 0
	global_load_lds_dwordx4 v134, s[4:5]
	s_barrier
	s_waitcnt lgkmcnt(0)
	v_mfma_f32_16x16x32_bf16 v[62:65], v[142:145], v[158:161], v[62:65]
	v_mfma_f32_16x16x32_bf16 v[58:61], v[150:153], v[158:161], v[58:61]
	v_mfma_f32_16x16x32_bf16 v[46:49], v[142:145], v[172:175], v[46:49]
	v_mfma_f32_16x16x32_bf16 v[42:45], v[150:153], v[172:175], v[42:45]
	v_mfma_f32_16x16x32_bf16 v[30:33], v[142:145], v[180:183], v[30:33]
	v_mfma_f32_16x16x32_bf16 v[26:29], v[150:153], v[180:183], v[26:29]
	v_mfma_f32_16x16x32_bf16 v[14:17], v[142:145], v[208:211], v[14:17]
	v_mfma_f32_16x16x32_bf16 v[10:13], v[150:153], v[208:211], v[10:13]
	v_mfma_f32_16x16x32_bf16 v[62:65], v[146:149], v[168:171], v[62:65]
	v_mfma_f32_16x16x32_bf16 v[58:61], v[154:157], v[168:171], v[58:61]
	v_mfma_f32_16x16x32_bf16 v[46:49], v[146:149], v[176:179], v[46:49]
	v_mfma_f32_16x16x32_bf16 v[42:45], v[154:157], v[176:179], v[42:45]
	v_mfma_f32_16x16x32_bf16 v[30:33], v[146:149], v[204:207], v[30:33]
	v_mfma_f32_16x16x32_bf16 v[26:29], v[154:157], v[204:207], v[26:29]
	v_mfma_f32_16x16x32_bf16 v[14:17], v[146:149], v[212:215], v[14:17]
	v_mfma_f32_16x16x32_bf16 v[10:13], v[154:157], v[212:215], v[10:13]
	s_barrier
	s_add_u32 s10, s10, s92
	s_addc_u32 s11, s11, 0
	s_add_i32 s23, s24, s28
	s_add_u32 s80, s10, s6
	s_addc_u32 s81, s11, s7
	s_mov_b32 m0, s23
	s_nop 0
	global_load_lds_dwordx4 v132, s[10:11]
	s_add_i32 m0, s23, 0x2000
	s_nop 0
	global_load_lds_dwordx4 v136, s[10:11]
	s_waitcnt vmcnt(6)
	s_barrier
	v_mfma_f32_16x16x32_bf16 v[54:57], v[216:219], v[158:161], v[54:57]
	v_mfma_f32_16x16x32_bf16 v[50:53], v[224:227], v[158:161], v[50:53]
	v_mfma_f32_16x16x32_bf16 v[38:41], v[216:219], v[172:175], v[38:41]
	v_mfma_f32_16x16x32_bf16 v[34:37], v[224:227], v[172:175], v[34:37]
	v_mfma_f32_16x16x32_bf16 v[22:25], v[216:219], v[180:183], v[22:25]
	v_mfma_f32_16x16x32_bf16 v[18:21], v[224:227], v[180:183], v[18:21]
	v_mfma_f32_16x16x32_bf16 v[6:9], v[216:219], v[208:211], v[6:9]
	v_mfma_f32_16x16x32_bf16 v[2:5], v[224:227], v[208:211], v[2:5]
	v_mfma_f32_16x16x32_bf16 v[54:57], v[220:223], v[168:171], v[54:57]
	v_mfma_f32_16x16x32_bf16 v[50:53], v[228:231], v[168:171], v[50:53]
	v_mfma_f32_16x16x32_bf16 v[38:41], v[220:223], v[176:179], v[38:41]
	v_mfma_f32_16x16x32_bf16 v[34:37], v[228:231], v[176:179], v[34:37]
	v_mfma_f32_16x16x32_bf16 v[22:25], v[220:223], v[204:207], v[22:25]
	v_mfma_f32_16x16x32_bf16 v[18:21], v[228:231], v[204:207], v[18:21]
	v_mfma_f32_16x16x32_bf16 v[6:9], v[220:223], v[212:215], v[6:9]
	v_mfma_f32_16x16x32_bf16 v[2:5], v[228:231], v[212:215], v[2:5]
	s_barrier
	s_add_i32 s10, 0, 0x18000
	ds_read_b128 v[142:145], v248 offset:32768
	ds_read_b128 v[146:149], v248 offset:33792
	ds_read_b128 v[150:153], v248 offset:34816
	ds_read_b128 v[154:157], v248 offset:35840
	s_add_u32 s4, s4, s92
	s_addc_u32 s5, s5, 0
	s_mov_b32 m0, s31
	ds_read_b128 v[158:161], v166 offset:32768
	ds_read_b128 v[168:171], v166 offset:33792
	ds_read_b128 v[172:175], v166 offset:34816
	ds_read_b128 v[176:179], v166 offset:35840
	ds_read_b128 v[180:183], v166 offset:36864
	ds_read_b128 v[204:207], v166 offset:37888
	ds_read_b128 v[208:211], v166 offset:38912
	ds_read_b128 v[212:215], v166 offset:39936
	global_load_lds_dwordx4 v130, s[4:5]
	s_mov_b32 m0, s34
	s_nop 0
	global_load_lds_dwordx4 v134, s[4:5]
	s_waitcnt lgkmcnt(8)
	s_barrier
	s_waitcnt lgkmcnt(0)
	v_mfma_f32_16x16x32_bf16 v[126:129], v[142:145], v[158:161], v[126:129]
	v_mfma_f32_16x16x32_bf16 v[122:125], v[150:153], v[158:161], v[122:125]
	v_mfma_f32_16x16x32_bf16 v[110:113], v[142:145], v[172:175], v[110:113]
	v_mfma_f32_16x16x32_bf16 v[106:109], v[150:153], v[172:175], v[106:109]
	v_mfma_f32_16x16x32_bf16 v[94:97], v[142:145], v[180:183], v[94:97]
	v_mfma_f32_16x16x32_bf16 v[90:93], v[150:153], v[180:183], v[90:93]
	v_mfma_f32_16x16x32_bf16 v[78:81], v[142:145], v[208:211], v[78:81]
	v_mfma_f32_16x16x32_bf16 v[74:77], v[150:153], v[208:211], v[74:77]
	v_mfma_f32_16x16x32_bf16 v[126:129], v[146:149], v[168:171], v[126:129]
	v_mfma_f32_16x16x32_bf16 v[122:125], v[154:157], v[168:171], v[122:125]
	v_mfma_f32_16x16x32_bf16 v[110:113], v[146:149], v[176:179], v[110:113]
	v_mfma_f32_16x16x32_bf16 v[106:109], v[154:157], v[176:179], v[106:109]
	v_mfma_f32_16x16x32_bf16 v[94:97], v[146:149], v[204:207], v[94:97]
	v_mfma_f32_16x16x32_bf16 v[90:93], v[154:157], v[204:207], v[90:93]
	v_mfma_f32_16x16x32_bf16 v[78:81], v[146:149], v[212:215], v[78:81]
	v_mfma_f32_16x16x32_bf16 v[74:77], v[154:157], v[212:215], v[74:77]
	s_barrier
	s_add_i32 s4, 0, 0x1c000
	s_add_i32 s5, s10, s28
	s_mov_b32 m0, s5
	ds_read_b128 v[216:219], v248 offset:49152
	ds_read_b128 v[220:223], v248 offset:50176
	ds_read_b128 v[224:227], v248 offset:51200
	ds_read_b128 v[228:231], v248 offset:52224
	global_load_lds_dwordx4 v132, s[70:71]
	s_add_i32 m0, s5, 0x2000
	s_nop 0
	global_load_lds_dwordx4 v136, s[70:71]
	s_barrier
	s_waitcnt lgkmcnt(0)
	v_mfma_f32_16x16x32_bf16 v[118:121], v[216:219], v[158:161], v[118:121]
	v_mfma_f32_16x16x32_bf16 v[114:117], v[224:227], v[158:161], v[114:117]
	v_mfma_f32_16x16x32_bf16 v[102:105], v[216:219], v[172:175], v[102:105]
	v_mfma_f32_16x16x32_bf16 v[98:101], v[224:227], v[172:175], v[98:101]
	v_mfma_f32_16x16x32_bf16 v[86:89], v[216:219], v[180:183], v[86:89]
	v_mfma_f32_16x16x32_bf16 v[82:85], v[224:227], v[180:183], v[82:85]
	v_mfma_f32_16x16x32_bf16 v[70:73], v[216:219], v[208:211], v[70:73]
	v_mfma_f32_16x16x32_bf16 v[66:69], v[224:227], v[208:211], v[66:69]
	v_mfma_f32_16x16x32_bf16 v[118:121], v[220:223], v[168:171], v[118:121]
	v_mfma_f32_16x16x32_bf16 v[114:117], v[228:231], v[168:171], v[114:117]
	v_mfma_f32_16x16x32_bf16 v[102:105], v[220:223], v[176:179], v[102:105]
	v_mfma_f32_16x16x32_bf16 v[98:101], v[228:231], v[176:179], v[98:101]
	v_mfma_f32_16x16x32_bf16 v[86:89], v[220:223], v[204:207], v[86:89]
	v_mfma_f32_16x16x32_bf16 v[82:85], v[228:231], v[204:207], v[82:85]
	v_mfma_f32_16x16x32_bf16 v[70:73], v[220:223], v[212:215], v[70:73]
	v_mfma_f32_16x16x32_bf16 v[66:69], v[228:231], v[212:215], v[66:69]
	s_barrier
	s_mov_b32 m0, s42
	ds_read_b128 v[158:161], v166 offset:49152
	ds_read_b128 v[168:171], v166 offset:50176
	ds_read_b128 v[172:175], v166 offset:51200
	ds_read_b128 v[176:179], v166 offset:52224
	ds_read_b128 v[180:183], v166 offset:53248
	ds_read_b128 v[204:207], v166 offset:54272
	ds_read_b128 v[208:211], v166 offset:55296
	ds_read_b128 v[212:215], v166 offset:56320
	global_load_lds_dwordx4 v130, s[72:73]
	s_mov_b32 m0, s43
	s_nop 0
	global_load_lds_dwordx4 v134, s[72:73]
	s_barrier
	s_waitcnt lgkmcnt(0)
	v_mfma_f32_16x16x32_bf16 v[62:65], v[142:145], v[158:161], v[62:65]
	v_mfma_f32_16x16x32_bf16 v[58:61], v[150:153], v[158:161], v[58:61]
	v_mfma_f32_16x16x32_bf16 v[46:49], v[142:145], v[172:175], v[46:49]
	v_mfma_f32_16x16x32_bf16 v[42:45], v[150:153], v[172:175], v[42:45]
	v_mfma_f32_16x16x32_bf16 v[30:33], v[142:145], v[180:183], v[30:33]
	v_mfma_f32_16x16x32_bf16 v[26:29], v[150:153], v[180:183], v[26:29]
	v_mfma_f32_16x16x32_bf16 v[14:17], v[142:145], v[208:211], v[14:17]
	v_mfma_f32_16x16x32_bf16 v[10:13], v[150:153], v[208:211], v[10:13]
	v_mfma_f32_16x16x32_bf16 v[62:65], v[146:149], v[168:171], v[62:65]
	v_mfma_f32_16x16x32_bf16 v[58:61], v[154:157], v[168:171], v[58:61]
	v_mfma_f32_16x16x32_bf16 v[46:49], v[146:149], v[176:179], v[46:49]
	v_mfma_f32_16x16x32_bf16 v[42:45], v[154:157], v[176:179], v[42:45]
	v_mfma_f32_16x16x32_bf16 v[30:33], v[146:149], v[204:207], v[30:33]
	v_mfma_f32_16x16x32_bf16 v[26:29], v[154:157], v[204:207], v[26:29]
	v_mfma_f32_16x16x32_bf16 v[14:17], v[146:149], v[212:215], v[14:17]
	v_mfma_f32_16x16x32_bf16 v[10:13], v[154:157], v[212:215], v[10:13]
	s_barrier
	s_add_i32 s4, s4, s28
	s_mov_b32 m0, s4
	s_nop 0
	global_load_lds_dwordx4 v132, s[80:81]
	s_add_i32 m0, s4, 0x2000
	s_nop 0
	global_load_lds_dwordx4 v136, s[80:81]
	s_add_u32 s0, s0, 0x100
	s_addc_u32 s1, s1, 0
	s_add_u32 s20, s20, 0x100
	s_addc_u32 s21, s21, 0
	s_cmp_ge_u32 s22, s35
	s_mov_b32 s4, s22
	s_waitcnt vmcnt(6)
	s_barrier
	v_mfma_f32_16x16x32_bf16 v[54:57], v[216:219], v[158:161], v[54:57]
	v_mfma_f32_16x16x32_bf16 v[50:53], v[224:227], v[158:161], v[50:53]
	v_mfma_f32_16x16x32_bf16 v[38:41], v[216:219], v[172:175], v[38:41]
	v_mfma_f32_16x16x32_bf16 v[34:37], v[224:227], v[172:175], v[34:37]
	v_mfma_f32_16x16x32_bf16 v[22:25], v[216:219], v[180:183], v[22:25]
	v_mfma_f32_16x16x32_bf16 v[18:21], v[224:227], v[180:183], v[18:21]
	v_mfma_f32_16x16x32_bf16 v[6:9], v[216:219], v[208:211], v[6:9]
	v_mfma_f32_16x16x32_bf16 v[2:5], v[224:227], v[208:211], v[2:5]
	v_mfma_f32_16x16x32_bf16 v[54:57], v[220:223], v[168:171], v[54:57]
	v_mfma_f32_16x16x32_bf16 v[50:53], v[228:231], v[168:171], v[50:53]
	v_mfma_f32_16x16x32_bf16 v[38:41], v[220:223], v[176:179], v[38:41]
	v_mfma_f32_16x16x32_bf16 v[34:37], v[228:231], v[176:179], v[34:37]
	v_mfma_f32_16x16x32_bf16 v[22:25], v[220:223], v[204:207], v[22:25]
	v_mfma_f32_16x16x32_bf16 v[18:21], v[228:231], v[204:207], v[18:21]
	v_mfma_f32_16x16x32_bf16 v[6:9], v[220:223], v[212:215], v[6:9]
	v_mfma_f32_16x16x32_bf16 v[2:5], v[228:231], v[212:215], v[2:5]
	s_barrier
	s_cbranch_scc0 .LBB0_282

.LBB0_346:
	s_add_u32 s0, s0, 0x80
	s_addc_u32 s1, s1, 0
	s_add_u32 s12, s4, 0x100
	s_addc_u32 s13, s5, 0
	s_mov_b32 s4, 0
	s_waitcnt lgkmcnt(0)
	s_waitcnt vmcnt(0)
	s_add_i32 s15, s4, 2
	s_add_u32 s10, s0, 0x80
	s_addc_u32 s5, s1, 0
	s_add_i32 s16, 0, 0x10000
	ds_read_b128 v[130:133], v248
	ds_read_b128 v[134:137], v248 offset:1024
	ds_read_b128 v[138:141], v248 offset:2048
	ds_read_b128 v[142:145], v248 offset:3072
	s_cmp_eq_u32 s79, s4
	s_cselect_b32 s4, s44, s10
	s_cselect_b32 s5, s45, s5
	s_cselect_b32 s11, s47, s13
	s_cselect_b32 s10, s46, s12
	s_add_i32 m0, s71, 0xc000
	ds_read_b128 v[158:161], v206
	ds_read_b128 v[162:165], v206 offset:1024
	ds_read_b128 v[166:169], v206 offset:2048
	ds_read_b128 v[170:173], v206 offset:3072
	ds_read_b128 v[174:177], v206 offset:4096
	ds_read_b128 v[178:181], v206 offset:5120
	ds_read_b128 v[182:185], v206 offset:6144
	ds_read_b128 v[208:211], v206 offset:7168
	global_load_lds_dwordx4 v154, s[0:1]
	s_add_i32 m0, s71, 0xe000
	s_nop 0
	global_load_lds_dwordx4 v156, s[0:1]
	s_waitcnt lgkmcnt(8)
	s_barrier
	s_waitcnt lgkmcnt(0)
	v_mfma_f32_16x16x32_bf16 v[126:129], v[130:133], v[158:161], 0
	v_mfma_f32_16x16x32_bf16 v[122:125], v[138:141], v[158:161], 0
	v_mfma_f32_16x16x32_bf16 v[110:113], v[130:133], v[166:169], 0
	v_mfma_f32_16x16x32_bf16 v[106:109], v[138:141], v[166:169], 0
	v_mfma_f32_16x16x32_bf16 v[94:97], v[130:133], v[174:177], 0
	v_mfma_f32_16x16x32_bf16 v[90:93], v[138:141], v[174:177], 0
	v_mfma_f32_16x16x32_bf16 v[78:81], v[130:133], v[182:185], 0
	v_mfma_f32_16x16x32_bf16 v[74:77], v[138:141], v[182:185], 0
	v_mfma_f32_16x16x32_bf16 v[126:129], v[134:137], v[162:165], v[126:129]
	v_mfma_f32_16x16x32_bf16 v[122:125], v[142:145], v[162:165], v[122:125]
	v_mfma_f32_16x16x32_bf16 v[110:113], v[134:137], v[170:173], v[110:113]
	v_mfma_f32_16x16x32_bf16 v[106:109], v[142:145], v[170:173], v[106:109]
	v_mfma_f32_16x16x32_bf16 v[94:97], v[134:137], v[178:181], v[94:97]
	v_mfma_f32_16x16x32_bf16 v[90:93], v[142:145], v[178:181], v[90:93]
	v_mfma_f32_16x16x32_bf16 v[78:81], v[134:137], v[208:211], v[78:81]
	v_mfma_f32_16x16x32_bf16 v[74:77], v[142:145], v[208:211], v[74:77]
	s_barrier
	s_add_i32 s17, 0, 0x14000
	s_add_i32 s16, s16, s70
	s_add_u32 s2, s10, s6
	s_addc_u32 s3, s11, s7
	s_mov_b32 m0, s16
	ds_read_b128 v[212:215], v248 offset:16384
	ds_read_b128 v[216:219], v248 offset:17408
	ds_read_b128 v[220:223], v248 offset:18432
	ds_read_b128 v[224:227], v248 offset:19456
	global_load_lds_dwordx4 v148, s[10:11]
	s_add_i32 m0, s16, 0x2000
	s_nop 0
	global_load_lds_dwordx4 v152, s[10:11]
	s_barrier
	s_waitcnt lgkmcnt(0)
	v_mfma_f32_16x16x32_bf16 v[118:121], v[212:215], v[158:161], 0
	v_mfma_f32_16x16x32_bf16 v[114:117], v[220:223], v[158:161], 0
	v_mfma_f32_16x16x32_bf16 v[102:105], v[212:215], v[166:169], 0
	v_mfma_f32_16x16x32_bf16 v[98:101], v[220:223], v[166:169], 0
	v_mfma_f32_16x16x32_bf16 v[86:89], v[212:215], v[174:177], 0
	v_mfma_f32_16x16x32_bf16 v[82:85], v[220:223], v[174:177], 0
	v_mfma_f32_16x16x32_bf16 v[70:73], v[212:215], v[182:185], 0
	v_mfma_f32_16x16x32_bf16 v[66:69], v[220:223], v[182:185], 0
	v_mfma_f32_16x16x32_bf16 v[118:121], v[216:219], v[162:165], v[118:121]
	v_mfma_f32_16x16x32_bf16 v[114:117], v[224:227], v[162:165], v[114:117]
	v_mfma_f32_16x16x32_bf16 v[102:105], v[216:219], v[170:173], v[102:105]
	v_mfma_f32_16x16x32_bf16 v[98:101], v[224:227], v[170:173], v[98:101]
	v_mfma_f32_16x16x32_bf16 v[86:89], v[216:219], v[178:181], v[86:89]
	v_mfma_f32_16x16x32_bf16 v[82:85], v[224:227], v[178:181], v[82:85]
	v_mfma_f32_16x16x32_bf16 v[70:73], v[216:219], v[208:211], v[70:73]
	v_mfma_f32_16x16x32_bf16 v[66:69], v[224:227], v[208:211], v[66:69]
	s_barrier
	s_mov_b32 m0, s71
	s_add_u32 s98, s4, s6
	s_addc_u32 s99, s5, s7
	ds_read_b128 v[158:161], v206 offset:16384
	ds_read_b128 v[162:165], v206 offset:17408
	ds_read_b128 v[166:169], v206 offset:18432
	ds_read_b128 v[170:173], v206 offset:19456
	ds_read_b128 v[174:177], v206 offset:20480
	ds_read_b128 v[178:181], v206 offset:21504
	ds_read_b128 v[182:185], v206 offset:22528
	ds_read_b128 v[208:211], v206 offset:23552
	global_load_lds_dwordx4 v146, s[4:5]
	s_mov_b32 m0, s72
	s_nop 0
	global_load_lds_dwordx4 v150, s[4:5]
	s_barrier
	s_waitcnt lgkmcnt(0)
	v_mfma_f32_16x16x32_bf16 v[62:65], v[130:133], v[158:161], 0
	v_mfma_f32_16x16x32_bf16 v[58:61], v[138:141], v[158:161], 0
	v_mfma_f32_16x16x32_bf16 v[46:49], v[130:133], v[166:169], 0
	v_mfma_f32_16x16x32_bf16 v[42:45], v[138:141], v[166:169], 0
	v_mfma_f32_16x16x32_bf16 v[30:33], v[130:133], v[174:177], 0
	v_mfma_f32_16x16x32_bf16 v[26:29], v[138:141], v[174:177], 0
	v_mfma_f32_16x16x32_bf16 v[14:17], v[130:133], v[182:185], 0
	v_mfma_f32_16x16x32_bf16 v[10:13], v[138:141], v[182:185], 0
	v_mfma_f32_16x16x32_bf16 v[62:65], v[134:137], v[162:165], v[62:65]
	v_mfma_f32_16x16x32_bf16 v[58:61], v[142:145], v[162:165], v[58:61]
	v_mfma_f32_16x16x32_bf16 v[46:49], v[134:137], v[170:173], v[46:49]
	v_mfma_f32_16x16x32_bf16 v[42:45], v[142:145], v[170:173], v[42:45]
	v_mfma_f32_16x16x32_bf16 v[30:33], v[134:137], v[178:181], v[30:33]
	v_mfma_f32_16x16x32_bf16 v[26:29], v[142:145], v[178:181], v[26:29]
	v_mfma_f32_16x16x32_bf16 v[14:17], v[134:137], v[208:211], v[14:17]
	v_mfma_f32_16x16x32_bf16 v[10:13], v[142:145], v[208:211], v[10:13]
	s_barrier
	s_add_u32 s10, s10, s92
	s_addc_u32 s11, s11, 0
	s_add_i32 s16, s17, s70
	v_lshl_add_u64 v[236:237], s[10:11], 0, v[148:149]
	s_mov_b32 m0, s16
	v_lshl_add_u64 v[238:239], s[10:11], 0, v[152:153]
	global_load_lds_dwordx4 v[236:237], off
	s_add_i32 m0, s16, 0x2000
	s_nop 0
	global_load_lds_dwordx4 v[238:239], off
	s_waitcnt vmcnt(6)
	s_barrier
	v_mfma_f32_16x16x32_bf16 v[54:57], v[212:215], v[158:161], 0
	v_mfma_f32_16x16x32_bf16 v[50:53], v[220:223], v[158:161], 0
	v_mfma_f32_16x16x32_bf16 v[38:41], v[212:215], v[166:169], 0
	v_mfma_f32_16x16x32_bf16 v[34:37], v[220:223], v[166:169], 0
	v_mfma_f32_16x16x32_bf16 v[22:25], v[212:215], v[174:177], 0
	v_mfma_f32_16x16x32_bf16 v[18:21], v[220:223], v[174:177], 0
	v_mfma_f32_16x16x32_bf16 v[6:9], v[212:215], v[182:185], 0
	v_mfma_f32_16x16x32_bf16 v[2:5], v[220:223], v[182:185], 0
	v_mfma_f32_16x16x32_bf16 v[54:57], v[216:219], v[162:165], v[54:57]
	v_mfma_f32_16x16x32_bf16 v[50:53], v[224:227], v[162:165], v[50:53]
	v_mfma_f32_16x16x32_bf16 v[38:41], v[216:219], v[170:173], v[38:41]
	v_mfma_f32_16x16x32_bf16 v[34:37], v[224:227], v[170:173], v[34:37]
	v_mfma_f32_16x16x32_bf16 v[22:25], v[216:219], v[178:181], v[22:25]
	v_mfma_f32_16x16x32_bf16 v[18:21], v[224:227], v[178:181], v[18:21]
	v_mfma_f32_16x16x32_bf16 v[6:9], v[216:219], v[208:211], v[6:9]
	v_mfma_f32_16x16x32_bf16 v[2:5], v[224:227], v[208:211], v[2:5]
	s_barrier
	s_add_i32 s10, 0, 0x18000
	ds_read_b128 v[130:133], v248 offset:32768
	ds_read_b128 v[134:137], v248 offset:33792
	ds_read_b128 v[138:141], v248 offset:34816
	ds_read_b128 v[142:145], v248 offset:35840
	s_add_u32 s4, s4, s92
	s_addc_u32 s5, s5, 0
	s_mov_b32 m0, s73
	ds_read_b128 v[158:161], v206 offset:32768
	ds_read_b128 v[162:165], v206 offset:33792
	ds_read_b128 v[166:169], v206 offset:34816
	ds_read_b128 v[170:173], v206 offset:35840
	ds_read_b128 v[174:177], v206 offset:36864
	ds_read_b128 v[178:181], v206 offset:37888
	ds_read_b128 v[182:185], v206 offset:38912
	ds_read_b128 v[208:211], v206 offset:39936
	global_load_lds_dwordx4 v146, s[4:5]
	s_mov_b32 m0, s74
	s_nop 0
	global_load_lds_dwordx4 v150, s[4:5]
	s_waitcnt lgkmcnt(8)
	s_barrier
	s_waitcnt lgkmcnt(0)
	v_mfma_f32_16x16x32_bf16 v[126:129], v[130:133], v[158:161], v[126:129]
	v_mfma_f32_16x16x32_bf16 v[122:125], v[138:141], v[158:161], v[122:125]
	v_mfma_f32_16x16x32_bf16 v[110:113], v[130:133], v[166:169], v[110:113]
	v_mfma_f32_16x16x32_bf16 v[106:109], v[138:141], v[166:169], v[106:109]
	v_mfma_f32_16x16x32_bf16 v[94:97], v[130:133], v[174:177], v[94:97]
	v_mfma_f32_16x16x32_bf16 v[90:93], v[138:141], v[174:177], v[90:93]
	v_mfma_f32_16x16x32_bf16 v[78:81], v[130:133], v[182:185], v[78:81]
	v_mfma_f32_16x16x32_bf16 v[74:77], v[138:141], v[182:185], v[74:77]
	v_mfma_f32_16x16x32_bf16 v[126:129], v[134:137], v[162:165], v[126:129]
	v_mfma_f32_16x16x32_bf16 v[122:125], v[142:145], v[162:165], v[122:125]
	v_mfma_f32_16x16x32_bf16 v[110:113], v[134:137], v[170:173], v[110:113]
	v_mfma_f32_16x16x32_bf16 v[106:109], v[142:145], v[170:173], v[106:109]
	v_mfma_f32_16x16x32_bf16 v[94:97], v[134:137], v[178:181], v[94:97]
	v_mfma_f32_16x16x32_bf16 v[90:93], v[142:145], v[178:181], v[90:93]
	v_mfma_f32_16x16x32_bf16 v[78:81], v[134:137], v[208:211], v[78:81]
	v_mfma_f32_16x16x32_bf16 v[74:77], v[142:145], v[208:211], v[74:77]
	s_barrier
	s_add_i32 s4, 0, 0x1c000
	s_add_i32 s5, s10, s70
	s_mov_b32 m0, s5
	ds_read_b128 v[212:215], v248 offset:49152
	ds_read_b128 v[216:219], v248 offset:50176
	ds_read_b128 v[220:223], v248 offset:51200
	ds_read_b128 v[224:227], v248 offset:52224
	global_load_lds_dwordx4 v148, s[2:3]
	s_add_i32 m0, s5, 0x2000
	s_nop 0
	global_load_lds_dwordx4 v152, s[2:3]
	s_barrier
	s_waitcnt lgkmcnt(0)
	v_mfma_f32_16x16x32_bf16 v[118:121], v[212:215], v[158:161], v[118:121]
	v_mfma_f32_16x16x32_bf16 v[114:117], v[220:223], v[158:161], v[114:117]
	v_mfma_f32_16x16x32_bf16 v[102:105], v[212:215], v[166:169], v[102:105]
	v_mfma_f32_16x16x32_bf16 v[98:101], v[220:223], v[166:169], v[98:101]
	v_mfma_f32_16x16x32_bf16 v[86:89], v[212:215], v[174:177], v[86:89]
	v_mfma_f32_16x16x32_bf16 v[82:85], v[220:223], v[174:177], v[82:85]
	v_mfma_f32_16x16x32_bf16 v[70:73], v[212:215], v[182:185], v[70:73]
	v_mfma_f32_16x16x32_bf16 v[66:69], v[220:223], v[182:185], v[66:69]
	v_mfma_f32_16x16x32_bf16 v[118:121], v[216:219], v[162:165], v[118:121]
	v_mfma_f32_16x16x32_bf16 v[114:117], v[224:227], v[162:165], v[114:117]
	v_mfma_f32_16x16x32_bf16 v[102:105], v[216:219], v[170:173], v[102:105]
	v_mfma_f32_16x16x32_bf16 v[98:101], v[224:227], v[170:173], v[98:101]
	v_mfma_f32_16x16x32_bf16 v[86:89], v[216:219], v[178:181], v[86:89]
	v_mfma_f32_16x16x32_bf16 v[82:85], v[224:227], v[178:181], v[82:85]
	v_mfma_f32_16x16x32_bf16 v[70:73], v[216:219], v[208:211], v[70:73]
	v_mfma_f32_16x16x32_bf16 v[66:69], v[224:227], v[208:211], v[66:69]
	s_barrier
	s_mov_b32 m0, s77
	ds_read_b128 v[158:161], v206 offset:49152
	ds_read_b128 v[162:165], v206 offset:50176
	ds_read_b128 v[166:169], v206 offset:51200
	ds_read_b128 v[170:173], v206 offset:52224
	ds_read_b128 v[174:177], v206 offset:53248
	ds_read_b128 v[178:181], v206 offset:54272
	ds_read_b128 v[182:185], v206 offset:55296
	ds_read_b128 v[208:211], v206 offset:56320
	global_load_lds_dwordx4 v146, s[98:99]
	s_mov_b32 m0, s78
	s_nop 0
	global_load_lds_dwordx4 v150, s[98:99]
	s_barrier
	s_waitcnt lgkmcnt(0)
	v_mfma_f32_16x16x32_bf16 v[62:65], v[130:133], v[158:161], v[62:65]
	v_mfma_f32_16x16x32_bf16 v[58:61], v[138:141], v[158:161], v[58:61]
	v_mfma_f32_16x16x32_bf16 v[46:49], v[130:133], v[166:169], v[46:49]
	v_mfma_f32_16x16x32_bf16 v[42:45], v[138:141], v[166:169], v[42:45]
	v_mfma_f32_16x16x32_bf16 v[30:33], v[130:133], v[174:177], v[30:33]
	v_mfma_f32_16x16x32_bf16 v[26:29], v[138:141], v[174:177], v[26:29]
	v_mfma_f32_16x16x32_bf16 v[14:17], v[130:133], v[182:185], v[14:17]
	v_mfma_f32_16x16x32_bf16 v[10:13], v[138:141], v[182:185], v[10:13]
	v_mfma_f32_16x16x32_bf16 v[62:65], v[134:137], v[162:165], v[62:65]
	v_mfma_f32_16x16x32_bf16 v[58:61], v[142:145], v[162:165], v[58:61]
	v_mfma_f32_16x16x32_bf16 v[46:49], v[134:137], v[170:173], v[46:49]
	v_mfma_f32_16x16x32_bf16 v[42:45], v[142:145], v[170:173], v[42:45]
	v_mfma_f32_16x16x32_bf16 v[30:33], v[134:137], v[178:181], v[30:33]
	v_mfma_f32_16x16x32_bf16 v[26:29], v[142:145], v[178:181], v[26:29]
	v_mfma_f32_16x16x32_bf16 v[14:17], v[134:137], v[208:211], v[14:17]
	v_mfma_f32_16x16x32_bf16 v[10:13], v[142:145], v[208:211], v[10:13]
	s_barrier
	s_add_i32 s4, s4, s70
	v_lshl_add_u64 v[130:131], v[236:237], 0, s[6:7]
	s_mov_b32 m0, s4
	s_nop 0
	global_load_lds_dwordx4 v[130:131], off
	v_lshl_add_u64 v[130:131], v[238:239], 0, s[6:7]
	s_add_i32 m0, s4, 0x2000
	s_nop 0
	global_load_lds_dwordx4 v[130:131], off
	s_add_u32 s0, s0, 0x100
	s_addc_u32 s1, s1, 0
	s_add_u32 s12, s12, 0x100
	s_addc_u32 s13, s13, 0
	s_cmp_ge_u32 s15, s75
	s_mov_b32 s4, s15
	s_waitcnt vmcnt(6)
	s_barrier
	v_mfma_f32_16x16x32_bf16 v[54:57], v[212:215], v[158:161], v[54:57]
	v_mfma_f32_16x16x32_bf16 v[50:53], v[220:223], v[158:161], v[50:53]
	v_mfma_f32_16x16x32_bf16 v[38:41], v[212:215], v[166:169], v[38:41]
	v_mfma_f32_16x16x32_bf16 v[34:37], v[220:223], v[166:169], v[34:37]
	v_mfma_f32_16x16x32_bf16 v[22:25], v[212:215], v[174:177], v[22:25]
	v_mfma_f32_16x16x32_bf16 v[18:21], v[220:223], v[174:177], v[18:21]
	v_mfma_f32_16x16x32_bf16 v[6:9], v[212:215], v[182:185], v[6:9]
	v_mfma_f32_16x16x32_bf16 v[2:5], v[220:223], v[182:185], v[2:5]
	v_mfma_f32_16x16x32_bf16 v[54:57], v[216:219], v[162:165], v[54:57]
	v_mfma_f32_16x16x32_bf16 v[50:53], v[224:227], v[162:165], v[50:53]
	v_mfma_f32_16x16x32_bf16 v[38:41], v[216:219], v[170:173], v[38:41]
	v_mfma_f32_16x16x32_bf16 v[34:37], v[224:227], v[170:173], v[34:37]
	v_mfma_f32_16x16x32_bf16 v[22:25], v[216:219], v[178:181], v[22:25]
	v_mfma_f32_16x16x32_bf16 v[18:21], v[224:227], v[178:181], v[18:21]
	v_mfma_f32_16x16x32_bf16 v[6:9], v[216:219], v[208:211], v[6:9]
	v_mfma_f32_16x16x32_bf16 v[2:5], v[224:227], v[208:211], v[2:5]
	s_barrier
	s_cbranch_scc1 .Lkexit_347
.LBB0_347:
	s_add_i32 s15, s4, 2
	s_add_u32 s10, s0, 0x80
	s_addc_u32 s5, s1, 0
	s_add_i32 s16, 0, 0x10000
	ds_read_b128 v[130:133], v248
	ds_read_b128 v[134:137], v248 offset:1024
	ds_read_b128 v[138:141], v248 offset:2048
	ds_read_b128 v[142:145], v248 offset:3072
	s_cmp_eq_u32 s79, s4
	s_cselect_b32 s4, s44, s10
	s_cselect_b32 s5, s45, s5
	s_cselect_b32 s11, s47, s13
	s_cselect_b32 s10, s46, s12
	s_add_i32 m0, s71, 0xc000
	ds_read_b128 v[158:161], v206
	ds_read_b128 v[162:165], v206 offset:1024
	ds_read_b128 v[166:169], v206 offset:2048
	ds_read_b128 v[170:173], v206 offset:3072
	ds_read_b128 v[174:177], v206 offset:4096
	ds_read_b128 v[178:181], v206 offset:5120
	ds_read_b128 v[182:185], v206 offset:6144
	ds_read_b128 v[208:211], v206 offset:7168
	global_load_lds_dwordx4 v154, s[0:1]
	s_add_i32 m0, s71, 0xe000
	s_nop 0
	global_load_lds_dwordx4 v156, s[0:1]
	s_waitcnt lgkmcnt(8)
	s_barrier
	s_waitcnt lgkmcnt(0)
	v_mfma_f32_16x16x32_bf16 v[126:129], v[130:133], v[158:161], v[126:129]
	v_mfma_f32_16x16x32_bf16 v[122:125], v[138:141], v[158:161], v[122:125]
	v_mfma_f32_16x16x32_bf16 v[110:113], v[130:133], v[166:169], v[110:113]
	v_mfma_f32_16x16x32_bf16 v[106:109], v[138:141], v[166:169], v[106:109]
	v_mfma_f32_16x16x32_bf16 v[94:97], v[130:133], v[174:177], v[94:97]
	v_mfma_f32_16x16x32_bf16 v[90:93], v[138:141], v[174:177], v[90:93]
	v_mfma_f32_16x16x32_bf16 v[78:81], v[130:133], v[182:185], v[78:81]
	v_mfma_f32_16x16x32_bf16 v[74:77], v[138:141], v[182:185], v[74:77]
	v_mfma_f32_16x16x32_bf16 v[126:129], v[134:137], v[162:165], v[126:129]
	v_mfma_f32_16x16x32_bf16 v[122:125], v[142:145], v[162:165], v[122:125]
	v_mfma_f32_16x16x32_bf16 v[110:113], v[134:137], v[170:173], v[110:113]
	v_mfma_f32_16x16x32_bf16 v[106:109], v[142:145], v[170:173], v[106:109]
	v_mfma_f32_16x16x32_bf16 v[94:97], v[134:137], v[178:181], v[94:97]
	v_mfma_f32_16x16x32_bf16 v[90:93], v[142:145], v[178:181], v[90:93]
	v_mfma_f32_16x16x32_bf16 v[78:81], v[134:137], v[208:211], v[78:81]
	v_mfma_f32_16x16x32_bf16 v[74:77], v[142:145], v[208:211], v[74:77]
	s_barrier
	s_add_i32 s17, 0, 0x14000
	s_add_i32 s16, s16, s70
	s_add_u32 s2, s10, s6
	s_addc_u32 s3, s11, s7
	s_mov_b32 m0, s16
	ds_read_b128 v[212:215], v248 offset:16384
	ds_read_b128 v[216:219], v248 offset:17408
	ds_read_b128 v[220:223], v248 offset:18432
	ds_read_b128 v[224:227], v248 offset:19456
	global_load_lds_dwordx4 v148, s[10:11]
	s_add_i32 m0, s16, 0x2000
	s_nop 0
	global_load_lds_dwordx4 v152, s[10:11]
	s_barrier
	s_waitcnt lgkmcnt(0)
	v_mfma_f32_16x16x32_bf16 v[118:121], v[212:215], v[158:161], v[118:121]
	v_mfma_f32_16x16x32_bf16 v[114:117], v[220:223], v[158:161], v[114:117]
	v_mfma_f32_16x16x32_bf16 v[102:105], v[212:215], v[166:169], v[102:105]
	v_mfma_f32_16x16x32_bf16 v[98:101], v[220:223], v[166:169], v[98:101]
	v_mfma_f32_16x16x32_bf16 v[86:89], v[212:215], v[174:177], v[86:89]
	v_mfma_f32_16x16x32_bf16 v[82:85], v[220:223], v[174:177], v[82:85]
	v_mfma_f32_16x16x32_bf16 v[70:73], v[212:215], v[182:185], v[70:73]
	v_mfma_f32_16x16x32_bf16 v[66:69], v[220:223], v[182:185], v[66:69]
	v_mfma_f32_16x16x32_bf16 v[118:121], v[216:219], v[162:165], v[118:121]
	v_mfma_f32_16x16x32_bf16 v[114:117], v[224:227], v[162:165], v[114:117]
	v_mfma_f32_16x16x32_bf16 v[102:105], v[216:219], v[170:173], v[102:105]
	v_mfma_f32_16x16x32_bf16 v[98:101], v[224:227], v[170:173], v[98:101]
	v_mfma_f32_16x16x32_bf16 v[86:89], v[216:219], v[178:181], v[86:89]
	v_mfma_f32_16x16x32_bf16 v[82:85], v[224:227], v[178:181], v[82:85]
	v_mfma_f32_16x16x32_bf16 v[70:73], v[216:219], v[208:211], v[70:73]
	v_mfma_f32_16x16x32_bf16 v[66:69], v[224:227], v[208:211], v[66:69]
	s_barrier
	s_mov_b32 m0, s71
	s_add_u32 s98, s4, s6
	s_addc_u32 s99, s5, s7
	ds_read_b128 v[158:161], v206 offset:16384
	ds_read_b128 v[162:165], v206 offset:17408
	ds_read_b128 v[166:169], v206 offset:18432
	ds_read_b128 v[170:173], v206 offset:19456
	ds_read_b128 v[174:177], v206 offset:20480
	ds_read_b128 v[178:181], v206 offset:21504
	ds_read_b128 v[182:185], v206 offset:22528
	ds_read_b128 v[208:211], v206 offset:23552
	global_load_lds_dwordx4 v146, s[4:5]
	s_mov_b32 m0, s72
	s_nop 0
	global_load_lds_dwordx4 v150, s[4:5]
	s_barrier
	s_waitcnt lgkmcnt(0)
	v_mfma_f32_16x16x32_bf16 v[62:65], v[130:133], v[158:161], v[62:65]
	v_mfma_f32_16x16x32_bf16 v[58:61], v[138:141], v[158:161], v[58:61]
	v_mfma_f32_16x16x32_bf16 v[46:49], v[130:133], v[166:169], v[46:49]
	v_mfma_f32_16x16x32_bf16 v[42:45], v[138:141], v[166:169], v[42:45]
	v_mfma_f32_16x16x32_bf16 v[30:33], v[130:133], v[174:177], v[30:33]
	v_mfma_f32_16x16x32_bf16 v[26:29], v[138:141], v[174:177], v[26:29]
	v_mfma_f32_16x16x32_bf16 v[14:17], v[130:133], v[182:185], v[14:17]
	v_mfma_f32_16x16x32_bf16 v[10:13], v[138:141], v[182:185], v[10:13]
	v_mfma_f32_16x16x32_bf16 v[62:65], v[134:137], v[162:165], v[62:65]
	v_mfma_f32_16x16x32_bf16 v[58:61], v[142:145], v[162:165], v[58:61]
	v_mfma_f32_16x16x32_bf16 v[46:49], v[134:137], v[170:173], v[46:49]
	v_mfma_f32_16x16x32_bf16 v[42:45], v[142:145], v[170:173], v[42:45]
	v_mfma_f32_16x16x32_bf16 v[30:33], v[134:137], v[178:181], v[30:33]
	v_mfma_f32_16x16x32_bf16 v[26:29], v[142:145], v[178:181], v[26:29]
	v_mfma_f32_16x16x32_bf16 v[14:17], v[134:137], v[208:211], v[14:17]
	v_mfma_f32_16x16x32_bf16 v[10:13], v[142:145], v[208:211], v[10:13]
	s_barrier
	s_add_u32 s10, s10, s92
	s_addc_u32 s11, s11, 0
	s_add_i32 s16, s17, s70
	v_lshl_add_u64 v[236:237], s[10:11], 0, v[148:149]
	s_mov_b32 m0, s16
	v_lshl_add_u64 v[238:239], s[10:11], 0, v[152:153]
	global_load_lds_dwordx4 v[236:237], off
	s_add_i32 m0, s16, 0x2000
	s_nop 0
	global_load_lds_dwordx4 v[238:239], off
	s_waitcnt vmcnt(6)
	s_barrier
	v_mfma_f32_16x16x32_bf16 v[54:57], v[212:215], v[158:161], v[54:57]
	v_mfma_f32_16x16x32_bf16 v[50:53], v[220:223], v[158:161], v[50:53]
	v_mfma_f32_16x16x32_bf16 v[38:41], v[212:215], v[166:169], v[38:41]
	v_mfma_f32_16x16x32_bf16 v[34:37], v[220:223], v[166:169], v[34:37]
	v_mfma_f32_16x16x32_bf16 v[22:25], v[212:215], v[174:177], v[22:25]
	v_mfma_f32_16x16x32_bf16 v[18:21], v[220:223], v[174:177], v[18:21]
	v_mfma_f32_16x16x32_bf16 v[6:9], v[212:215], v[182:185], v[6:9]
	v_mfma_f32_16x16x32_bf16 v[2:5], v[220:223], v[182:185], v[2:5]
	v_mfma_f32_16x16x32_bf16 v[54:57], v[216:219], v[162:165], v[54:57]
	v_mfma_f32_16x16x32_bf16 v[50:53], v[224:227], v[162:165], v[50:53]
	v_mfma_f32_16x16x32_bf16 v[38:41], v[216:219], v[170:173], v[38:41]
	v_mfma_f32_16x16x32_bf16 v[34:37], v[224:227], v[170:173], v[34:37]
	v_mfma_f32_16x16x32_bf16 v[22:25], v[216:219], v[178:181], v[22:25]
	v_mfma_f32_16x16x32_bf16 v[18:21], v[224:227], v[178:181], v[18:21]
	v_mfma_f32_16x16x32_bf16 v[6:9], v[216:219], v[208:211], v[6:9]
	v_mfma_f32_16x16x32_bf16 v[2:5], v[224:227], v[208:211], v[2:5]
	s_barrier
	s_add_i32 s10, 0, 0x18000
	ds_read_b128 v[130:133], v248 offset:32768
	ds_read_b128 v[134:137], v248 offset:33792
	ds_read_b128 v[138:141], v248 offset:34816
	ds_read_b128 v[142:145], v248 offset:35840
	s_add_u32 s4, s4, s92
	s_addc_u32 s5, s5, 0
	s_mov_b32 m0, s73
	ds_read_b128 v[158:161], v206 offset:32768
	ds_read_b128 v[162:165], v206 offset:33792
	ds_read_b128 v[166:169], v206 offset:34816
	ds_read_b128 v[170:173], v206 offset:35840
	ds_read_b128 v[174:177], v206 offset:36864
	ds_read_b128 v[178:181], v206 offset:37888
	ds_read_b128 v[182:185], v206 offset:38912
	ds_read_b128 v[208:211], v206 offset:39936
	global_load_lds_dwordx4 v146, s[4:5]
	s_mov_b32 m0, s74
	s_nop 0
	global_load_lds_dwordx4 v150, s[4:5]
	s_waitcnt lgkmcnt(8)
	s_barrier
	s_waitcnt lgkmcnt(0)
	v_mfma_f32_16x16x32_bf16 v[126:129], v[130:133], v[158:161], v[126:129]
	v_mfma_f32_16x16x32_bf16 v[122:125], v[138:141], v[158:161], v[122:125]
	v_mfma_f32_16x16x32_bf16 v[110:113], v[130:133], v[166:169], v[110:113]
	v_mfma_f32_16x16x32_bf16 v[106:109], v[138:141], v[166:169], v[106:109]
	v_mfma_f32_16x16x32_bf16 v[94:97], v[130:133], v[174:177], v[94:97]
	v_mfma_f32_16x16x32_bf16 v[90:93], v[138:141], v[174:177], v[90:93]
	v_mfma_f32_16x16x32_bf16 v[78:81], v[130:133], v[182:185], v[78:81]
	v_mfma_f32_16x16x32_bf16 v[74:77], v[138:141], v[182:185], v[74:77]
	v_mfma_f32_16x16x32_bf16 v[126:129], v[134:137], v[162:165], v[126:129]
	v_mfma_f32_16x16x32_bf16 v[122:125], v[142:145], v[162:165], v[122:125]
	v_mfma_f32_16x16x32_bf16 v[110:113], v[134:137], v[170:173], v[110:113]
	v_mfma_f32_16x16x32_bf16 v[106:109], v[142:145], v[170:173], v[106:109]
	v_mfma_f32_16x16x32_bf16 v[94:97], v[134:137], v[178:181], v[94:97]
	v_mfma_f32_16x16x32_bf16 v[90:93], v[142:145], v[178:181], v[90:93]
	v_mfma_f32_16x16x32_bf16 v[78:81], v[134:137], v[208:211], v[78:81]
	v_mfma_f32_16x16x32_bf16 v[74:77], v[142:145], v[208:211], v[74:77]
	s_barrier
	s_add_i32 s4, 0, 0x1c000
	s_add_i32 s5, s10, s70
	s_mov_b32 m0, s5
	ds_read_b128 v[212:215], v248 offset:49152
	ds_read_b128 v[216:219], v248 offset:50176
	ds_read_b128 v[220:223], v248 offset:51200
	ds_read_b128 v[224:227], v248 offset:52224
	global_load_lds_dwordx4 v148, s[2:3]
	s_add_i32 m0, s5, 0x2000
	s_nop 0
	global_load_lds_dwordx4 v152, s[2:3]
	s_barrier
	s_waitcnt lgkmcnt(0)
	v_mfma_f32_16x16x32_bf16 v[118:121], v[212:215], v[158:161], v[118:121]
	v_mfma_f32_16x16x32_bf16 v[114:117], v[220:223], v[158:161], v[114:117]
	v_mfma_f32_16x16x32_bf16 v[102:105], v[212:215], v[166:169], v[102:105]
	v_mfma_f32_16x16x32_bf16 v[98:101], v[220:223], v[166:169], v[98:101]
	v_mfma_f32_16x16x32_bf16 v[86:89], v[212:215], v[174:177], v[86:89]
	v_mfma_f32_16x16x32_bf16 v[82:85], v[220:223], v[174:177], v[82:85]
	v_mfma_f32_16x16x32_bf16 v[70:73], v[212:215], v[182:185], v[70:73]
	v_mfma_f32_16x16x32_bf16 v[66:69], v[220:223], v[182:185], v[66:69]
	v_mfma_f32_16x16x32_bf16 v[118:121], v[216:219], v[162:165], v[118:121]
	v_mfma_f32_16x16x32_bf16 v[114:117], v[224:227], v[162:165], v[114:117]
	v_mfma_f32_16x16x32_bf16 v[102:105], v[216:219], v[170:173], v[102:105]
	v_mfma_f32_16x16x32_bf16 v[98:101], v[224:227], v[170:173], v[98:101]
	v_mfma_f32_16x16x32_bf16 v[86:89], v[216:219], v[178:181], v[86:89]
	v_mfma_f32_16x16x32_bf16 v[82:85], v[224:227], v[178:181], v[82:85]
	v_mfma_f32_16x16x32_bf16 v[70:73], v[216:219], v[208:211], v[70:73]
	v_mfma_f32_16x16x32_bf16 v[66:69], v[224:227], v[208:211], v[66:69]
	s_barrier
	s_mov_b32 m0, s77
	ds_read_b128 v[158:161], v206 offset:49152
	ds_read_b128 v[162:165], v206 offset:50176
	ds_read_b128 v[166:169], v206 offset:51200
	ds_read_b128 v[170:173], v206 offset:52224
	ds_read_b128 v[174:177], v206 offset:53248
	ds_read_b128 v[178:181], v206 offset:54272
	ds_read_b128 v[182:185], v206 offset:55296
	ds_read_b128 v[208:211], v206 offset:56320
	global_load_lds_dwordx4 v146, s[98:99]
	s_mov_b32 m0, s78
	s_nop 0
	global_load_lds_dwordx4 v150, s[98:99]
	s_barrier
	s_waitcnt lgkmcnt(0)
	v_mfma_f32_16x16x32_bf16 v[62:65], v[130:133], v[158:161], v[62:65]
	v_mfma_f32_16x16x32_bf16 v[58:61], v[138:141], v[158:161], v[58:61]
	v_mfma_f32_16x16x32_bf16 v[46:49], v[130:133], v[166:169], v[46:49]
	v_mfma_f32_16x16x32_bf16 v[42:45], v[138:141], v[166:169], v[42:45]
	v_mfma_f32_16x16x32_bf16 v[30:33], v[130:133], v[174:177], v[30:33]
	v_mfma_f32_16x16x32_bf16 v[26:29], v[138:141], v[174:177], v[26:29]
	v_mfma_f32_16x16x32_bf16 v[14:17], v[130:133], v[182:185], v[14:17]
	v_mfma_f32_16x16x32_bf16 v[10:13], v[138:141], v[182:185], v[10:13]
	v_mfma_f32_16x16x32_bf16 v[62:65], v[134:137], v[162:165], v[62:65]
	v_mfma_f32_16x16x32_bf16 v[58:61], v[142:145], v[162:165], v[58:61]
	v_mfma_f32_16x16x32_bf16 v[46:49], v[134:137], v[170:173], v[46:49]
	v_mfma_f32_16x16x32_bf16 v[42:45], v[142:145], v[170:173], v[42:45]
	v_mfma_f32_16x16x32_bf16 v[30:33], v[134:137], v[178:181], v[30:33]
	v_mfma_f32_16x16x32_bf16 v[26:29], v[142:145], v[178:181], v[26:29]
	v_mfma_f32_16x16x32_bf16 v[14:17], v[134:137], v[208:211], v[14:17]
	v_mfma_f32_16x16x32_bf16 v[10:13], v[142:145], v[208:211], v[10:13]
	s_barrier
	s_add_i32 s4, s4, s70
	v_lshl_add_u64 v[130:131], v[236:237], 0, s[6:7]
	s_mov_b32 m0, s4
	s_nop 0
	global_load_lds_dwordx4 v[130:131], off
	v_lshl_add_u64 v[130:131], v[238:239], 0, s[6:7]
	s_add_i32 m0, s4, 0x2000
	s_nop 0
	global_load_lds_dwordx4 v[130:131], off
	s_add_u32 s0, s0, 0x100
	s_addc_u32 s1, s1, 0
	s_add_u32 s12, s12, 0x100
	s_addc_u32 s13, s13, 0
	s_cmp_ge_u32 s15, s75
	s_mov_b32 s4, s15
	s_waitcnt vmcnt(6)
	s_barrier
	v_mfma_f32_16x16x32_bf16 v[54:57], v[212:215], v[158:161], v[54:57]
	v_mfma_f32_16x16x32_bf16 v[50:53], v[220:223], v[158:161], v[50:53]
	v_mfma_f32_16x16x32_bf16 v[38:41], v[212:215], v[166:169], v[38:41]
	v_mfma_f32_16x16x32_bf16 v[34:37], v[220:223], v[166:169], v[34:37]
	v_mfma_f32_16x16x32_bf16 v[22:25], v[212:215], v[174:177], v[22:25]
	v_mfma_f32_16x16x32_bf16 v[18:21], v[220:223], v[174:177], v[18:21]
	v_mfma_f32_16x16x32_bf16 v[6:9], v[212:215], v[182:185], v[6:9]
	v_mfma_f32_16x16x32_bf16 v[2:5], v[220:223], v[182:185], v[2:5]
	v_mfma_f32_16x16x32_bf16 v[54:57], v[216:219], v[162:165], v[54:57]
	v_mfma_f32_16x16x32_bf16 v[50:53], v[224:227], v[162:165], v[50:53]
	v_mfma_f32_16x16x32_bf16 v[38:41], v[216:219], v[170:173], v[38:41]
	v_mfma_f32_16x16x32_bf16 v[34:37], v[224:227], v[170:173], v[34:37]
	v_mfma_f32_16x16x32_bf16 v[22:25], v[216:219], v[178:181], v[22:25]
	v_mfma_f32_16x16x32_bf16 v[18:21], v[224:227], v[178:181], v[18:21]
	v_mfma_f32_16x16x32_bf16 v[6:9], v[216:219], v[208:211], v[6:9]
	v_mfma_f32_16x16x32_bf16 v[2:5], v[224:227], v[208:211], v[2:5]
	s_barrier
	s_cbranch_scc0 .LBB0_347

.LBB0_663:
	s_add_u32 s0, s0, 0x80
	s_addc_u32 s1, s1, 0
	s_add_u32 s49, s4, 0x100
	s_addc_u32 s65, s5, 0
	s_mov_b32 s4, 0
	s_waitcnt lgkmcnt(0)
	s_waitcnt vmcnt(0)
	s_add_i32 s66, s4, 2
	s_add_u32 s18, s0, 0x80
	s_addc_u32 s5, s1, 0
	s_add_i32 s68, 0, 0x10000
	ds_read_b128 v[142:145], v248
	ds_read_b128 v[146:149], v248 offset:1024
	ds_read_b128 v[156:159], v248 offset:2048
	ds_read_b128 v[160:163], v248 offset:3072
	s_cmp_eq_u32 s43, s4
	s_cselect_b32 s4, s10, s18
	s_cselect_b32 s5, s11, s5
	s_cselect_b32 s19, s13, s65
	s_cselect_b32 s18, s12, s49
	s_add_i32 m0, s28, 0xc000
	ds_read_b128 v[164:167], v154
	ds_read_b128 v[168:171], v154 offset:1024
	ds_read_b128 v[172:175], v154 offset:2048
	ds_read_b128 v[176:179], v154 offset:3072
	ds_read_b128 v[180:183], v154 offset:4096
	ds_read_b128 v[204:207], v154 offset:5120
	ds_read_b128 v[208:211], v154 offset:6144
	ds_read_b128 v[212:215], v154 offset:7168
	global_load_lds_dwordx4 v138, s[0:1]
	s_add_i32 m0, s28, 0xe000
	s_nop 0
	global_load_lds_dwordx4 v140, s[0:1]
	s_waitcnt lgkmcnt(8)
	s_barrier
	s_waitcnt lgkmcnt(0)
	v_mfma_f32_16x16x32_bf16 v[126:129], v[142:145], v[164:167], 0
	v_mfma_f32_16x16x32_bf16 v[122:125], v[156:159], v[164:167], 0
	v_mfma_f32_16x16x32_bf16 v[110:113], v[142:145], v[172:175], 0
	v_mfma_f32_16x16x32_bf16 v[106:109], v[156:159], v[172:175], 0
	v_mfma_f32_16x16x32_bf16 v[94:97], v[142:145], v[180:183], 0
	v_mfma_f32_16x16x32_bf16 v[90:93], v[156:159], v[180:183], 0
	v_mfma_f32_16x16x32_bf16 v[78:81], v[142:145], v[208:211], 0
	v_mfma_f32_16x16x32_bf16 v[74:77], v[156:159], v[208:211], 0
	v_mfma_f32_16x16x32_bf16 v[126:129], v[146:149], v[168:171], v[126:129]
	v_mfma_f32_16x16x32_bf16 v[122:125], v[160:163], v[168:171], v[122:125]
	v_mfma_f32_16x16x32_bf16 v[110:113], v[146:149], v[176:179], v[110:113]
	v_mfma_f32_16x16x32_bf16 v[106:109], v[160:163], v[176:179], v[106:109]
	v_mfma_f32_16x16x32_bf16 v[94:97], v[146:149], v[204:207], v[94:97]
	v_mfma_f32_16x16x32_bf16 v[90:93], v[160:163], v[204:207], v[90:93]
	v_mfma_f32_16x16x32_bf16 v[78:81], v[146:149], v[212:215], v[78:81]
	v_mfma_f32_16x16x32_bf16 v[74:77], v[160:163], v[212:215], v[74:77]
	s_barrier
	s_add_i32 s69, 0, 0x14000
	s_add_i32 s68, s68, s25
	ds_read_b128 v[216:219], v248 offset:16384
	ds_read_b128 v[220:223], v248 offset:17408
	ds_read_b128 v[224:227], v248 offset:18432
	ds_read_b128 v[228:231], v248 offset:19456
	s_add_u32 s70, s18, s6
	s_addc_u32 s71, s19, s7
	s_mov_b32 m0, s68
	s_nop 0
	global_load_lds_dwordx4 v132, s[18:19]
	s_add_i32 m0, s68, 0x2000
	s_nop 0
	global_load_lds_dwordx4 v136, s[18:19]
	s_barrier
	s_waitcnt lgkmcnt(0)
	v_mfma_f32_16x16x32_bf16 v[118:121], v[216:219], v[164:167], 0
	v_mfma_f32_16x16x32_bf16 v[114:117], v[224:227], v[164:167], 0
	v_mfma_f32_16x16x32_bf16 v[102:105], v[216:219], v[172:175], 0
	v_mfma_f32_16x16x32_bf16 v[98:101], v[224:227], v[172:175], 0
	v_mfma_f32_16x16x32_bf16 v[86:89], v[216:219], v[180:183], 0
	v_mfma_f32_16x16x32_bf16 v[82:85], v[224:227], v[180:183], 0
	v_mfma_f32_16x16x32_bf16 v[70:73], v[216:219], v[208:211], 0
	v_mfma_f32_16x16x32_bf16 v[66:69], v[224:227], v[208:211], 0
	v_mfma_f32_16x16x32_bf16 v[118:121], v[220:223], v[168:171], v[118:121]
	v_mfma_f32_16x16x32_bf16 v[114:117], v[228:231], v[168:171], v[114:117]
	v_mfma_f32_16x16x32_bf16 v[102:105], v[220:223], v[176:179], v[102:105]
	v_mfma_f32_16x16x32_bf16 v[98:101], v[228:231], v[176:179], v[98:101]
	v_mfma_f32_16x16x32_bf16 v[86:89], v[220:223], v[204:207], v[86:89]
	v_mfma_f32_16x16x32_bf16 v[82:85], v[228:231], v[204:207], v[82:85]
	v_mfma_f32_16x16x32_bf16 v[70:73], v[220:223], v[212:215], v[70:73]
	v_mfma_f32_16x16x32_bf16 v[66:69], v[228:231], v[212:215], v[66:69]
	s_barrier
	s_mov_b32 m0, s28
	s_add_u32 s72, s4, s6
	s_addc_u32 s73, s5, s7
	ds_read_b128 v[164:167], v154 offset:16384
	ds_read_b128 v[168:171], v154 offset:17408
	ds_read_b128 v[172:175], v154 offset:18432
	ds_read_b128 v[176:179], v154 offset:19456
	ds_read_b128 v[180:183], v154 offset:20480
	ds_read_b128 v[204:207], v154 offset:21504
	ds_read_b128 v[208:211], v154 offset:22528
	ds_read_b128 v[212:215], v154 offset:23552
	global_load_lds_dwordx4 v130, s[4:5]
	s_mov_b32 m0, s29
	s_nop 0
	global_load_lds_dwordx4 v134, s[4:5]
	s_barrier
	s_waitcnt lgkmcnt(0)
	v_mfma_f32_16x16x32_bf16 v[62:65], v[142:145], v[164:167], 0
	v_mfma_f32_16x16x32_bf16 v[58:61], v[156:159], v[164:167], 0
	v_mfma_f32_16x16x32_bf16 v[46:49], v[142:145], v[172:175], 0
	v_mfma_f32_16x16x32_bf16 v[42:45], v[156:159], v[172:175], 0
	v_mfma_f32_16x16x32_bf16 v[30:33], v[142:145], v[180:183], 0
	v_mfma_f32_16x16x32_bf16 v[26:29], v[156:159], v[180:183], 0
	v_mfma_f32_16x16x32_bf16 v[14:17], v[142:145], v[208:211], 0
	v_mfma_f32_16x16x32_bf16 v[10:13], v[156:159], v[208:211], 0
	v_mfma_f32_16x16x32_bf16 v[62:65], v[146:149], v[168:171], v[62:65]
	v_mfma_f32_16x16x32_bf16 v[58:61], v[160:163], v[168:171], v[58:61]
	v_mfma_f32_16x16x32_bf16 v[46:49], v[146:149], v[176:179], v[46:49]
	v_mfma_f32_16x16x32_bf16 v[42:45], v[160:163], v[176:179], v[42:45]
	v_mfma_f32_16x16x32_bf16 v[30:33], v[146:149], v[204:207], v[30:33]
	v_mfma_f32_16x16x32_bf16 v[26:29], v[160:163], v[204:207], v[26:29]
	v_mfma_f32_16x16x32_bf16 v[14:17], v[146:149], v[212:215], v[14:17]
	v_mfma_f32_16x16x32_bf16 v[10:13], v[160:163], v[212:215], v[10:13]
	s_barrier
	s_add_u32 s18, s18, s14
	s_addc_u32 s19, s19, 0
	s_add_i32 s68, s69, s25
	s_add_u32 s76, s18, s6
	s_addc_u32 s77, s19, s7
	s_mov_b32 m0, s68
	s_nop 0
	global_load_lds_dwordx4 v132, s[18:19]
	s_add_i32 m0, s68, 0x2000
	s_nop 0
	global_load_lds_dwordx4 v136, s[18:19]
	s_waitcnt vmcnt(6)
	s_barrier
	v_mfma_f32_16x16x32_bf16 v[54:57], v[216:219], v[164:167], 0
	v_mfma_f32_16x16x32_bf16 v[50:53], v[224:227], v[164:167], 0
	v_mfma_f32_16x16x32_bf16 v[38:41], v[216:219], v[172:175], 0
	v_mfma_f32_16x16x32_bf16 v[34:37], v[224:227], v[172:175], 0
	v_mfma_f32_16x16x32_bf16 v[22:25], v[216:219], v[180:183], 0
	v_mfma_f32_16x16x32_bf16 v[18:21], v[224:227], v[180:183], 0
	v_mfma_f32_16x16x32_bf16 v[6:9], v[216:219], v[208:211], 0
	v_mfma_f32_16x16x32_bf16 v[2:5], v[224:227], v[208:211], 0
	v_mfma_f32_16x16x32_bf16 v[54:57], v[220:223], v[168:171], v[54:57]
	v_mfma_f32_16x16x32_bf16 v[50:53], v[228:231], v[168:171], v[50:53]
	v_mfma_f32_16x16x32_bf16 v[38:41], v[220:223], v[176:179], v[38:41]
	v_mfma_f32_16x16x32_bf16 v[34:37], v[228:231], v[176:179], v[34:37]
	v_mfma_f32_16x16x32_bf16 v[22:25], v[220:223], v[204:207], v[22:25]
	v_mfma_f32_16x16x32_bf16 v[18:21], v[228:231], v[204:207], v[18:21]
	v_mfma_f32_16x16x32_bf16 v[6:9], v[220:223], v[212:215], v[6:9]
	v_mfma_f32_16x16x32_bf16 v[2:5], v[228:231], v[212:215], v[2:5]
	s_barrier
	s_add_i32 s18, 0, 0x18000
	ds_read_b128 v[142:145], v248 offset:32768
	ds_read_b128 v[146:149], v248 offset:33792
	ds_read_b128 v[156:159], v248 offset:34816
	ds_read_b128 v[160:163], v248 offset:35840
	s_add_u32 s4, s4, s14
	s_addc_u32 s5, s5, 0
	s_mov_b32 m0, s31
	ds_read_b128 v[164:167], v154 offset:32768
	ds_read_b128 v[168:171], v154 offset:33792
	ds_read_b128 v[172:175], v154 offset:34816
	ds_read_b128 v[176:179], v154 offset:35840
	ds_read_b128 v[180:183], v154 offset:36864
	ds_read_b128 v[204:207], v154 offset:37888
	ds_read_b128 v[208:211], v154 offset:38912
	ds_read_b128 v[212:215], v154 offset:39936
	global_load_lds_dwordx4 v130, s[4:5]
	s_mov_b32 m0, s34
	s_nop 0
	global_load_lds_dwordx4 v134, s[4:5]
	s_waitcnt lgkmcnt(8)
	s_barrier
	s_waitcnt lgkmcnt(0)
	v_mfma_f32_16x16x32_bf16 v[126:129], v[142:145], v[164:167], v[126:129]
	v_mfma_f32_16x16x32_bf16 v[122:125], v[156:159], v[164:167], v[122:125]
	v_mfma_f32_16x16x32_bf16 v[110:113], v[142:145], v[172:175], v[110:113]
	v_mfma_f32_16x16x32_bf16 v[106:109], v[156:159], v[172:175], v[106:109]
	v_mfma_f32_16x16x32_bf16 v[94:97], v[142:145], v[180:183], v[94:97]
	v_mfma_f32_16x16x32_bf16 v[90:93], v[156:159], v[180:183], v[90:93]
	v_mfma_f32_16x16x32_bf16 v[78:81], v[142:145], v[208:211], v[78:81]
	v_mfma_f32_16x16x32_bf16 v[74:77], v[156:159], v[208:211], v[74:77]
	v_mfma_f32_16x16x32_bf16 v[126:129], v[146:149], v[168:171], v[126:129]
	v_mfma_f32_16x16x32_bf16 v[122:125], v[160:163], v[168:171], v[122:125]
	v_mfma_f32_16x16x32_bf16 v[110:113], v[146:149], v[176:179], v[110:113]
	v_mfma_f32_16x16x32_bf16 v[106:109], v[160:163], v[176:179], v[106:109]
	v_mfma_f32_16x16x32_bf16 v[94:97], v[146:149], v[204:207], v[94:97]
	v_mfma_f32_16x16x32_bf16 v[90:93], v[160:163], v[204:207], v[90:93]
	v_mfma_f32_16x16x32_bf16 v[78:81], v[146:149], v[212:215], v[78:81]
	v_mfma_f32_16x16x32_bf16 v[74:77], v[160:163], v[212:215], v[74:77]
	s_barrier
	s_add_i32 s4, 0, 0x1c000
	s_add_i32 s5, s18, s25
	s_mov_b32 m0, s5
	ds_read_b128 v[216:219], v248 offset:49152
	ds_read_b128 v[220:223], v248 offset:50176
	ds_read_b128 v[224:227], v248 offset:51200
	ds_read_b128 v[228:231], v248 offset:52224
	global_load_lds_dwordx4 v132, s[70:71]
	s_add_i32 m0, s5, 0x2000
	s_nop 0
	global_load_lds_dwordx4 v136, s[70:71]
	s_barrier
	s_waitcnt lgkmcnt(0)
	v_mfma_f32_16x16x32_bf16 v[118:121], v[216:219], v[164:167], v[118:121]
	v_mfma_f32_16x16x32_bf16 v[114:117], v[224:227], v[164:167], v[114:117]
	v_mfma_f32_16x16x32_bf16 v[102:105], v[216:219], v[172:175], v[102:105]
	v_mfma_f32_16x16x32_bf16 v[98:101], v[224:227], v[172:175], v[98:101]
	v_mfma_f32_16x16x32_bf16 v[86:89], v[216:219], v[180:183], v[86:89]
	v_mfma_f32_16x16x32_bf16 v[82:85], v[224:227], v[180:183], v[82:85]
	v_mfma_f32_16x16x32_bf16 v[70:73], v[216:219], v[208:211], v[70:73]
	v_mfma_f32_16x16x32_bf16 v[66:69], v[224:227], v[208:211], v[66:69]
	v_mfma_f32_16x16x32_bf16 v[118:121], v[220:223], v[168:171], v[118:121]
	v_mfma_f32_16x16x32_bf16 v[114:117], v[228:231], v[168:171], v[114:117]
	v_mfma_f32_16x16x32_bf16 v[102:105], v[220:223], v[176:179], v[102:105]
	v_mfma_f32_16x16x32_bf16 v[98:101], v[228:231], v[176:179], v[98:101]
	v_mfma_f32_16x16x32_bf16 v[86:89], v[220:223], v[204:207], v[86:89]
	v_mfma_f32_16x16x32_bf16 v[82:85], v[228:231], v[204:207], v[82:85]
	v_mfma_f32_16x16x32_bf16 v[70:73], v[220:223], v[212:215], v[70:73]
	v_mfma_f32_16x16x32_bf16 v[66:69], v[228:231], v[212:215], v[66:69]
	s_barrier
	s_mov_b32 m0, s41
	ds_read_b128 v[164:167], v154 offset:49152
	ds_read_b128 v[168:171], v154 offset:50176
	ds_read_b128 v[172:175], v154 offset:51200
	ds_read_b128 v[176:179], v154 offset:52224
	ds_read_b128 v[180:183], v154 offset:53248
	ds_read_b128 v[204:207], v154 offset:54272
	ds_read_b128 v[208:211], v154 offset:55296
	ds_read_b128 v[212:215], v154 offset:56320
	global_load_lds_dwordx4 v130, s[72:73]
	s_mov_b32 m0, s42
	s_nop 0
	global_load_lds_dwordx4 v134, s[72:73]
	s_barrier
	s_waitcnt lgkmcnt(0)
	v_mfma_f32_16x16x32_bf16 v[62:65], v[142:145], v[164:167], v[62:65]
	v_mfma_f32_16x16x32_bf16 v[58:61], v[156:159], v[164:167], v[58:61]
	v_mfma_f32_16x16x32_bf16 v[46:49], v[142:145], v[172:175], v[46:49]
	v_mfma_f32_16x16x32_bf16 v[42:45], v[156:159], v[172:175], v[42:45]
	v_mfma_f32_16x16x32_bf16 v[30:33], v[142:145], v[180:183], v[30:33]
	v_mfma_f32_16x16x32_bf16 v[26:29], v[156:159], v[180:183], v[26:29]
	v_mfma_f32_16x16x32_bf16 v[14:17], v[142:145], v[208:211], v[14:17]
	v_mfma_f32_16x16x32_bf16 v[10:13], v[156:159], v[208:211], v[10:13]
	v_mfma_f32_16x16x32_bf16 v[62:65], v[146:149], v[168:171], v[62:65]
	v_mfma_f32_16x16x32_bf16 v[58:61], v[160:163], v[168:171], v[58:61]
	v_mfma_f32_16x16x32_bf16 v[46:49], v[146:149], v[176:179], v[46:49]
	v_mfma_f32_16x16x32_bf16 v[42:45], v[160:163], v[176:179], v[42:45]
	v_mfma_f32_16x16x32_bf16 v[30:33], v[146:149], v[204:207], v[30:33]
	v_mfma_f32_16x16x32_bf16 v[26:29], v[160:163], v[204:207], v[26:29]
	v_mfma_f32_16x16x32_bf16 v[14:17], v[146:149], v[212:215], v[14:17]
	v_mfma_f32_16x16x32_bf16 v[10:13], v[160:163], v[212:215], v[10:13]
	s_barrier
	s_add_i32 s4, s4, s25
	s_mov_b32 m0, s4
	s_nop 0
	global_load_lds_dwordx4 v132, s[76:77]
	s_add_i32 m0, s4, 0x2000
	s_nop 0
	global_load_lds_dwordx4 v136, s[76:77]
	s_add_u32 s0, s0, 0x100
	s_addc_u32 s1, s1, 0
	s_add_u32 s49, s49, 0x100
	s_addc_u32 s65, s65, 0
	s_cmp_ge_u32 s66, s35
	s_mov_b32 s4, s66
	s_waitcnt vmcnt(6)
	s_barrier
	v_mfma_f32_16x16x32_bf16 v[54:57], v[216:219], v[164:167], v[54:57]
	v_mfma_f32_16x16x32_bf16 v[50:53], v[224:227], v[164:167], v[50:53]
	v_mfma_f32_16x16x32_bf16 v[38:41], v[216:219], v[172:175], v[38:41]
	v_mfma_f32_16x16x32_bf16 v[34:37], v[224:227], v[172:175], v[34:37]
	v_mfma_f32_16x16x32_bf16 v[22:25], v[216:219], v[180:183], v[22:25]
	v_mfma_f32_16x16x32_bf16 v[18:21], v[224:227], v[180:183], v[18:21]
	v_mfma_f32_16x16x32_bf16 v[6:9], v[216:219], v[208:211], v[6:9]
	v_mfma_f32_16x16x32_bf16 v[2:5], v[224:227], v[208:211], v[2:5]
	v_mfma_f32_16x16x32_bf16 v[54:57], v[220:223], v[168:171], v[54:57]
	v_mfma_f32_16x16x32_bf16 v[50:53], v[228:231], v[168:171], v[50:53]
	v_mfma_f32_16x16x32_bf16 v[38:41], v[220:223], v[176:179], v[38:41]
	v_mfma_f32_16x16x32_bf16 v[34:37], v[228:231], v[176:179], v[34:37]
	v_mfma_f32_16x16x32_bf16 v[22:25], v[220:223], v[204:207], v[22:25]
	v_mfma_f32_16x16x32_bf16 v[18:21], v[228:231], v[204:207], v[18:21]
	v_mfma_f32_16x16x32_bf16 v[6:9], v[220:223], v[212:215], v[6:9]
	v_mfma_f32_16x16x32_bf16 v[2:5], v[228:231], v[212:215], v[2:5]
	s_barrier
	s_cbranch_scc1 .Lkexit_664
.LBB0_664:
	s_add_i32 s66, s4, 2
	s_add_u32 s18, s0, 0x80
	s_addc_u32 s5, s1, 0
	s_add_i32 s68, 0, 0x10000
	ds_read_b128 v[142:145], v248
	ds_read_b128 v[146:149], v248 offset:1024
	ds_read_b128 v[156:159], v248 offset:2048
	ds_read_b128 v[160:163], v248 offset:3072
	s_cmp_eq_u32 s43, s4
	s_cselect_b32 s4, s10, s18
	s_cselect_b32 s5, s11, s5
	s_cselect_b32 s19, s13, s65
	s_cselect_b32 s18, s12, s49
	s_add_i32 m0, s28, 0xc000
	ds_read_b128 v[164:167], v154
	ds_read_b128 v[168:171], v154 offset:1024
	ds_read_b128 v[172:175], v154 offset:2048
	ds_read_b128 v[176:179], v154 offset:3072
	ds_read_b128 v[180:183], v154 offset:4096
	ds_read_b128 v[204:207], v154 offset:5120
	ds_read_b128 v[208:211], v154 offset:6144
	ds_read_b128 v[212:215], v154 offset:7168
	global_load_lds_dwordx4 v138, s[0:1]
	s_add_i32 m0, s28, 0xe000
	s_nop 0
	global_load_lds_dwordx4 v140, s[0:1]
	s_waitcnt lgkmcnt(8)
	s_barrier
	s_waitcnt lgkmcnt(0)
	v_mfma_f32_16x16x32_bf16 v[126:129], v[142:145], v[164:167], v[126:129]
	v_mfma_f32_16x16x32_bf16 v[122:125], v[156:159], v[164:167], v[122:125]
	v_mfma_f32_16x16x32_bf16 v[110:113], v[142:145], v[172:175], v[110:113]
	v_mfma_f32_16x16x32_bf16 v[106:109], v[156:159], v[172:175], v[106:109]
	v_mfma_f32_16x16x32_bf16 v[94:97], v[142:145], v[180:183], v[94:97]
	v_mfma_f32_16x16x32_bf16 v[90:93], v[156:159], v[180:183], v[90:93]
	v_mfma_f32_16x16x32_bf16 v[78:81], v[142:145], v[208:211], v[78:81]
	v_mfma_f32_16x16x32_bf16 v[74:77], v[156:159], v[208:211], v[74:77]
	v_mfma_f32_16x16x32_bf16 v[126:129], v[146:149], v[168:171], v[126:129]
	v_mfma_f32_16x16x32_bf16 v[122:125], v[160:163], v[168:171], v[122:125]
	v_mfma_f32_16x16x32_bf16 v[110:113], v[146:149], v[176:179], v[110:113]
	v_mfma_f32_16x16x32_bf16 v[106:109], v[160:163], v[176:179], v[106:109]
	v_mfma_f32_16x16x32_bf16 v[94:97], v[146:149], v[204:207], v[94:97]
	v_mfma_f32_16x16x32_bf16 v[90:93], v[160:163], v[204:207], v[90:93]
	v_mfma_f32_16x16x32_bf16 v[78:81], v[146:149], v[212:215], v[78:81]
	v_mfma_f32_16x16x32_bf16 v[74:77], v[160:163], v[212:215], v[74:77]
	s_barrier
	s_add_i32 s69, 0, 0x14000
	s_add_i32 s68, s68, s25
	ds_read_b128 v[216:219], v248 offset:16384
	ds_read_b128 v[220:223], v248 offset:17408
	ds_read_b128 v[224:227], v248 offset:18432
	ds_read_b128 v[228:231], v248 offset:19456
	s_add_u32 s70, s18, s6
	s_addc_u32 s71, s19, s7
	s_mov_b32 m0, s68
	s_nop 0
	global_load_lds_dwordx4 v132, s[18:19]
	s_add_i32 m0, s68, 0x2000
	s_nop 0
	global_load_lds_dwordx4 v136, s[18:19]
	s_barrier
	s_waitcnt lgkmcnt(0)
	v_mfma_f32_16x16x32_bf16 v[118:121], v[216:219], v[164:167], v[118:121]
	v_mfma_f32_16x16x32_bf16 v[114:117], v[224:227], v[164:167], v[114:117]
	v_mfma_f32_16x16x32_bf16 v[102:105], v[216:219], v[172:175], v[102:105]
	v_mfma_f32_16x16x32_bf16 v[98:101], v[224:227], v[172:175], v[98:101]
	v_mfma_f32_16x16x32_bf16 v[86:89], v[216:219], v[180:183], v[86:89]
	v_mfma_f32_16x16x32_bf16 v[82:85], v[224:227], v[180:183], v[82:85]
	v_mfma_f32_16x16x32_bf16 v[70:73], v[216:219], v[208:211], v[70:73]
	v_mfma_f32_16x16x32_bf16 v[66:69], v[224:227], v[208:211], v[66:69]
	v_mfma_f32_16x16x32_bf16 v[118:121], v[220:223], v[168:171], v[118:121]
	v_mfma_f32_16x16x32_bf16 v[114:117], v[228:231], v[168:171], v[114:117]
	v_mfma_f32_16x16x32_bf16 v[102:105], v[220:223], v[176:179], v[102:105]
	v_mfma_f32_16x16x32_bf16 v[98:101], v[228:231], v[176:179], v[98:101]
	v_mfma_f32_16x16x32_bf16 v[86:89], v[220:223], v[204:207], v[86:89]
	v_mfma_f32_16x16x32_bf16 v[82:85], v[228:231], v[204:207], v[82:85]
	v_mfma_f32_16x16x32_bf16 v[70:73], v[220:223], v[212:215], v[70:73]
	v_mfma_f32_16x16x32_bf16 v[66:69], v[228:231], v[212:215], v[66:69]
	s_barrier
	s_mov_b32 m0, s28
	s_add_u32 s72, s4, s6
	s_addc_u32 s73, s5, s7
	ds_read_b128 v[164:167], v154 offset:16384
	ds_read_b128 v[168:171], v154 offset:17408
	ds_read_b128 v[172:175], v154 offset:18432
	ds_read_b128 v[176:179], v154 offset:19456
	ds_read_b128 v[180:183], v154 offset:20480
	ds_read_b128 v[204:207], v154 offset:21504
	ds_read_b128 v[208:211], v154 offset:22528
	ds_read_b128 v[212:215], v154 offset:23552
	global_load_lds_dwordx4 v130, s[4:5]
	s_mov_b32 m0, s29
	s_nop 0
	global_load_lds_dwordx4 v134, s[4:5]
	s_barrier
	s_waitcnt lgkmcnt(0)
	v_mfma_f32_16x16x32_bf16 v[62:65], v[142:145], v[164:167], v[62:65]
	v_mfma_f32_16x16x32_bf16 v[58:61], v[156:159], v[164:167], v[58:61]
	v_mfma_f32_16x16x32_bf16 v[46:49], v[142:145], v[172:175], v[46:49]
	v_mfma_f32_16x16x32_bf16 v[42:45], v[156:159], v[172:175], v[42:45]
	v_mfma_f32_16x16x32_bf16 v[30:33], v[142:145], v[180:183], v[30:33]
	v_mfma_f32_16x16x32_bf16 v[26:29], v[156:159], v[180:183], v[26:29]
	v_mfma_f32_16x16x32_bf16 v[14:17], v[142:145], v[208:211], v[14:17]
	v_mfma_f32_16x16x32_bf16 v[10:13], v[156:159], v[208:211], v[10:13]
	v_mfma_f32_16x16x32_bf16 v[62:65], v[146:149], v[168:171], v[62:65]
	v_mfma_f32_16x16x32_bf16 v[58:61], v[160:163], v[168:171], v[58:61]
	v_mfma_f32_16x16x32_bf16 v[46:49], v[146:149], v[176:179], v[46:49]
	v_mfma_f32_16x16x32_bf16 v[42:45], v[160:163], v[176:179], v[42:45]
	v_mfma_f32_16x16x32_bf16 v[30:33], v[146:149], v[204:207], v[30:33]
	v_mfma_f32_16x16x32_bf16 v[26:29], v[160:163], v[204:207], v[26:29]
	v_mfma_f32_16x16x32_bf16 v[14:17], v[146:149], v[212:215], v[14:17]
	v_mfma_f32_16x16x32_bf16 v[10:13], v[160:163], v[212:215], v[10:13]
	s_barrier
	s_add_u32 s18, s18, s14
	s_addc_u32 s19, s19, 0
	s_add_i32 s68, s69, s25
	s_add_u32 s76, s18, s6
	s_addc_u32 s77, s19, s7
	s_mov_b32 m0, s68
	s_nop 0
	global_load_lds_dwordx4 v132, s[18:19]
	s_add_i32 m0, s68, 0x2000
	s_nop 0
	global_load_lds_dwordx4 v136, s[18:19]
	s_waitcnt vmcnt(6)
	s_barrier
	v_mfma_f32_16x16x32_bf16 v[54:57], v[216:219], v[164:167], v[54:57]
	v_mfma_f32_16x16x32_bf16 v[50:53], v[224:227], v[164:167], v[50:53]
	v_mfma_f32_16x16x32_bf16 v[38:41], v[216:219], v[172:175], v[38:41]
	v_mfma_f32_16x16x32_bf16 v[34:37], v[224:227], v[172:175], v[34:37]
	v_mfma_f32_16x16x32_bf16 v[22:25], v[216:219], v[180:183], v[22:25]
	v_mfma_f32_16x16x32_bf16 v[18:21], v[224:227], v[180:183], v[18:21]
	v_mfma_f32_16x16x32_bf16 v[6:9], v[216:219], v[208:211], v[6:9]
	v_mfma_f32_16x16x32_bf16 v[2:5], v[224:227], v[208:211], v[2:5]
	v_mfma_f32_16x16x32_bf16 v[54:57], v[220:223], v[168:171], v[54:57]
	v_mfma_f32_16x16x32_bf16 v[50:53], v[228:231], v[168:171], v[50:53]
	v_mfma_f32_16x16x32_bf16 v[38:41], v[220:223], v[176:179], v[38:41]
	v_mfma_f32_16x16x32_bf16 v[34:37], v[228:231], v[176:179], v[34:37]
	v_mfma_f32_16x16x32_bf16 v[22:25], v[220:223], v[204:207], v[22:25]
	v_mfma_f32_16x16x32_bf16 v[18:21], v[228:231], v[204:207], v[18:21]
	v_mfma_f32_16x16x32_bf16 v[6:9], v[220:223], v[212:215], v[6:9]
	v_mfma_f32_16x16x32_bf16 v[2:5], v[228:231], v[212:215], v[2:5]
	s_barrier
	s_add_i32 s18, 0, 0x18000
	ds_read_b128 v[142:145], v248 offset:32768
	ds_read_b128 v[146:149], v248 offset:33792
	ds_read_b128 v[156:159], v248 offset:34816
	ds_read_b128 v[160:163], v248 offset:35840
	s_add_u32 s4, s4, s14
	s_addc_u32 s5, s5, 0
	s_mov_b32 m0, s31
	ds_read_b128 v[164:167], v154 offset:32768
	ds_read_b128 v[168:171], v154 offset:33792
	ds_read_b128 v[172:175], v154 offset:34816
	ds_read_b128 v[176:179], v154 offset:35840
	ds_read_b128 v[180:183], v154 offset:36864
	ds_read_b128 v[204:207], v154 offset:37888
	ds_read_b128 v[208:211], v154 offset:38912
	ds_read_b128 v[212:215], v154 offset:39936
	global_load_lds_dwordx4 v130, s[4:5]
	s_mov_b32 m0, s34
	s_nop 0
	global_load_lds_dwordx4 v134, s[4:5]
	s_waitcnt lgkmcnt(8)
	s_barrier
	s_waitcnt lgkmcnt(0)
	v_mfma_f32_16x16x32_bf16 v[126:129], v[142:145], v[164:167], v[126:129]
	v_mfma_f32_16x16x32_bf16 v[122:125], v[156:159], v[164:167], v[122:125]
	v_mfma_f32_16x16x32_bf16 v[110:113], v[142:145], v[172:175], v[110:113]
	v_mfma_f32_16x16x32_bf16 v[106:109], v[156:159], v[172:175], v[106:109]
	v_mfma_f32_16x16x32_bf16 v[94:97], v[142:145], v[180:183], v[94:97]
	v_mfma_f32_16x16x32_bf16 v[90:93], v[156:159], v[180:183], v[90:93]
	v_mfma_f32_16x16x32_bf16 v[78:81], v[142:145], v[208:211], v[78:81]
	v_mfma_f32_16x16x32_bf16 v[74:77], v[156:159], v[208:211], v[74:77]
	v_mfma_f32_16x16x32_bf16 v[126:129], v[146:149], v[168:171], v[126:129]
	v_mfma_f32_16x16x32_bf16 v[122:125], v[160:163], v[168:171], v[122:125]
	v_mfma_f32_16x16x32_bf16 v[110:113], v[146:149], v[176:179], v[110:113]
	v_mfma_f32_16x16x32_bf16 v[106:109], v[160:163], v[176:179], v[106:109]
	v_mfma_f32_16x16x32_bf16 v[94:97], v[146:149], v[204:207], v[94:97]
	v_mfma_f32_16x16x32_bf16 v[90:93], v[160:163], v[204:207], v[90:93]
	v_mfma_f32_16x16x32_bf16 v[78:81], v[146:149], v[212:215], v[78:81]
	v_mfma_f32_16x16x32_bf16 v[74:77], v[160:163], v[212:215], v[74:77]
	s_barrier
	s_add_i32 s4, 0, 0x1c000
	s_add_i32 s5, s18, s25
	s_mov_b32 m0, s5
	ds_read_b128 v[216:219], v248 offset:49152
	ds_read_b128 v[220:223], v248 offset:50176
	ds_read_b128 v[224:227], v248 offset:51200
	ds_read_b128 v[228:231], v248 offset:52224
	global_load_lds_dwordx4 v132, s[70:71]
	s_add_i32 m0, s5, 0x2000
	s_nop 0
	global_load_lds_dwordx4 v136, s[70:71]
	s_barrier
	s_waitcnt lgkmcnt(0)
	v_mfma_f32_16x16x32_bf16 v[118:121], v[216:219], v[164:167], v[118:121]
	v_mfma_f32_16x16x32_bf16 v[114:117], v[224:227], v[164:167], v[114:117]
	v_mfma_f32_16x16x32_bf16 v[102:105], v[216:219], v[172:175], v[102:105]
	v_mfma_f32_16x16x32_bf16 v[98:101], v[224:227], v[172:175], v[98:101]
	v_mfma_f32_16x16x32_bf16 v[86:89], v[216:219], v[180:183], v[86:89]
	v_mfma_f32_16x16x32_bf16 v[82:85], v[224:227], v[180:183], v[82:85]
	v_mfma_f32_16x16x32_bf16 v[70:73], v[216:219], v[208:211], v[70:73]
	v_mfma_f32_16x16x32_bf16 v[66:69], v[224:227], v[208:211], v[66:69]
	v_mfma_f32_16x16x32_bf16 v[118:121], v[220:223], v[168:171], v[118:121]
	v_mfma_f32_16x16x32_bf16 v[114:117], v[228:231], v[168:171], v[114:117]
	v_mfma_f32_16x16x32_bf16 v[102:105], v[220:223], v[176:179], v[102:105]
	v_mfma_f32_16x16x32_bf16 v[98:101], v[228:231], v[176:179], v[98:101]
	v_mfma_f32_16x16x32_bf16 v[86:89], v[220:223], v[204:207], v[86:89]
	v_mfma_f32_16x16x32_bf16 v[82:85], v[228:231], v[204:207], v[82:85]
	v_mfma_f32_16x16x32_bf16 v[70:73], v[220:223], v[212:215], v[70:73]
	v_mfma_f32_16x16x32_bf16 v[66:69], v[228:231], v[212:215], v[66:69]
	s_barrier
	s_mov_b32 m0, s41
	ds_read_b128 v[164:167], v154 offset:49152
	ds_read_b128 v[168:171], v154 offset:50176
	ds_read_b128 v[172:175], v154 offset:51200
	ds_read_b128 v[176:179], v154 offset:52224
	ds_read_b128 v[180:183], v154 offset:53248
	ds_read_b128 v[204:207], v154 offset:54272
	ds_read_b128 v[208:211], v154 offset:55296
	ds_read_b128 v[212:215], v154 offset:56320
	global_load_lds_dwordx4 v130, s[72:73]
	s_mov_b32 m0, s42
	s_nop 0
	global_load_lds_dwordx4 v134, s[72:73]
	s_barrier
	s_waitcnt lgkmcnt(0)
	v_mfma_f32_16x16x32_bf16 v[62:65], v[142:145], v[164:167], v[62:65]
	v_mfma_f32_16x16x32_bf16 v[58:61], v[156:159], v[164:167], v[58:61]
	v_mfma_f32_16x16x32_bf16 v[46:49], v[142:145], v[172:175], v[46:49]
	v_mfma_f32_16x16x32_bf16 v[42:45], v[156:159], v[172:175], v[42:45]
	v_mfma_f32_16x16x32_bf16 v[30:33], v[142:145], v[180:183], v[30:33]
	v_mfma_f32_16x16x32_bf16 v[26:29], v[156:159], v[180:183], v[26:29]
	v_mfma_f32_16x16x32_bf16 v[14:17], v[142:145], v[208:211], v[14:17]
	v_mfma_f32_16x16x32_bf16 v[10:13], v[156:159], v[208:211], v[10:13]
	v_mfma_f32_16x16x32_bf16 v[62:65], v[146:149], v[168:171], v[62:65]
	v_mfma_f32_16x16x32_bf16 v[58:61], v[160:163], v[168:171], v[58:61]
	v_mfma_f32_16x16x32_bf16 v[46:49], v[146:149], v[176:179], v[46:49]
	v_mfma_f32_16x16x32_bf16 v[42:45], v[160:163], v[176:179], v[42:45]
	v_mfma_f32_16x16x32_bf16 v[30:33], v[146:149], v[204:207], v[30:33]
	v_mfma_f32_16x16x32_bf16 v[26:29], v[160:163], v[204:207], v[26:29]
	v_mfma_f32_16x16x32_bf16 v[14:17], v[146:149], v[212:215], v[14:17]
	v_mfma_f32_16x16x32_bf16 v[10:13], v[160:163], v[212:215], v[10:13]
	s_barrier
	s_add_i32 s4, s4, s25
	s_mov_b32 m0, s4
	s_nop 0
	global_load_lds_dwordx4 v132, s[76:77]
	s_add_i32 m0, s4, 0x2000
	s_nop 0
	global_load_lds_dwordx4 v136, s[76:77]
	s_add_u32 s0, s0, 0x100
	s_addc_u32 s1, s1, 0
	s_add_u32 s49, s49, 0x100
	s_addc_u32 s65, s65, 0
	s_cmp_ge_u32 s66, s35
	s_mov_b32 s4, s66
	s_waitcnt vmcnt(6)
	s_barrier
	v_mfma_f32_16x16x32_bf16 v[54:57], v[216:219], v[164:167], v[54:57]
	v_mfma_f32_16x16x32_bf16 v[50:53], v[224:227], v[164:167], v[50:53]
	v_mfma_f32_16x16x32_bf16 v[38:41], v[216:219], v[172:175], v[38:41]
	v_mfma_f32_16x16x32_bf16 v[34:37], v[224:227], v[172:175], v[34:37]
	v_mfma_f32_16x16x32_bf16 v[22:25], v[216:219], v[180:183], v[22:25]
	v_mfma_f32_16x16x32_bf16 v[18:21], v[224:227], v[180:183], v[18:21]
	v_mfma_f32_16x16x32_bf16 v[6:9], v[216:219], v[208:211], v[6:9]
	v_mfma_f32_16x16x32_bf16 v[2:5], v[224:227], v[208:211], v[2:5]
	v_mfma_f32_16x16x32_bf16 v[54:57], v[220:223], v[168:171], v[54:57]
	v_mfma_f32_16x16x32_bf16 v[50:53], v[228:231], v[168:171], v[50:53]
	v_mfma_f32_16x16x32_bf16 v[38:41], v[220:223], v[176:179], v[38:41]
	v_mfma_f32_16x16x32_bf16 v[34:37], v[228:231], v[176:179], v[34:37]
	v_mfma_f32_16x16x32_bf16 v[22:25], v[220:223], v[204:207], v[22:25]
	v_mfma_f32_16x16x32_bf16 v[18:21], v[228:231], v[204:207], v[18:21]
	v_mfma_f32_16x16x32_bf16 v[6:9], v[220:223], v[212:215], v[6:9]
	v_mfma_f32_16x16x32_bf16 v[2:5], v[228:231], v[212:215], v[2:5]
	s_barrier
	s_cbranch_scc0 .LBB0_664

.LBB0_697:
	s_add_u32 s0, s0, 0x80
	s_addc_u32 s1, s1, 0
	s_add_u32 s48, s4, 0x100
	s_addc_u32 s49, s5, 0
	s_mov_b32 s4, 0
	s_waitcnt lgkmcnt(0)
	s_waitcnt vmcnt(0)
	s_add_i32 s65, s4, 2
	s_add_u32 s18, s0, 0x80
	s_addc_u32 s5, s1, 0
	s_add_i32 s66, 0, 0x10000
	ds_read_b128 v[142:145], v248
	ds_read_b128 v[152:155], v248 offset:1024
	ds_read_b128 v[156:159], v248 offset:2048
	ds_read_b128 v[160:163], v248 offset:3072
	s_cmp_eq_u32 s34, s4
	s_cselect_b32 s4, s10, s18
	s_cselect_b32 s5, s11, s5
	s_cselect_b32 s19, s13, s49
	s_cselect_b32 s18, s12, s48
	s_add_i32 m0, s22, 0xc000
	ds_read_b128 v[164:167], v150
	ds_read_b128 v[168:171], v150 offset:1024
	ds_read_b128 v[172:175], v150 offset:2048
	ds_read_b128 v[176:179], v150 offset:3072
	ds_read_b128 v[180:183], v150 offset:4096
	ds_read_b128 v[204:207], v150 offset:5120
	ds_read_b128 v[208:211], v150 offset:6144
	ds_read_b128 v[212:215], v150 offset:7168
	global_load_lds_dwordx4 v138, s[0:1]
	s_add_i32 m0, s22, 0xe000
	s_nop 0
	global_load_lds_dwordx4 v140, s[0:1]
	s_waitcnt lgkmcnt(8)
	s_barrier
	s_waitcnt lgkmcnt(0)
	v_mfma_f32_16x16x32_bf16 v[126:129], v[142:145], v[164:167], 0
	v_mfma_f32_16x16x32_bf16 v[122:125], v[156:159], v[164:167], 0
	v_mfma_f32_16x16x32_bf16 v[110:113], v[142:145], v[172:175], 0
	v_mfma_f32_16x16x32_bf16 v[106:109], v[156:159], v[172:175], 0
	v_mfma_f32_16x16x32_bf16 v[94:97], v[142:145], v[180:183], 0
	v_mfma_f32_16x16x32_bf16 v[90:93], v[156:159], v[180:183], 0
	v_mfma_f32_16x16x32_bf16 v[78:81], v[142:145], v[208:211], 0
	v_mfma_f32_16x16x32_bf16 v[74:77], v[156:159], v[208:211], 0
	v_mfma_f32_16x16x32_bf16 v[126:129], v[152:155], v[168:171], v[126:129]
	v_mfma_f32_16x16x32_bf16 v[122:125], v[160:163], v[168:171], v[122:125]
	v_mfma_f32_16x16x32_bf16 v[110:113], v[152:155], v[176:179], v[110:113]
	v_mfma_f32_16x16x32_bf16 v[106:109], v[160:163], v[176:179], v[106:109]
	v_mfma_f32_16x16x32_bf16 v[94:97], v[152:155], v[204:207], v[94:97]
	v_mfma_f32_16x16x32_bf16 v[90:93], v[160:163], v[204:207], v[90:93]
	v_mfma_f32_16x16x32_bf16 v[78:81], v[152:155], v[212:215], v[78:81]
	v_mfma_f32_16x16x32_bf16 v[74:77], v[160:163], v[212:215], v[74:77]
	s_barrier
	s_add_i32 s67, 0, 0x14000
	s_add_i32 s66, s66, s21
	ds_read_b128 v[216:219], v248 offset:16384
	ds_read_b128 v[220:223], v248 offset:17408
	ds_read_b128 v[224:227], v248 offset:18432
	ds_read_b128 v[228:231], v248 offset:19456
	s_add_u32 s70, s18, s6
	s_addc_u32 s71, s19, s7
	s_mov_b32 m0, s66
	s_nop 0
	global_load_lds_dwordx4 v132, s[18:19]
	s_add_i32 m0, s66, 0x2000
	s_nop 0
	global_load_lds_dwordx4 v136, s[18:19]
	s_barrier
	s_waitcnt lgkmcnt(0)
	v_mfma_f32_16x16x32_bf16 v[118:121], v[216:219], v[164:167], 0
	v_mfma_f32_16x16x32_bf16 v[114:117], v[224:227], v[164:167], 0
	v_mfma_f32_16x16x32_bf16 v[102:105], v[216:219], v[172:175], 0
	v_mfma_f32_16x16x32_bf16 v[98:101], v[224:227], v[172:175], 0
	v_mfma_f32_16x16x32_bf16 v[86:89], v[216:219], v[180:183], 0
	v_mfma_f32_16x16x32_bf16 v[82:85], v[224:227], v[180:183], 0
	v_mfma_f32_16x16x32_bf16 v[70:73], v[216:219], v[208:211], 0
	v_mfma_f32_16x16x32_bf16 v[66:69], v[224:227], v[208:211], 0
	v_mfma_f32_16x16x32_bf16 v[118:121], v[220:223], v[168:171], v[118:121]
	v_mfma_f32_16x16x32_bf16 v[114:117], v[228:231], v[168:171], v[114:117]
	v_mfma_f32_16x16x32_bf16 v[102:105], v[220:223], v[176:179], v[102:105]
	v_mfma_f32_16x16x32_bf16 v[98:101], v[228:231], v[176:179], v[98:101]
	v_mfma_f32_16x16x32_bf16 v[86:89], v[220:223], v[204:207], v[86:89]
	v_mfma_f32_16x16x32_bf16 v[82:85], v[228:231], v[204:207], v[82:85]
	v_mfma_f32_16x16x32_bf16 v[70:73], v[220:223], v[212:215], v[70:73]
	v_mfma_f32_16x16x32_bf16 v[66:69], v[228:231], v[212:215], v[66:69]
	s_barrier
	s_mov_b32 m0, s22
	s_add_u32 s72, s4, s6
	s_addc_u32 s73, s5, s7
	ds_read_b128 v[164:167], v150 offset:16384
	ds_read_b128 v[168:171], v150 offset:17408
	ds_read_b128 v[172:175], v150 offset:18432
	ds_read_b128 v[176:179], v150 offset:19456
	ds_read_b128 v[180:183], v150 offset:20480
	ds_read_b128 v[204:207], v150 offset:21504
	ds_read_b128 v[208:211], v150 offset:22528
	ds_read_b128 v[212:215], v150 offset:23552
	global_load_lds_dwordx4 v130, s[4:5]
	s_mov_b32 m0, s23
	s_nop 0
	global_load_lds_dwordx4 v134, s[4:5]
	s_barrier
	s_waitcnt lgkmcnt(0)
	v_mfma_f32_16x16x32_bf16 v[62:65], v[142:145], v[164:167], 0
	v_mfma_f32_16x16x32_bf16 v[58:61], v[156:159], v[164:167], 0
	v_mfma_f32_16x16x32_bf16 v[46:49], v[142:145], v[172:175], 0
	v_mfma_f32_16x16x32_bf16 v[42:45], v[156:159], v[172:175], 0
	v_mfma_f32_16x16x32_bf16 v[30:33], v[142:145], v[180:183], 0
	v_mfma_f32_16x16x32_bf16 v[26:29], v[156:159], v[180:183], 0
	v_mfma_f32_16x16x32_bf16 v[14:17], v[142:145], v[208:211], 0
	v_mfma_f32_16x16x32_bf16 v[10:13], v[156:159], v[208:211], 0
	v_mfma_f32_16x16x32_bf16 v[62:65], v[152:155], v[168:171], v[62:65]
	v_mfma_f32_16x16x32_bf16 v[58:61], v[160:163], v[168:171], v[58:61]
	v_mfma_f32_16x16x32_bf16 v[46:49], v[152:155], v[176:179], v[46:49]
	v_mfma_f32_16x16x32_bf16 v[42:45], v[160:163], v[176:179], v[42:45]
	v_mfma_f32_16x16x32_bf16 v[30:33], v[152:155], v[204:207], v[30:33]
	v_mfma_f32_16x16x32_bf16 v[26:29], v[160:163], v[204:207], v[26:29]
	v_mfma_f32_16x16x32_bf16 v[14:17], v[152:155], v[212:215], v[14:17]
	v_mfma_f32_16x16x32_bf16 v[10:13], v[160:163], v[212:215], v[10:13]
	s_barrier
	s_add_u32 s18, s18, s2
	s_addc_u32 s19, s19, 0
	s_add_i32 s66, s67, s21
	s_add_u32 s76, s18, s6
	s_addc_u32 s77, s19, s7
	s_mov_b32 m0, s66
	s_nop 0
	global_load_lds_dwordx4 v132, s[18:19]
	s_add_i32 m0, s66, 0x2000
	s_nop 0
	global_load_lds_dwordx4 v136, s[18:19]
	s_waitcnt vmcnt(6)
	s_barrier
	v_mfma_f32_16x16x32_bf16 v[54:57], v[216:219], v[164:167], 0
	v_mfma_f32_16x16x32_bf16 v[50:53], v[224:227], v[164:167], 0
	v_mfma_f32_16x16x32_bf16 v[38:41], v[216:219], v[172:175], 0
	v_mfma_f32_16x16x32_bf16 v[34:37], v[224:227], v[172:175], 0
	v_mfma_f32_16x16x32_bf16 v[22:25], v[216:219], v[180:183], 0
	v_mfma_f32_16x16x32_bf16 v[18:21], v[224:227], v[180:183], 0
	v_mfma_f32_16x16x32_bf16 v[6:9], v[216:219], v[208:211], 0
	v_mfma_f32_16x16x32_bf16 v[2:5], v[224:227], v[208:211], 0
	v_mfma_f32_16x16x32_bf16 v[54:57], v[220:223], v[168:171], v[54:57]
	v_mfma_f32_16x16x32_bf16 v[50:53], v[228:231], v[168:171], v[50:53]
	v_mfma_f32_16x16x32_bf16 v[38:41], v[220:223], v[176:179], v[38:41]
	v_mfma_f32_16x16x32_bf16 v[34:37], v[228:231], v[176:179], v[34:37]
	v_mfma_f32_16x16x32_bf16 v[22:25], v[220:223], v[204:207], v[22:25]
	v_mfma_f32_16x16x32_bf16 v[18:21], v[228:231], v[204:207], v[18:21]
	v_mfma_f32_16x16x32_bf16 v[6:9], v[220:223], v[212:215], v[6:9]
	v_mfma_f32_16x16x32_bf16 v[2:5], v[228:231], v[212:215], v[2:5]
	s_barrier
	s_add_i32 s18, 0, 0x18000
	ds_read_b128 v[142:145], v248 offset:32768
	ds_read_b128 v[152:155], v248 offset:33792
	ds_read_b128 v[156:159], v248 offset:34816
	ds_read_b128 v[160:163], v248 offset:35840
	s_add_u32 s4, s4, s2
	s_addc_u32 s5, s5, 0
	s_mov_b32 m0, s24
	ds_read_b128 v[164:167], v150 offset:32768
	ds_read_b128 v[168:171], v150 offset:33792
	ds_read_b128 v[172:175], v150 offset:34816
	ds_read_b128 v[176:179], v150 offset:35840
	ds_read_b128 v[180:183], v150 offset:36864
	ds_read_b128 v[204:207], v150 offset:37888
	ds_read_b128 v[208:211], v150 offset:38912
	ds_read_b128 v[212:215], v150 offset:39936
	global_load_lds_dwordx4 v130, s[4:5]
	s_mov_b32 m0, s25
	s_nop 0
	global_load_lds_dwordx4 v134, s[4:5]
	s_waitcnt lgkmcnt(8)
	s_barrier
	s_waitcnt lgkmcnt(0)
	v_mfma_f32_16x16x32_bf16 v[126:129], v[142:145], v[164:167], v[126:129]
	v_mfma_f32_16x16x32_bf16 v[122:125], v[156:159], v[164:167], v[122:125]
	v_mfma_f32_16x16x32_bf16 v[110:113], v[142:145], v[172:175], v[110:113]
	v_mfma_f32_16x16x32_bf16 v[106:109], v[156:159], v[172:175], v[106:109]
	v_mfma_f32_16x16x32_bf16 v[94:97], v[142:145], v[180:183], v[94:97]
	v_mfma_f32_16x16x32_bf16 v[90:93], v[156:159], v[180:183], v[90:93]
	v_mfma_f32_16x16x32_bf16 v[78:81], v[142:145], v[208:211], v[78:81]
	v_mfma_f32_16x16x32_bf16 v[74:77], v[156:159], v[208:211], v[74:77]
	v_mfma_f32_16x16x32_bf16 v[126:129], v[152:155], v[168:171], v[126:129]
	v_mfma_f32_16x16x32_bf16 v[122:125], v[160:163], v[168:171], v[122:125]
	v_mfma_f32_16x16x32_bf16 v[110:113], v[152:155], v[176:179], v[110:113]
	v_mfma_f32_16x16x32_bf16 v[106:109], v[160:163], v[176:179], v[106:109]
	v_mfma_f32_16x16x32_bf16 v[94:97], v[152:155], v[204:207], v[94:97]
	v_mfma_f32_16x16x32_bf16 v[90:93], v[160:163], v[204:207], v[90:93]
	v_mfma_f32_16x16x32_bf16 v[78:81], v[152:155], v[212:215], v[78:81]
	v_mfma_f32_16x16x32_bf16 v[74:77], v[160:163], v[212:215], v[74:77]
	s_barrier
	s_add_i32 s4, 0, 0x1c000
	s_add_i32 s5, s18, s21
	s_mov_b32 m0, s5
	ds_read_b128 v[216:219], v248 offset:49152
	ds_read_b128 v[220:223], v248 offset:50176
	ds_read_b128 v[224:227], v248 offset:51200
	ds_read_b128 v[228:231], v248 offset:52224
	global_load_lds_dwordx4 v132, s[70:71]
	s_add_i32 m0, s5, 0x2000
	s_nop 0
	global_load_lds_dwordx4 v136, s[70:71]
	s_barrier
	s_waitcnt lgkmcnt(0)
	v_mfma_f32_16x16x32_bf16 v[118:121], v[216:219], v[164:167], v[118:121]
	v_mfma_f32_16x16x32_bf16 v[114:117], v[224:227], v[164:167], v[114:117]
	v_mfma_f32_16x16x32_bf16 v[102:105], v[216:219], v[172:175], v[102:105]
	v_mfma_f32_16x16x32_bf16 v[98:101], v[224:227], v[172:175], v[98:101]
	v_mfma_f32_16x16x32_bf16 v[86:89], v[216:219], v[180:183], v[86:89]
	v_mfma_f32_16x16x32_bf16 v[82:85], v[224:227], v[180:183], v[82:85]
	v_mfma_f32_16x16x32_bf16 v[70:73], v[216:219], v[208:211], v[70:73]
	v_mfma_f32_16x16x32_bf16 v[66:69], v[224:227], v[208:211], v[66:69]
	v_mfma_f32_16x16x32_bf16 v[118:121], v[220:223], v[168:171], v[118:121]
	v_mfma_f32_16x16x32_bf16 v[114:117], v[228:231], v[168:171], v[114:117]
	v_mfma_f32_16x16x32_bf16 v[102:105], v[220:223], v[176:179], v[102:105]
	v_mfma_f32_16x16x32_bf16 v[98:101], v[228:231], v[176:179], v[98:101]
	v_mfma_f32_16x16x32_bf16 v[86:89], v[220:223], v[204:207], v[86:89]
	v_mfma_f32_16x16x32_bf16 v[82:85], v[228:231], v[204:207], v[82:85]
	v_mfma_f32_16x16x32_bf16 v[70:73], v[220:223], v[212:215], v[70:73]
	v_mfma_f32_16x16x32_bf16 v[66:69], v[228:231], v[212:215], v[66:69]
	s_barrier
	s_mov_b32 m0, s30
	ds_read_b128 v[164:167], v150 offset:49152
	ds_read_b128 v[168:171], v150 offset:50176
	ds_read_b128 v[172:175], v150 offset:51200
	ds_read_b128 v[176:179], v150 offset:52224
	ds_read_b128 v[180:183], v150 offset:53248
	ds_read_b128 v[204:207], v150 offset:54272
	ds_read_b128 v[208:211], v150 offset:55296
	ds_read_b128 v[212:215], v150 offset:56320
	global_load_lds_dwordx4 v130, s[72:73]
	s_mov_b32 m0, s31
	s_nop 0
	global_load_lds_dwordx4 v134, s[72:73]
	s_barrier
	s_waitcnt lgkmcnt(0)
	v_mfma_f32_16x16x32_bf16 v[62:65], v[142:145], v[164:167], v[62:65]
	v_mfma_f32_16x16x32_bf16 v[58:61], v[156:159], v[164:167], v[58:61]
	v_mfma_f32_16x16x32_bf16 v[46:49], v[142:145], v[172:175], v[46:49]
	v_mfma_f32_16x16x32_bf16 v[42:45], v[156:159], v[172:175], v[42:45]
	v_mfma_f32_16x16x32_bf16 v[30:33], v[142:145], v[180:183], v[30:33]
	v_mfma_f32_16x16x32_bf16 v[26:29], v[156:159], v[180:183], v[26:29]
	v_mfma_f32_16x16x32_bf16 v[14:17], v[142:145], v[208:211], v[14:17]
	v_mfma_f32_16x16x32_bf16 v[10:13], v[156:159], v[208:211], v[10:13]
	v_mfma_f32_16x16x32_bf16 v[62:65], v[152:155], v[168:171], v[62:65]
	v_mfma_f32_16x16x32_bf16 v[58:61], v[160:163], v[168:171], v[58:61]
	v_mfma_f32_16x16x32_bf16 v[46:49], v[152:155], v[176:179], v[46:49]
	v_mfma_f32_16x16x32_bf16 v[42:45], v[160:163], v[176:179], v[42:45]
	v_mfma_f32_16x16x32_bf16 v[30:33], v[152:155], v[204:207], v[30:33]
	v_mfma_f32_16x16x32_bf16 v[26:29], v[160:163], v[204:207], v[26:29]
	v_mfma_f32_16x16x32_bf16 v[14:17], v[152:155], v[212:215], v[14:17]
	v_mfma_f32_16x16x32_bf16 v[10:13], v[160:163], v[212:215], v[10:13]
	s_barrier
	s_add_i32 s4, s4, s21
	s_mov_b32 m0, s4
	s_nop 0
	global_load_lds_dwordx4 v132, s[76:77]
	s_add_i32 m0, s4, 0x2000
	s_nop 0
	global_load_lds_dwordx4 v136, s[76:77]
	s_add_u32 s0, s0, 0x100
	s_addc_u32 s1, s1, 0
	s_add_u32 s48, s48, 0x100
	s_addc_u32 s49, s49, 0
	s_cmp_ge_u32 s65, s27
	s_mov_b32 s4, s65
	s_waitcnt vmcnt(6)
	s_barrier
	v_mfma_f32_16x16x32_bf16 v[54:57], v[216:219], v[164:167], v[54:57]
	v_mfma_f32_16x16x32_bf16 v[50:53], v[224:227], v[164:167], v[50:53]
	v_mfma_f32_16x16x32_bf16 v[38:41], v[216:219], v[172:175], v[38:41]
	v_mfma_f32_16x16x32_bf16 v[34:37], v[224:227], v[172:175], v[34:37]
	v_mfma_f32_16x16x32_bf16 v[22:25], v[216:219], v[180:183], v[22:25]
	v_mfma_f32_16x16x32_bf16 v[18:21], v[224:227], v[180:183], v[18:21]
	v_mfma_f32_16x16x32_bf16 v[6:9], v[216:219], v[208:211], v[6:9]
	v_mfma_f32_16x16x32_bf16 v[2:5], v[224:227], v[208:211], v[2:5]
	v_mfma_f32_16x16x32_bf16 v[54:57], v[220:223], v[168:171], v[54:57]
	v_mfma_f32_16x16x32_bf16 v[50:53], v[228:231], v[168:171], v[50:53]
	v_mfma_f32_16x16x32_bf16 v[38:41], v[220:223], v[176:179], v[38:41]
	v_mfma_f32_16x16x32_bf16 v[34:37], v[228:231], v[176:179], v[34:37]
	v_mfma_f32_16x16x32_bf16 v[22:25], v[220:223], v[204:207], v[22:25]
	v_mfma_f32_16x16x32_bf16 v[18:21], v[228:231], v[204:207], v[18:21]
	v_mfma_f32_16x16x32_bf16 v[6:9], v[220:223], v[212:215], v[6:9]
	v_mfma_f32_16x16x32_bf16 v[2:5], v[228:231], v[212:215], v[2:5]
	s_barrier
	s_cbranch_scc1 .Lkexit_698
.LBB0_698:
	s_add_i32 s65, s4, 2
	s_add_u32 s18, s0, 0x80
	s_addc_u32 s5, s1, 0
	s_add_i32 s66, 0, 0x10000
	ds_read_b128 v[142:145], v248
	ds_read_b128 v[152:155], v248 offset:1024
	ds_read_b128 v[156:159], v248 offset:2048
	ds_read_b128 v[160:163], v248 offset:3072
	s_cmp_eq_u32 s34, s4
	s_cselect_b32 s4, s10, s18
	s_cselect_b32 s5, s11, s5
	s_cselect_b32 s19, s13, s49
	s_cselect_b32 s18, s12, s48
	s_add_i32 m0, s22, 0xc000
	ds_read_b128 v[164:167], v150
	ds_read_b128 v[168:171], v150 offset:1024
	ds_read_b128 v[172:175], v150 offset:2048
	ds_read_b128 v[176:179], v150 offset:3072
	ds_read_b128 v[180:183], v150 offset:4096
	ds_read_b128 v[204:207], v150 offset:5120
	ds_read_b128 v[208:211], v150 offset:6144
	ds_read_b128 v[212:215], v150 offset:7168
	global_load_lds_dwordx4 v138, s[0:1]
	s_add_i32 m0, s22, 0xe000
	s_nop 0
	global_load_lds_dwordx4 v140, s[0:1]
	s_waitcnt lgkmcnt(8)
	s_barrier
	s_waitcnt lgkmcnt(0)
	v_mfma_f32_16x16x32_bf16 v[126:129], v[142:145], v[164:167], v[126:129]
	v_mfma_f32_16x16x32_bf16 v[122:125], v[156:159], v[164:167], v[122:125]
	v_mfma_f32_16x16x32_bf16 v[110:113], v[142:145], v[172:175], v[110:113]
	v_mfma_f32_16x16x32_bf16 v[106:109], v[156:159], v[172:175], v[106:109]
	v_mfma_f32_16x16x32_bf16 v[94:97], v[142:145], v[180:183], v[94:97]
	v_mfma_f32_16x16x32_bf16 v[90:93], v[156:159], v[180:183], v[90:93]
	v_mfma_f32_16x16x32_bf16 v[78:81], v[142:145], v[208:211], v[78:81]
	v_mfma_f32_16x16x32_bf16 v[74:77], v[156:159], v[208:211], v[74:77]
	v_mfma_f32_16x16x32_bf16 v[126:129], v[152:155], v[168:171], v[126:129]
	v_mfma_f32_16x16x32_bf16 v[122:125], v[160:163], v[168:171], v[122:125]
	v_mfma_f32_16x16x32_bf16 v[110:113], v[152:155], v[176:179], v[110:113]
	v_mfma_f32_16x16x32_bf16 v[106:109], v[160:163], v[176:179], v[106:109]
	v_mfma_f32_16x16x32_bf16 v[94:97], v[152:155], v[204:207], v[94:97]
	v_mfma_f32_16x16x32_bf16 v[90:93], v[160:163], v[204:207], v[90:93]
	v_mfma_f32_16x16x32_bf16 v[78:81], v[152:155], v[212:215], v[78:81]
	v_mfma_f32_16x16x32_bf16 v[74:77], v[160:163], v[212:215], v[74:77]
	s_barrier
	s_add_i32 s67, 0, 0x14000
	s_add_i32 s66, s66, s21
	ds_read_b128 v[216:219], v248 offset:16384
	ds_read_b128 v[220:223], v248 offset:17408
	ds_read_b128 v[224:227], v248 offset:18432
	ds_read_b128 v[228:231], v248 offset:19456
	s_add_u32 s70, s18, s6
	s_addc_u32 s71, s19, s7
	s_mov_b32 m0, s66
	s_nop 0
	global_load_lds_dwordx4 v132, s[18:19]
	s_add_i32 m0, s66, 0x2000
	s_nop 0
	global_load_lds_dwordx4 v136, s[18:19]
	s_barrier
	s_waitcnt lgkmcnt(0)
	v_mfma_f32_16x16x32_bf16 v[118:121], v[216:219], v[164:167], v[118:121]
	v_mfma_f32_16x16x32_bf16 v[114:117], v[224:227], v[164:167], v[114:117]
	v_mfma_f32_16x16x32_bf16 v[102:105], v[216:219], v[172:175], v[102:105]
	v_mfma_f32_16x16x32_bf16 v[98:101], v[224:227], v[172:175], v[98:101]
	v_mfma_f32_16x16x32_bf16 v[86:89], v[216:219], v[180:183], v[86:89]
	v_mfma_f32_16x16x32_bf16 v[82:85], v[224:227], v[180:183], v[82:85]
	v_mfma_f32_16x16x32_bf16 v[70:73], v[216:219], v[208:211], v[70:73]
	v_mfma_f32_16x16x32_bf16 v[66:69], v[224:227], v[208:211], v[66:69]
	v_mfma_f32_16x16x32_bf16 v[118:121], v[220:223], v[168:171], v[118:121]
	v_mfma_f32_16x16x32_bf16 v[114:117], v[228:231], v[168:171], v[114:117]
	v_mfma_f32_16x16x32_bf16 v[102:105], v[220:223], v[176:179], v[102:105]
	v_mfma_f32_16x16x32_bf16 v[98:101], v[228:231], v[176:179], v[98:101]
	v_mfma_f32_16x16x32_bf16 v[86:89], v[220:223], v[204:207], v[86:89]
	v_mfma_f32_16x16x32_bf16 v[82:85], v[228:231], v[204:207], v[82:85]
	v_mfma_f32_16x16x32_bf16 v[70:73], v[220:223], v[212:215], v[70:73]
	v_mfma_f32_16x16x32_bf16 v[66:69], v[228:231], v[212:215], v[66:69]
	s_barrier
	s_mov_b32 m0, s22
	s_add_u32 s72, s4, s6
	s_addc_u32 s73, s5, s7
	ds_read_b128 v[164:167], v150 offset:16384
	ds_read_b128 v[168:171], v150 offset:17408
	ds_read_b128 v[172:175], v150 offset:18432
	ds_read_b128 v[176:179], v150 offset:19456
	ds_read_b128 v[180:183], v150 offset:20480
	ds_read_b128 v[204:207], v150 offset:21504
	ds_read_b128 v[208:211], v150 offset:22528
	ds_read_b128 v[212:215], v150 offset:23552
	global_load_lds_dwordx4 v130, s[4:5]
	s_mov_b32 m0, s23
	s_nop 0
	global_load_lds_dwordx4 v134, s[4:5]
	s_barrier
	s_waitcnt lgkmcnt(0)
	v_mfma_f32_16x16x32_bf16 v[62:65], v[142:145], v[164:167], v[62:65]
	v_mfma_f32_16x16x32_bf16 v[58:61], v[156:159], v[164:167], v[58:61]
	v_mfma_f32_16x16x32_bf16 v[46:49], v[142:145], v[172:175], v[46:49]
	v_mfma_f32_16x16x32_bf16 v[42:45], v[156:159], v[172:175], v[42:45]
	v_mfma_f32_16x16x32_bf16 v[30:33], v[142:145], v[180:183], v[30:33]
	v_mfma_f32_16x16x32_bf16 v[26:29], v[156:159], v[180:183], v[26:29]
	v_mfma_f32_16x16x32_bf16 v[14:17], v[142:145], v[208:211], v[14:17]
	v_mfma_f32_16x16x32_bf16 v[10:13], v[156:159], v[208:211], v[10:13]
	v_mfma_f32_16x16x32_bf16 v[62:65], v[152:155], v[168:171], v[62:65]
	v_mfma_f32_16x16x32_bf16 v[58:61], v[160:163], v[168:171], v[58:61]
	v_mfma_f32_16x16x32_bf16 v[46:49], v[152:155], v[176:179], v[46:49]
	v_mfma_f32_16x16x32_bf16 v[42:45], v[160:163], v[176:179], v[42:45]
	v_mfma_f32_16x16x32_bf16 v[30:33], v[152:155], v[204:207], v[30:33]
	v_mfma_f32_16x16x32_bf16 v[26:29], v[160:163], v[204:207], v[26:29]
	v_mfma_f32_16x16x32_bf16 v[14:17], v[152:155], v[212:215], v[14:17]
	v_mfma_f32_16x16x32_bf16 v[10:13], v[160:163], v[212:215], v[10:13]
	s_barrier
	s_add_u32 s18, s18, s2
	s_addc_u32 s19, s19, 0
	s_add_i32 s66, s67, s21
	s_add_u32 s76, s18, s6
	s_addc_u32 s77, s19, s7
	s_mov_b32 m0, s66
	s_nop 0
	global_load_lds_dwordx4 v132, s[18:19]
	s_add_i32 m0, s66, 0x2000
	s_nop 0
	global_load_lds_dwordx4 v136, s[18:19]
	s_waitcnt vmcnt(6)
	s_barrier
	v_mfma_f32_16x16x32_bf16 v[54:57], v[216:219], v[164:167], v[54:57]
	v_mfma_f32_16x16x32_bf16 v[50:53], v[224:227], v[164:167], v[50:53]
	v_mfma_f32_16x16x32_bf16 v[38:41], v[216:219], v[172:175], v[38:41]
	v_mfma_f32_16x16x32_bf16 v[34:37], v[224:227], v[172:175], v[34:37]
	v_mfma_f32_16x16x32_bf16 v[22:25], v[216:219], v[180:183], v[22:25]
	v_mfma_f32_16x16x32_bf16 v[18:21], v[224:227], v[180:183], v[18:21]
	v_mfma_f32_16x16x32_bf16 v[6:9], v[216:219], v[208:211], v[6:9]
	v_mfma_f32_16x16x32_bf16 v[2:5], v[224:227], v[208:211], v[2:5]
	v_mfma_f32_16x16x32_bf16 v[54:57], v[220:223], v[168:171], v[54:57]
	v_mfma_f32_16x16x32_bf16 v[50:53], v[228:231], v[168:171], v[50:53]
	v_mfma_f32_16x16x32_bf16 v[38:41], v[220:223], v[176:179], v[38:41]
	v_mfma_f32_16x16x32_bf16 v[34:37], v[228:231], v[176:179], v[34:37]
	v_mfma_f32_16x16x32_bf16 v[22:25], v[220:223], v[204:207], v[22:25]
	v_mfma_f32_16x16x32_bf16 v[18:21], v[228:231], v[204:207], v[18:21]
	v_mfma_f32_16x16x32_bf16 v[6:9], v[220:223], v[212:215], v[6:9]
	v_mfma_f32_16x16x32_bf16 v[2:5], v[228:231], v[212:215], v[2:5]
	s_barrier
	s_add_i32 s18, 0, 0x18000
	ds_read_b128 v[142:145], v248 offset:32768
	ds_read_b128 v[152:155], v248 offset:33792
	ds_read_b128 v[156:159], v248 offset:34816
	ds_read_b128 v[160:163], v248 offset:35840
	s_add_u32 s4, s4, s2
	s_addc_u32 s5, s5, 0
	s_mov_b32 m0, s24
	ds_read_b128 v[164:167], v150 offset:32768
	ds_read_b128 v[168:171], v150 offset:33792
	ds_read_b128 v[172:175], v150 offset:34816
	ds_read_b128 v[176:179], v150 offset:35840
	ds_read_b128 v[180:183], v150 offset:36864
	ds_read_b128 v[204:207], v150 offset:37888
	ds_read_b128 v[208:211], v150 offset:38912
	ds_read_b128 v[212:215], v150 offset:39936
	global_load_lds_dwordx4 v130, s[4:5]
	s_mov_b32 m0, s25
	s_nop 0
	global_load_lds_dwordx4 v134, s[4:5]
	s_waitcnt lgkmcnt(8)
	s_barrier
	s_waitcnt lgkmcnt(0)
	v_mfma_f32_16x16x32_bf16 v[126:129], v[142:145], v[164:167], v[126:129]
	v_mfma_f32_16x16x32_bf16 v[122:125], v[156:159], v[164:167], v[122:125]
	v_mfma_f32_16x16x32_bf16 v[110:113], v[142:145], v[172:175], v[110:113]
	v_mfma_f32_16x16x32_bf16 v[106:109], v[156:159], v[172:175], v[106:109]
	v_mfma_f32_16x16x32_bf16 v[94:97], v[142:145], v[180:183], v[94:97]
	v_mfma_f32_16x16x32_bf16 v[90:93], v[156:159], v[180:183], v[90:93]
	v_mfma_f32_16x16x32_bf16 v[78:81], v[142:145], v[208:211], v[78:81]
	v_mfma_f32_16x16x32_bf16 v[74:77], v[156:159], v[208:211], v[74:77]
	v_mfma_f32_16x16x32_bf16 v[126:129], v[152:155], v[168:171], v[126:129]
	v_mfma_f32_16x16x32_bf16 v[122:125], v[160:163], v[168:171], v[122:125]
	v_mfma_f32_16x16x32_bf16 v[110:113], v[152:155], v[176:179], v[110:113]
	v_mfma_f32_16x16x32_bf16 v[106:109], v[160:163], v[176:179], v[106:109]
	v_mfma_f32_16x16x32_bf16 v[94:97], v[152:155], v[204:207], v[94:97]
	v_mfma_f32_16x16x32_bf16 v[90:93], v[160:163], v[204:207], v[90:93]
	v_mfma_f32_16x16x32_bf16 v[78:81], v[152:155], v[212:215], v[78:81]
	v_mfma_f32_16x16x32_bf16 v[74:77], v[160:163], v[212:215], v[74:77]
	s_barrier
	s_add_i32 s4, 0, 0x1c000
	s_add_i32 s5, s18, s21
	s_mov_b32 m0, s5
	ds_read_b128 v[216:219], v248 offset:49152
	ds_read_b128 v[220:223], v248 offset:50176
	ds_read_b128 v[224:227], v248 offset:51200
	ds_read_b128 v[228:231], v248 offset:52224
	global_load_lds_dwordx4 v132, s[70:71]
	s_add_i32 m0, s5, 0x2000
	s_nop 0
	global_load_lds_dwordx4 v136, s[70:71]
	s_barrier
	s_waitcnt lgkmcnt(0)
	v_mfma_f32_16x16x32_bf16 v[118:121], v[216:219], v[164:167], v[118:121]
	v_mfma_f32_16x16x32_bf16 v[114:117], v[224:227], v[164:167], v[114:117]
	v_mfma_f32_16x16x32_bf16 v[102:105], v[216:219], v[172:175], v[102:105]
	v_mfma_f32_16x16x32_bf16 v[98:101], v[224:227], v[172:175], v[98:101]
	v_mfma_f32_16x16x32_bf16 v[86:89], v[216:219], v[180:183], v[86:89]
	v_mfma_f32_16x16x32_bf16 v[82:85], v[224:227], v[180:183], v[82:85]
	v_mfma_f32_16x16x32_bf16 v[70:73], v[216:219], v[208:211], v[70:73]
	v_mfma_f32_16x16x32_bf16 v[66:69], v[224:227], v[208:211], v[66:69]
	v_mfma_f32_16x16x32_bf16 v[118:121], v[220:223], v[168:171], v[118:121]
	v_mfma_f32_16x16x32_bf16 v[114:117], v[228:231], v[168:171], v[114:117]
	v_mfma_f32_16x16x32_bf16 v[102:105], v[220:223], v[176:179], v[102:105]
	v_mfma_f32_16x16x32_bf16 v[98:101], v[228:231], v[176:179], v[98:101]
	v_mfma_f32_16x16x32_bf16 v[86:89], v[220:223], v[204:207], v[86:89]
	v_mfma_f32_16x16x32_bf16 v[82:85], v[228:231], v[204:207], v[82:85]
	v_mfma_f32_16x16x32_bf16 v[70:73], v[220:223], v[212:215], v[70:73]
	v_mfma_f32_16x16x32_bf16 v[66:69], v[228:231], v[212:215], v[66:69]
	s_barrier
	s_mov_b32 m0, s30
	ds_read_b128 v[164:167], v150 offset:49152
	ds_read_b128 v[168:171], v150 offset:50176
	ds_read_b128 v[172:175], v150 offset:51200
	ds_read_b128 v[176:179], v150 offset:52224
	ds_read_b128 v[180:183], v150 offset:53248
	ds_read_b128 v[204:207], v150 offset:54272
	ds_read_b128 v[208:211], v150 offset:55296
	ds_read_b128 v[212:215], v150 offset:56320
	global_load_lds_dwordx4 v130, s[72:73]
	s_mov_b32 m0, s31
	s_nop 0
	global_load_lds_dwordx4 v134, s[72:73]
	s_barrier
	s_waitcnt lgkmcnt(0)
	v_mfma_f32_16x16x32_bf16 v[62:65], v[142:145], v[164:167], v[62:65]
	v_mfma_f32_16x16x32_bf16 v[58:61], v[156:159], v[164:167], v[58:61]
	v_mfma_f32_16x16x32_bf16 v[46:49], v[142:145], v[172:175], v[46:49]
	v_mfma_f32_16x16x32_bf16 v[42:45], v[156:159], v[172:175], v[42:45]
	v_mfma_f32_16x16x32_bf16 v[30:33], v[142:145], v[180:183], v[30:33]
	v_mfma_f32_16x16x32_bf16 v[26:29], v[156:159], v[180:183], v[26:29]
	v_mfma_f32_16x16x32_bf16 v[14:17], v[142:145], v[208:211], v[14:17]
	v_mfma_f32_16x16x32_bf16 v[10:13], v[156:159], v[208:211], v[10:13]
	v_mfma_f32_16x16x32_bf16 v[62:65], v[152:155], v[168:171], v[62:65]
	v_mfma_f32_16x16x32_bf16 v[58:61], v[160:163], v[168:171], v[58:61]
	v_mfma_f32_16x16x32_bf16 v[46:49], v[152:155], v[176:179], v[46:49]
	v_mfma_f32_16x16x32_bf16 v[42:45], v[160:163], v[176:179], v[42:45]
	v_mfma_f32_16x16x32_bf16 v[30:33], v[152:155], v[204:207], v[30:33]
	v_mfma_f32_16x16x32_bf16 v[26:29], v[160:163], v[204:207], v[26:29]
	v_mfma_f32_16x16x32_bf16 v[14:17], v[152:155], v[212:215], v[14:17]
	v_mfma_f32_16x16x32_bf16 v[10:13], v[160:163], v[212:215], v[10:13]
	s_barrier
	s_add_i32 s4, s4, s21
	s_mov_b32 m0, s4
	s_nop 0
	global_load_lds_dwordx4 v132, s[76:77]
	s_add_i32 m0, s4, 0x2000
	s_nop 0
	global_load_lds_dwordx4 v136, s[76:77]
	s_add_u32 s0, s0, 0x100
	s_addc_u32 s1, s1, 0
	s_add_u32 s48, s48, 0x100
	s_addc_u32 s49, s49, 0
	s_cmp_ge_u32 s65, s27
	s_mov_b32 s4, s65
	s_waitcnt vmcnt(6)
	s_barrier
	v_mfma_f32_16x16x32_bf16 v[54:57], v[216:219], v[164:167], v[54:57]
	v_mfma_f32_16x16x32_bf16 v[50:53], v[224:227], v[164:167], v[50:53]
	v_mfma_f32_16x16x32_bf16 v[38:41], v[216:219], v[172:175], v[38:41]
	v_mfma_f32_16x16x32_bf16 v[34:37], v[224:227], v[172:175], v[34:37]
	v_mfma_f32_16x16x32_bf16 v[22:25], v[216:219], v[180:183], v[22:25]
	v_mfma_f32_16x16x32_bf16 v[18:21], v[224:227], v[180:183], v[18:21]
	v_mfma_f32_16x16x32_bf16 v[6:9], v[216:219], v[208:211], v[6:9]
	v_mfma_f32_16x16x32_bf16 v[2:5], v[224:227], v[208:211], v[2:5]
	v_mfma_f32_16x16x32_bf16 v[54:57], v[220:223], v[168:171], v[54:57]
	v_mfma_f32_16x16x32_bf16 v[50:53], v[228:231], v[168:171], v[50:53]
	v_mfma_f32_16x16x32_bf16 v[38:41], v[220:223], v[176:179], v[38:41]
	v_mfma_f32_16x16x32_bf16 v[34:37], v[228:231], v[176:179], v[34:37]
	v_mfma_f32_16x16x32_bf16 v[22:25], v[220:223], v[204:207], v[22:25]
	v_mfma_f32_16x16x32_bf16 v[18:21], v[228:231], v[204:207], v[18:21]
	v_mfma_f32_16x16x32_bf16 v[6:9], v[220:223], v[212:215], v[6:9]
	v_mfma_f32_16x16x32_bf16 v[2:5], v[228:231], v[212:215], v[2:5]
	s_barrier
	s_cbranch_scc0 .LBB0_698

.LBB0_741:
	s_add_u32 s0, s0, 0x80
	s_addc_u32 s1, s1, 0
	s_add_u32 s65, s4, 0x100
	s_addc_u32 s66, s5, 0
	s_mov_b32 s4, 0
	s_add_i32 s70, s4, 2
	s_add_u32 s10, s0, 0x80
	s_addc_u32 s5, s1, 0
	s_add_i32 s71, 0, 0x10000
	ds_read_b128 v[142:145], v248
	ds_read_b128 v[146:149], v248 offset:1024
	ds_read_b128 v[150:153], v248 offset:2048
	ds_read_b128 v[154:157], v248 offset:3072
	s_cmp_eq_u32 s43, s4
	s_cselect_b32 s4, s22, s10
	s_cselect_b32 s5, s23, s5
	s_cselect_b32 s11, s13, s66
	s_cselect_b32 s10, s12, s65
	s_add_i32 m0, s29, 0xc000
	ds_read_b128 v[158:161], v166
	ds_read_b128 v[168:171], v166 offset:1024
	ds_read_b128 v[172:175], v166 offset:2048
	ds_read_b128 v[176:179], v166 offset:3072
	ds_read_b128 v[180:183], v166 offset:4096
	ds_read_b128 v[204:207], v166 offset:5120
	ds_read_b128 v[208:211], v166 offset:6144
	ds_read_b128 v[212:215], v166 offset:7168
	global_load_lds_dwordx4 v138, s[0:1]
	s_add_i32 m0, s29, 0xe000
	s_nop 0
	global_load_lds_dwordx4 v140, s[0:1]
	s_waitcnt lgkmcnt(8)
	s_barrier
	s_waitcnt lgkmcnt(0)
	v_mfma_f32_16x16x32_bf16 v[126:129], v[142:145], v[158:161], 0
	v_mfma_f32_16x16x32_bf16 v[122:125], v[150:153], v[158:161], 0
	v_mfma_f32_16x16x32_bf16 v[110:113], v[142:145], v[172:175], 0
	v_mfma_f32_16x16x32_bf16 v[106:109], v[150:153], v[172:175], 0
	v_mfma_f32_16x16x32_bf16 v[94:97], v[142:145], v[180:183], 0
	v_mfma_f32_16x16x32_bf16 v[90:93], v[150:153], v[180:183], 0
	v_mfma_f32_16x16x32_bf16 v[78:81], v[142:145], v[208:211], 0
	v_mfma_f32_16x16x32_bf16 v[74:77], v[150:153], v[208:211], 0
	v_mfma_f32_16x16x32_bf16 v[126:129], v[146:149], v[168:171], v[126:129]
	v_mfma_f32_16x16x32_bf16 v[122:125], v[154:157], v[168:171], v[122:125]
	v_mfma_f32_16x16x32_bf16 v[110:113], v[146:149], v[176:179], v[110:113]
	v_mfma_f32_16x16x32_bf16 v[106:109], v[154:157], v[176:179], v[106:109]
	v_mfma_f32_16x16x32_bf16 v[94:97], v[146:149], v[204:207], v[94:97]
	v_mfma_f32_16x16x32_bf16 v[90:93], v[154:157], v[204:207], v[90:93]
	v_mfma_f32_16x16x32_bf16 v[78:81], v[146:149], v[212:215], v[78:81]
	v_mfma_f32_16x16x32_bf16 v[74:77], v[154:157], v[212:215], v[74:77]
	s_barrier
	s_add_i32 s72, 0, 0x14000
	s_add_i32 s71, s71, s28
	ds_read_b128 v[216:219], v248 offset:16384
	ds_read_b128 v[220:223], v248 offset:17408
	ds_read_b128 v[224:227], v248 offset:18432
	ds_read_b128 v[228:231], v248 offset:19456
	s_add_u32 s76, s10, s6
	s_addc_u32 s77, s11, s7
	s_mov_b32 m0, s71
	s_nop 0
	global_load_lds_dwordx4 v132, s[10:11]
	s_add_i32 m0, s71, 0x2000
	s_nop 0
	global_load_lds_dwordx4 v136, s[10:11]
	s_barrier
	s_waitcnt lgkmcnt(0)
	v_mfma_f32_16x16x32_bf16 v[118:121], v[216:219], v[158:161], 0
	v_mfma_f32_16x16x32_bf16 v[114:117], v[224:227], v[158:161], 0
	v_mfma_f32_16x16x32_bf16 v[102:105], v[216:219], v[172:175], 0
	v_mfma_f32_16x16x32_bf16 v[98:101], v[224:227], v[172:175], 0
	v_mfma_f32_16x16x32_bf16 v[86:89], v[216:219], v[180:183], 0
	v_mfma_f32_16x16x32_bf16 v[82:85], v[224:227], v[180:183], 0
	v_mfma_f32_16x16x32_bf16 v[70:73], v[216:219], v[208:211], 0
	v_mfma_f32_16x16x32_bf16 v[66:69], v[224:227], v[208:211], 0
	v_mfma_f32_16x16x32_bf16 v[118:121], v[220:223], v[168:171], v[118:121]
	v_mfma_f32_16x16x32_bf16 v[114:117], v[228:231], v[168:171], v[114:117]
	v_mfma_f32_16x16x32_bf16 v[102:105], v[220:223], v[176:179], v[102:105]
	v_mfma_f32_16x16x32_bf16 v[98:101], v[228:231], v[176:179], v[98:101]
	v_mfma_f32_16x16x32_bf16 v[86:89], v[220:223], v[204:207], v[86:89]
	v_mfma_f32_16x16x32_bf16 v[82:85], v[228:231], v[204:207], v[82:85]
	v_mfma_f32_16x16x32_bf16 v[70:73], v[220:223], v[212:215], v[70:73]
	v_mfma_f32_16x16x32_bf16 v[66:69], v[228:231], v[212:215], v[66:69]
	s_barrier
	s_mov_b32 m0, s29
	s_add_u32 s78, s4, s6
	s_addc_u32 s79, s5, s7
	ds_read_b128 v[158:161], v166 offset:16384
	ds_read_b128 v[168:171], v166 offset:17408
	ds_read_b128 v[172:175], v166 offset:18432
	ds_read_b128 v[176:179], v166 offset:19456
	ds_read_b128 v[180:183], v166 offset:20480
	ds_read_b128 v[204:207], v166 offset:21504
	ds_read_b128 v[208:211], v166 offset:22528
	ds_read_b128 v[212:215], v166 offset:23552
	global_load_lds_dwordx4 v130, s[4:5]
	s_mov_b32 m0, s30
	s_nop 0
	global_load_lds_dwordx4 v134, s[4:5]
	s_barrier
	s_waitcnt lgkmcnt(0)
	v_mfma_f32_16x16x32_bf16 v[62:65], v[142:145], v[158:161], 0
	v_mfma_f32_16x16x32_bf16 v[58:61], v[150:153], v[158:161], 0
	v_mfma_f32_16x16x32_bf16 v[46:49], v[142:145], v[172:175], 0
	v_mfma_f32_16x16x32_bf16 v[42:45], v[150:153], v[172:175], 0
	v_mfma_f32_16x16x32_bf16 v[30:33], v[142:145], v[180:183], 0
	v_mfma_f32_16x16x32_bf16 v[26:29], v[150:153], v[180:183], 0
	v_mfma_f32_16x16x32_bf16 v[14:17], v[142:145], v[208:211], 0
	v_mfma_f32_16x16x32_bf16 v[10:13], v[150:153], v[208:211], 0
	v_mfma_f32_16x16x32_bf16 v[62:65], v[146:149], v[168:171], v[62:65]
	v_mfma_f32_16x16x32_bf16 v[58:61], v[154:157], v[168:171], v[58:61]
	v_mfma_f32_16x16x32_bf16 v[46:49], v[146:149], v[176:179], v[46:49]
	v_mfma_f32_16x16x32_bf16 v[42:45], v[154:157], v[176:179], v[42:45]
	v_mfma_f32_16x16x32_bf16 v[30:33], v[146:149], v[204:207], v[30:33]
	v_mfma_f32_16x16x32_bf16 v[26:29], v[154:157], v[204:207], v[26:29]
	v_mfma_f32_16x16x32_bf16 v[14:17], v[146:149], v[212:215], v[14:17]
	v_mfma_f32_16x16x32_bf16 v[10:13], v[154:157], v[212:215], v[10:13]
	s_barrier
	s_add_u32 s10, s10, s2
	s_addc_u32 s11, s11, 0
	s_add_i32 s71, s72, s28
	s_add_u32 s80, s10, s6
	s_addc_u32 s81, s11, s7
	s_mov_b32 m0, s71
	s_nop 0
	global_load_lds_dwordx4 v132, s[10:11]
	s_add_i32 m0, s71, 0x2000
	s_nop 0
	global_load_lds_dwordx4 v136, s[10:11]
	s_waitcnt vmcnt(6)
	s_barrier
	v_mfma_f32_16x16x32_bf16 v[54:57], v[216:219], v[158:161], 0
	v_mfma_f32_16x16x32_bf16 v[50:53], v[224:227], v[158:161], 0
	v_mfma_f32_16x16x32_bf16 v[38:41], v[216:219], v[172:175], 0
	v_mfma_f32_16x16x32_bf16 v[34:37], v[224:227], v[172:175], 0
	v_mfma_f32_16x16x32_bf16 v[22:25], v[216:219], v[180:183], 0
	v_mfma_f32_16x16x32_bf16 v[18:21], v[224:227], v[180:183], 0
	v_mfma_f32_16x16x32_bf16 v[6:9], v[216:219], v[208:211], 0
	v_mfma_f32_16x16x32_bf16 v[2:5], v[224:227], v[208:211], 0
	v_mfma_f32_16x16x32_bf16 v[54:57], v[220:223], v[168:171], v[54:57]
	v_mfma_f32_16x16x32_bf16 v[50:53], v[228:231], v[168:171], v[50:53]
	v_mfma_f32_16x16x32_bf16 v[38:41], v[220:223], v[176:179], v[38:41]
	v_mfma_f32_16x16x32_bf16 v[34:37], v[228:231], v[176:179], v[34:37]
	v_mfma_f32_16x16x32_bf16 v[22:25], v[220:223], v[204:207], v[22:25]
	v_mfma_f32_16x16x32_bf16 v[18:21], v[228:231], v[204:207], v[18:21]
	v_mfma_f32_16x16x32_bf16 v[6:9], v[220:223], v[212:215], v[6:9]
	v_mfma_f32_16x16x32_bf16 v[2:5], v[228:231], v[212:215], v[2:5]
	s_barrier
	s_add_i32 s10, 0, 0x18000
	ds_read_b128 v[142:145], v248 offset:32768
	ds_read_b128 v[146:149], v248 offset:33792
	ds_read_b128 v[150:153], v248 offset:34816
	ds_read_b128 v[154:157], v248 offset:35840
	s_add_u32 s4, s4, s2
	s_addc_u32 s5, s5, 0
	s_mov_b32 m0, s31
	ds_read_b128 v[158:161], v166 offset:32768
	ds_read_b128 v[168:171], v166 offset:33792
	ds_read_b128 v[172:175], v166 offset:34816
	ds_read_b128 v[176:179], v166 offset:35840
	ds_read_b128 v[180:183], v166 offset:36864
	ds_read_b128 v[204:207], v166 offset:37888
	ds_read_b128 v[208:211], v166 offset:38912
	ds_read_b128 v[212:215], v166 offset:39936
	global_load_lds_dwordx4 v130, s[4:5]
	s_mov_b32 m0, s34
	s_nop 0
	global_load_lds_dwordx4 v134, s[4:5]
	s_waitcnt lgkmcnt(8)
	s_barrier
	s_waitcnt lgkmcnt(0)
	v_mfma_f32_16x16x32_bf16 v[126:129], v[142:145], v[158:161], v[126:129]
	v_mfma_f32_16x16x32_bf16 v[122:125], v[150:153], v[158:161], v[122:125]
	v_mfma_f32_16x16x32_bf16 v[110:113], v[142:145], v[172:175], v[110:113]
	v_mfma_f32_16x16x32_bf16 v[106:109], v[150:153], v[172:175], v[106:109]
	v_mfma_f32_16x16x32_bf16 v[94:97], v[142:145], v[180:183], v[94:97]
	v_mfma_f32_16x16x32_bf16 v[90:93], v[150:153], v[180:183], v[90:93]
	v_mfma_f32_16x16x32_bf16 v[78:81], v[142:145], v[208:211], v[78:81]
	v_mfma_f32_16x16x32_bf16 v[74:77], v[150:153], v[208:211], v[74:77]
	v_mfma_f32_16x16x32_bf16 v[126:129], v[146:149], v[168:171], v[126:129]
	v_mfma_f32_16x16x32_bf16 v[122:125], v[154:157], v[168:171], v[122:125]
	v_mfma_f32_16x16x32_bf16 v[110:113], v[146:149], v[176:179], v[110:113]
	v_mfma_f32_16x16x32_bf16 v[106:109], v[154:157], v[176:179], v[106:109]
	v_mfma_f32_16x16x32_bf16 v[94:97], v[146:149], v[204:207], v[94:97]
	v_mfma_f32_16x16x32_bf16 v[90:93], v[154:157], v[204:207], v[90:93]
	v_mfma_f32_16x16x32_bf16 v[78:81], v[146:149], v[212:215], v[78:81]
	v_mfma_f32_16x16x32_bf16 v[74:77], v[154:157], v[212:215], v[74:77]
	s_barrier
	s_add_i32 s4, 0, 0x1c000
	s_add_i32 s5, s10, s28
	s_mov_b32 m0, s5
	ds_read_b128 v[216:219], v248 offset:49152
	ds_read_b128 v[220:223], v248 offset:50176
	ds_read_b128 v[224:227], v248 offset:51200
	ds_read_b128 v[228:231], v248 offset:52224
	global_load_lds_dwordx4 v132, s[76:77]
	s_add_i32 m0, s5, 0x2000
	s_nop 0
	global_load_lds_dwordx4 v136, s[76:77]
	s_barrier
	s_waitcnt lgkmcnt(0)
	v_mfma_f32_16x16x32_bf16 v[118:121], v[216:219], v[158:161], v[118:121]
	v_mfma_f32_16x16x32_bf16 v[114:117], v[224:227], v[158:161], v[114:117]
	v_mfma_f32_16x16x32_bf16 v[102:105], v[216:219], v[172:175], v[102:105]
	v_mfma_f32_16x16x32_bf16 v[98:101], v[224:227], v[172:175], v[98:101]
	v_mfma_f32_16x16x32_bf16 v[86:89], v[216:219], v[180:183], v[86:89]
	v_mfma_f32_16x16x32_bf16 v[82:85], v[224:227], v[180:183], v[82:85]
	v_mfma_f32_16x16x32_bf16 v[70:73], v[216:219], v[208:211], v[70:73]
	v_mfma_f32_16x16x32_bf16 v[66:69], v[224:227], v[208:211], v[66:69]
	v_mfma_f32_16x16x32_bf16 v[118:121], v[220:223], v[168:171], v[118:121]
	v_mfma_f32_16x16x32_bf16 v[114:117], v[228:231], v[168:171], v[114:117]
	v_mfma_f32_16x16x32_bf16 v[102:105], v[220:223], v[176:179], v[102:105]
	v_mfma_f32_16x16x32_bf16 v[98:101], v[228:231], v[176:179], v[98:101]
	v_mfma_f32_16x16x32_bf16 v[86:89], v[220:223], v[204:207], v[86:89]
	v_mfma_f32_16x16x32_bf16 v[82:85], v[228:231], v[204:207], v[82:85]
	v_mfma_f32_16x16x32_bf16 v[70:73], v[220:223], v[212:215], v[70:73]
	v_mfma_f32_16x16x32_bf16 v[66:69], v[228:231], v[212:215], v[66:69]
	s_barrier
	s_mov_b32 m0, s41
	ds_read_b128 v[158:161], v166 offset:49152
	ds_read_b128 v[168:171], v166 offset:50176
	ds_read_b128 v[172:175], v166 offset:51200
	ds_read_b128 v[176:179], v166 offset:52224
	ds_read_b128 v[180:183], v166 offset:53248
	ds_read_b128 v[204:207], v166 offset:54272
	ds_read_b128 v[208:211], v166 offset:55296
	ds_read_b128 v[212:215], v166 offset:56320
	global_load_lds_dwordx4 v130, s[78:79]
	s_mov_b32 m0, s42
	s_nop 0
	global_load_lds_dwordx4 v134, s[78:79]
	s_barrier
	s_waitcnt lgkmcnt(0)
	v_mfma_f32_16x16x32_bf16 v[62:65], v[142:145], v[158:161], v[62:65]
	v_mfma_f32_16x16x32_bf16 v[58:61], v[150:153], v[158:161], v[58:61]
	v_mfma_f32_16x16x32_bf16 v[46:49], v[142:145], v[172:175], v[46:49]
	v_mfma_f32_16x16x32_bf16 v[42:45], v[150:153], v[172:175], v[42:45]
	v_mfma_f32_16x16x32_bf16 v[30:33], v[142:145], v[180:183], v[30:33]
	v_mfma_f32_16x16x32_bf16 v[26:29], v[150:153], v[180:183], v[26:29]
	v_mfma_f32_16x16x32_bf16 v[14:17], v[142:145], v[208:211], v[14:17]
	v_mfma_f32_16x16x32_bf16 v[10:13], v[150:153], v[208:211], v[10:13]
	v_mfma_f32_16x16x32_bf16 v[62:65], v[146:149], v[168:171], v[62:65]
	v_mfma_f32_16x16x32_bf16 v[58:61], v[154:157], v[168:171], v[58:61]
	v_mfma_f32_16x16x32_bf16 v[46:49], v[146:149], v[176:179], v[46:49]
	v_mfma_f32_16x16x32_bf16 v[42:45], v[154:157], v[176:179], v[42:45]
	v_mfma_f32_16x16x32_bf16 v[30:33], v[146:149], v[204:207], v[30:33]
	v_mfma_f32_16x16x32_bf16 v[26:29], v[154:157], v[204:207], v[26:29]
	v_mfma_f32_16x16x32_bf16 v[14:17], v[146:149], v[212:215], v[14:17]
	v_mfma_f32_16x16x32_bf16 v[10:13], v[154:157], v[212:215], v[10:13]
	s_barrier
	s_add_i32 s4, s4, s28
	s_mov_b32 m0, s4
	s_nop 0
	global_load_lds_dwordx4 v132, s[80:81]
	s_add_i32 m0, s4, 0x2000
	s_nop 0
	global_load_lds_dwordx4 v136, s[80:81]
	s_add_u32 s0, s0, 0x100
	s_addc_u32 s1, s1, 0
	s_add_u32 s65, s65, 0x100
	s_addc_u32 s66, s66, 0
	s_cmp_ge_u32 s70, s35
	s_mov_b32 s4, s70
	s_waitcnt vmcnt(6)
	s_barrier
	v_mfma_f32_16x16x32_bf16 v[54:57], v[216:219], v[158:161], v[54:57]
	v_mfma_f32_16x16x32_bf16 v[50:53], v[224:227], v[158:161], v[50:53]
	v_mfma_f32_16x16x32_bf16 v[38:41], v[216:219], v[172:175], v[38:41]
	v_mfma_f32_16x16x32_bf16 v[34:37], v[224:227], v[172:175], v[34:37]
	v_mfma_f32_16x16x32_bf16 v[22:25], v[216:219], v[180:183], v[22:25]
	v_mfma_f32_16x16x32_bf16 v[18:21], v[224:227], v[180:183], v[18:21]
	v_mfma_f32_16x16x32_bf16 v[6:9], v[216:219], v[208:211], v[6:9]
	v_mfma_f32_16x16x32_bf16 v[2:5], v[224:227], v[208:211], v[2:5]
	v_mfma_f32_16x16x32_bf16 v[54:57], v[220:223], v[168:171], v[54:57]
	v_mfma_f32_16x16x32_bf16 v[50:53], v[228:231], v[168:171], v[50:53]
	v_mfma_f32_16x16x32_bf16 v[38:41], v[220:223], v[176:179], v[38:41]
	v_mfma_f32_16x16x32_bf16 v[34:37], v[228:231], v[176:179], v[34:37]
	v_mfma_f32_16x16x32_bf16 v[22:25], v[220:223], v[204:207], v[22:25]
	v_mfma_f32_16x16x32_bf16 v[18:21], v[228:231], v[204:207], v[18:21]
	v_mfma_f32_16x16x32_bf16 v[6:9], v[220:223], v[212:215], v[6:9]
	v_mfma_f32_16x16x32_bf16 v[2:5], v[228:231], v[212:215], v[2:5]
	s_barrier
	s_cbranch_scc1 .Lkexit_742
.LBB0_742:
	s_add_i32 s70, s4, 2
	s_add_u32 s10, s0, 0x80
	s_addc_u32 s5, s1, 0
	s_add_i32 s71, 0, 0x10000
	ds_read_b128 v[142:145], v248
	ds_read_b128 v[146:149], v248 offset:1024
	ds_read_b128 v[150:153], v248 offset:2048
	ds_read_b128 v[154:157], v248 offset:3072
	s_cmp_eq_u32 s43, s4
	s_cselect_b32 s4, s22, s10
	s_cselect_b32 s5, s23, s5
	s_cselect_b32 s11, s13, s66
	s_cselect_b32 s10, s12, s65
	s_add_i32 m0, s29, 0xc000
	ds_read_b128 v[158:161], v166
	ds_read_b128 v[168:171], v166 offset:1024
	ds_read_b128 v[172:175], v166 offset:2048
	ds_read_b128 v[176:179], v166 offset:3072
	ds_read_b128 v[180:183], v166 offset:4096
	ds_read_b128 v[204:207], v166 offset:5120
	ds_read_b128 v[208:211], v166 offset:6144
	ds_read_b128 v[212:215], v166 offset:7168
	global_load_lds_dwordx4 v138, s[0:1]
	s_add_i32 m0, s29, 0xe000
	s_nop 0
	global_load_lds_dwordx4 v140, s[0:1]
	s_waitcnt lgkmcnt(8)
	s_barrier
	s_waitcnt lgkmcnt(0)
	v_mfma_f32_16x16x32_bf16 v[126:129], v[142:145], v[158:161], v[126:129]
	v_mfma_f32_16x16x32_bf16 v[122:125], v[150:153], v[158:161], v[122:125]
	v_mfma_f32_16x16x32_bf16 v[110:113], v[142:145], v[172:175], v[110:113]
	v_mfma_f32_16x16x32_bf16 v[106:109], v[150:153], v[172:175], v[106:109]
	v_mfma_f32_16x16x32_bf16 v[94:97], v[142:145], v[180:183], v[94:97]
	v_mfma_f32_16x16x32_bf16 v[90:93], v[150:153], v[180:183], v[90:93]
	v_mfma_f32_16x16x32_bf16 v[78:81], v[142:145], v[208:211], v[78:81]
	v_mfma_f32_16x16x32_bf16 v[74:77], v[150:153], v[208:211], v[74:77]
	v_mfma_f32_16x16x32_bf16 v[126:129], v[146:149], v[168:171], v[126:129]
	v_mfma_f32_16x16x32_bf16 v[122:125], v[154:157], v[168:171], v[122:125]
	v_mfma_f32_16x16x32_bf16 v[110:113], v[146:149], v[176:179], v[110:113]
	v_mfma_f32_16x16x32_bf16 v[106:109], v[154:157], v[176:179], v[106:109]
	v_mfma_f32_16x16x32_bf16 v[94:97], v[146:149], v[204:207], v[94:97]
	v_mfma_f32_16x16x32_bf16 v[90:93], v[154:157], v[204:207], v[90:93]
	v_mfma_f32_16x16x32_bf16 v[78:81], v[146:149], v[212:215], v[78:81]
	v_mfma_f32_16x16x32_bf16 v[74:77], v[154:157], v[212:215], v[74:77]
	s_barrier
	s_add_i32 s72, 0, 0x14000
	s_add_i32 s71, s71, s28
	ds_read_b128 v[216:219], v248 offset:16384
	ds_read_b128 v[220:223], v248 offset:17408
	ds_read_b128 v[224:227], v248 offset:18432
	ds_read_b128 v[228:231], v248 offset:19456
	s_add_u32 s76, s10, s6
	s_addc_u32 s77, s11, s7
	s_mov_b32 m0, s71
	s_nop 0
	global_load_lds_dwordx4 v132, s[10:11]
	s_add_i32 m0, s71, 0x2000
	s_nop 0
	global_load_lds_dwordx4 v136, s[10:11]
	s_barrier
	s_waitcnt lgkmcnt(0)
	v_mfma_f32_16x16x32_bf16 v[118:121], v[216:219], v[158:161], v[118:121]
	v_mfma_f32_16x16x32_bf16 v[114:117], v[224:227], v[158:161], v[114:117]
	v_mfma_f32_16x16x32_bf16 v[102:105], v[216:219], v[172:175], v[102:105]
	v_mfma_f32_16x16x32_bf16 v[98:101], v[224:227], v[172:175], v[98:101]
	v_mfma_f32_16x16x32_bf16 v[86:89], v[216:219], v[180:183], v[86:89]
	v_mfma_f32_16x16x32_bf16 v[82:85], v[224:227], v[180:183], v[82:85]
	v_mfma_f32_16x16x32_bf16 v[70:73], v[216:219], v[208:211], v[70:73]
	v_mfma_f32_16x16x32_bf16 v[66:69], v[224:227], v[208:211], v[66:69]
	v_mfma_f32_16x16x32_bf16 v[118:121], v[220:223], v[168:171], v[118:121]
	v_mfma_f32_16x16x32_bf16 v[114:117], v[228:231], v[168:171], v[114:117]
	v_mfma_f32_16x16x32_bf16 v[102:105], v[220:223], v[176:179], v[102:105]
	v_mfma_f32_16x16x32_bf16 v[98:101], v[228:231], v[176:179], v[98:101]
	v_mfma_f32_16x16x32_bf16 v[86:89], v[220:223], v[204:207], v[86:89]
	v_mfma_f32_16x16x32_bf16 v[82:85], v[228:231], v[204:207], v[82:85]
	v_mfma_f32_16x16x32_bf16 v[70:73], v[220:223], v[212:215], v[70:73]
	v_mfma_f32_16x16x32_bf16 v[66:69], v[228:231], v[212:215], v[66:69]
	s_barrier
	s_mov_b32 m0, s29
	s_add_u32 s78, s4, s6
	s_addc_u32 s79, s5, s7
	ds_read_b128 v[158:161], v166 offset:16384
	ds_read_b128 v[168:171], v166 offset:17408
	ds_read_b128 v[172:175], v166 offset:18432
	ds_read_b128 v[176:179], v166 offset:19456
	ds_read_b128 v[180:183], v166 offset:20480
	ds_read_b128 v[204:207], v166 offset:21504
	ds_read_b128 v[208:211], v166 offset:22528
	ds_read_b128 v[212:215], v166 offset:23552
	global_load_lds_dwordx4 v130, s[4:5]
	s_mov_b32 m0, s30
	s_nop 0
	global_load_lds_dwordx4 v134, s[4:5]
	s_barrier
	s_waitcnt lgkmcnt(0)
	v_mfma_f32_16x16x32_bf16 v[62:65], v[142:145], v[158:161], v[62:65]
	v_mfma_f32_16x16x32_bf16 v[58:61], v[150:153], v[158:161], v[58:61]
	v_mfma_f32_16x16x32_bf16 v[46:49], v[142:145], v[172:175], v[46:49]
	v_mfma_f32_16x16x32_bf16 v[42:45], v[150:153], v[172:175], v[42:45]
	v_mfma_f32_16x16x32_bf16 v[30:33], v[142:145], v[180:183], v[30:33]
	v_mfma_f32_16x16x32_bf16 v[26:29], v[150:153], v[180:183], v[26:29]
	v_mfma_f32_16x16x32_bf16 v[14:17], v[142:145], v[208:211], v[14:17]
	v_mfma_f32_16x16x32_bf16 v[10:13], v[150:153], v[208:211], v[10:13]
	v_mfma_f32_16x16x32_bf16 v[62:65], v[146:149], v[168:171], v[62:65]
	v_mfma_f32_16x16x32_bf16 v[58:61], v[154:157], v[168:171], v[58:61]
	v_mfma_f32_16x16x32_bf16 v[46:49], v[146:149], v[176:179], v[46:49]
	v_mfma_f32_16x16x32_bf16 v[42:45], v[154:157], v[176:179], v[42:45]
	v_mfma_f32_16x16x32_bf16 v[30:33], v[146:149], v[204:207], v[30:33]
	v_mfma_f32_16x16x32_bf16 v[26:29], v[154:157], v[204:207], v[26:29]
	v_mfma_f32_16x16x32_bf16 v[14:17], v[146:149], v[212:215], v[14:17]
	v_mfma_f32_16x16x32_bf16 v[10:13], v[154:157], v[212:215], v[10:13]
	s_barrier
	s_add_u32 s10, s10, s2
	s_addc_u32 s11, s11, 0
	s_add_i32 s71, s72, s28
	s_add_u32 s80, s10, s6
	s_addc_u32 s81, s11, s7
	s_mov_b32 m0, s71
	s_nop 0
	global_load_lds_dwordx4 v132, s[10:11]
	s_add_i32 m0, s71, 0x2000
	s_nop 0
	global_load_lds_dwordx4 v136, s[10:11]
	s_waitcnt vmcnt(6)
	s_barrier
	v_mfma_f32_16x16x32_bf16 v[54:57], v[216:219], v[158:161], v[54:57]
	v_mfma_f32_16x16x32_bf16 v[50:53], v[224:227], v[158:161], v[50:53]
	v_mfma_f32_16x16x32_bf16 v[38:41], v[216:219], v[172:175], v[38:41]
	v_mfma_f32_16x16x32_bf16 v[34:37], v[224:227], v[172:175], v[34:37]
	v_mfma_f32_16x16x32_bf16 v[22:25], v[216:219], v[180:183], v[22:25]
	v_mfma_f32_16x16x32_bf16 v[18:21], v[224:227], v[180:183], v[18:21]
	v_mfma_f32_16x16x32_bf16 v[6:9], v[216:219], v[208:211], v[6:9]
	v_mfma_f32_16x16x32_bf16 v[2:5], v[224:227], v[208:211], v[2:5]
	v_mfma_f32_16x16x32_bf16 v[54:57], v[220:223], v[168:171], v[54:57]
	v_mfma_f32_16x16x32_bf16 v[50:53], v[228:231], v[168:171], v[50:53]
	v_mfma_f32_16x16x32_bf16 v[38:41], v[220:223], v[176:179], v[38:41]
	v_mfma_f32_16x16x32_bf16 v[34:37], v[228:231], v[176:179], v[34:37]
	v_mfma_f32_16x16x32_bf16 v[22:25], v[220:223], v[204:207], v[22:25]
	v_mfma_f32_16x16x32_bf16 v[18:21], v[228:231], v[204:207], v[18:21]
	v_mfma_f32_16x16x32_bf16 v[6:9], v[220:223], v[212:215], v[6:9]
	v_mfma_f32_16x16x32_bf16 v[2:5], v[228:231], v[212:215], v[2:5]
	s_barrier
	s_add_i32 s10, 0, 0x18000
	ds_read_b128 v[142:145], v248 offset:32768
	ds_read_b128 v[146:149], v248 offset:33792
	ds_read_b128 v[150:153], v248 offset:34816
	ds_read_b128 v[154:157], v248 offset:35840
	s_add_u32 s4, s4, s2
	s_addc_u32 s5, s5, 0
	s_mov_b32 m0, s31
	ds_read_b128 v[158:161], v166 offset:32768
	ds_read_b128 v[168:171], v166 offset:33792
	ds_read_b128 v[172:175], v166 offset:34816
	ds_read_b128 v[176:179], v166 offset:35840
	ds_read_b128 v[180:183], v166 offset:36864
	ds_read_b128 v[204:207], v166 offset:37888
	ds_read_b128 v[208:211], v166 offset:38912
	ds_read_b128 v[212:215], v166 offset:39936
	global_load_lds_dwordx4 v130, s[4:5]
	s_mov_b32 m0, s34
	s_nop 0
	global_load_lds_dwordx4 v134, s[4:5]
	s_waitcnt lgkmcnt(8)
	s_barrier
	s_waitcnt lgkmcnt(0)
	v_mfma_f32_16x16x32_bf16 v[126:129], v[142:145], v[158:161], v[126:129]
	v_mfma_f32_16x16x32_bf16 v[122:125], v[150:153], v[158:161], v[122:125]
	v_mfma_f32_16x16x32_bf16 v[110:113], v[142:145], v[172:175], v[110:113]
	v_mfma_f32_16x16x32_bf16 v[106:109], v[150:153], v[172:175], v[106:109]
	v_mfma_f32_16x16x32_bf16 v[94:97], v[142:145], v[180:183], v[94:97]
	v_mfma_f32_16x16x32_bf16 v[90:93], v[150:153], v[180:183], v[90:93]
	v_mfma_f32_16x16x32_bf16 v[78:81], v[142:145], v[208:211], v[78:81]
	v_mfma_f32_16x16x32_bf16 v[74:77], v[150:153], v[208:211], v[74:77]
	v_mfma_f32_16x16x32_bf16 v[126:129], v[146:149], v[168:171], v[126:129]
	v_mfma_f32_16x16x32_bf16 v[122:125], v[154:157], v[168:171], v[122:125]
	v_mfma_f32_16x16x32_bf16 v[110:113], v[146:149], v[176:179], v[110:113]
	v_mfma_f32_16x16x32_bf16 v[106:109], v[154:157], v[176:179], v[106:109]
	v_mfma_f32_16x16x32_bf16 v[94:97], v[146:149], v[204:207], v[94:97]
	v_mfma_f32_16x16x32_bf16 v[90:93], v[154:157], v[204:207], v[90:93]
	v_mfma_f32_16x16x32_bf16 v[78:81], v[146:149], v[212:215], v[78:81]
	v_mfma_f32_16x16x32_bf16 v[74:77], v[154:157], v[212:215], v[74:77]
	s_barrier
	s_add_i32 s4, 0, 0x1c000
	s_add_i32 s5, s10, s28
	s_mov_b32 m0, s5
	ds_read_b128 v[216:219], v248 offset:49152
	ds_read_b128 v[220:223], v248 offset:50176
	ds_read_b128 v[224:227], v248 offset:51200
	ds_read_b128 v[228:231], v248 offset:52224
	global_load_lds_dwordx4 v132, s[76:77]
	s_add_i32 m0, s5, 0x2000
	s_nop 0
	global_load_lds_dwordx4 v136, s[76:77]
	s_barrier
	s_waitcnt lgkmcnt(0)
	v_mfma_f32_16x16x32_bf16 v[118:121], v[216:219], v[158:161], v[118:121]
	v_mfma_f32_16x16x32_bf16 v[114:117], v[224:227], v[158:161], v[114:117]
	v_mfma_f32_16x16x32_bf16 v[102:105], v[216:219], v[172:175], v[102:105]
	v_mfma_f32_16x16x32_bf16 v[98:101], v[224:227], v[172:175], v[98:101]
	v_mfma_f32_16x16x32_bf16 v[86:89], v[216:219], v[180:183], v[86:89]
	v_mfma_f32_16x16x32_bf16 v[82:85], v[224:227], v[180:183], v[82:85]
	v_mfma_f32_16x16x32_bf16 v[70:73], v[216:219], v[208:211], v[70:73]
	v_mfma_f32_16x16x32_bf16 v[66:69], v[224:227], v[208:211], v[66:69]
	v_mfma_f32_16x16x32_bf16 v[118:121], v[220:223], v[168:171], v[118:121]
	v_mfma_f32_16x16x32_bf16 v[114:117], v[228:231], v[168:171], v[114:117]
	v_mfma_f32_16x16x32_bf16 v[102:105], v[220:223], v[176:179], v[102:105]
	v_mfma_f32_16x16x32_bf16 v[98:101], v[228:231], v[176:179], v[98:101]
	v_mfma_f32_16x16x32_bf16 v[86:89], v[220:223], v[204:207], v[86:89]
	v_mfma_f32_16x16x32_bf16 v[82:85], v[228:231], v[204:207], v[82:85]
	v_mfma_f32_16x16x32_bf16 v[70:73], v[220:223], v[212:215], v[70:73]
	v_mfma_f32_16x16x32_bf16 v[66:69], v[228:231], v[212:215], v[66:69]
	s_barrier
	s_mov_b32 m0, s41
	ds_read_b128 v[158:161], v166 offset:49152
	ds_read_b128 v[168:171], v166 offset:50176
	ds_read_b128 v[172:175], v166 offset:51200
	ds_read_b128 v[176:179], v166 offset:52224
	ds_read_b128 v[180:183], v166 offset:53248
	ds_read_b128 v[204:207], v166 offset:54272
	ds_read_b128 v[208:211], v166 offset:55296
	ds_read_b128 v[212:215], v166 offset:56320
	global_load_lds_dwordx4 v130, s[78:79]
	s_mov_b32 m0, s42
	s_nop 0
	global_load_lds_dwordx4 v134, s[78:79]
	s_barrier
	s_waitcnt lgkmcnt(0)
	v_mfma_f32_16x16x32_bf16 v[62:65], v[142:145], v[158:161], v[62:65]
	v_mfma_f32_16x16x32_bf16 v[58:61], v[150:153], v[158:161], v[58:61]
	v_mfma_f32_16x16x32_bf16 v[46:49], v[142:145], v[172:175], v[46:49]
	v_mfma_f32_16x16x32_bf16 v[42:45], v[150:153], v[172:175], v[42:45]
	v_mfma_f32_16x16x32_bf16 v[30:33], v[142:145], v[180:183], v[30:33]
	v_mfma_f32_16x16x32_bf16 v[26:29], v[150:153], v[180:183], v[26:29]
	v_mfma_f32_16x16x32_bf16 v[14:17], v[142:145], v[208:211], v[14:17]
	v_mfma_f32_16x16x32_bf16 v[10:13], v[150:153], v[208:211], v[10:13]
	v_mfma_f32_16x16x32_bf16 v[62:65], v[146:149], v[168:171], v[62:65]
	v_mfma_f32_16x16x32_bf16 v[58:61], v[154:157], v[168:171], v[58:61]
	v_mfma_f32_16x16x32_bf16 v[46:49], v[146:149], v[176:179], v[46:49]
	v_mfma_f32_16x16x32_bf16 v[42:45], v[154:157], v[176:179], v[42:45]
	v_mfma_f32_16x16x32_bf16 v[30:33], v[146:149], v[204:207], v[30:33]
	v_mfma_f32_16x16x32_bf16 v[26:29], v[154:157], v[204:207], v[26:29]
	v_mfma_f32_16x16x32_bf16 v[14:17], v[146:149], v[212:215], v[14:17]
	v_mfma_f32_16x16x32_bf16 v[10:13], v[154:157], v[212:215], v[10:13]
	s_barrier
	s_add_i32 s4, s4, s28
	s_mov_b32 m0, s4
	s_nop 0
	global_load_lds_dwordx4 v132, s[80:81]
	s_add_i32 m0, s4, 0x2000
	s_nop 0
	global_load_lds_dwordx4 v136, s[80:81]
	s_add_u32 s0, s0, 0x100
	s_addc_u32 s1, s1, 0
	s_add_u32 s65, s65, 0x100
	s_addc_u32 s66, s66, 0
	s_cmp_ge_u32 s70, s35
	s_mov_b32 s4, s70
	s_waitcnt vmcnt(6)
	s_barrier
	v_mfma_f32_16x16x32_bf16 v[54:57], v[216:219], v[158:161], v[54:57]
	v_mfma_f32_16x16x32_bf16 v[50:53], v[224:227], v[158:161], v[50:53]
	v_mfma_f32_16x16x32_bf16 v[38:41], v[216:219], v[172:175], v[38:41]
	v_mfma_f32_16x16x32_bf16 v[34:37], v[224:227], v[172:175], v[34:37]
	v_mfma_f32_16x16x32_bf16 v[22:25], v[216:219], v[180:183], v[22:25]
	v_mfma_f32_16x16x32_bf16 v[18:21], v[224:227], v[180:183], v[18:21]
	v_mfma_f32_16x16x32_bf16 v[6:9], v[216:219], v[208:211], v[6:9]
	v_mfma_f32_16x16x32_bf16 v[2:5], v[224:227], v[208:211], v[2:5]
	v_mfma_f32_16x16x32_bf16 v[54:57], v[220:223], v[168:171], v[54:57]
	v_mfma_f32_16x16x32_bf16 v[50:53], v[228:231], v[168:171], v[50:53]
	v_mfma_f32_16x16x32_bf16 v[38:41], v[220:223], v[176:179], v[38:41]
	v_mfma_f32_16x16x32_bf16 v[34:37], v[228:231], v[176:179], v[34:37]
	v_mfma_f32_16x16x32_bf16 v[22:25], v[220:223], v[204:207], v[22:25]
	v_mfma_f32_16x16x32_bf16 v[18:21], v[228:231], v[204:207], v[18:21]
	v_mfma_f32_16x16x32_bf16 v[6:9], v[220:223], v[212:215], v[6:9]
	v_mfma_f32_16x16x32_bf16 v[2:5], v[228:231], v[212:215], v[2:5]
	s_barrier
	s_cbranch_scc0 .LBB0_742

.LBB0_805:
	s_add_u32 s0, s0, 0x80
	s_addc_u32 s1, s1, 0
	s_add_u32 s12, s4, 0x100
	s_addc_u32 s13, s5, 0
	s_mov_b32 s4, 0
	s_waitcnt vmcnt(0)
	s_add_i32 s27, s4, 2
	s_add_u32 s10, s0, 0x80
	s_addc_u32 s5, s1, 0
	s_add_i32 s28, 0, 0x10000
	ds_read_b128 v[142:145], v248
	ds_read_b128 v[146:149], v248 offset:1024
	ds_read_b128 v[150:153], v248 offset:2048
	ds_read_b128 v[154:157], v248 offset:3072
	s_cmp_eq_u32 s48, s4
	s_cselect_b32 s4, s22, s10
	s_cselect_b32 s5, s23, s5
	s_cselect_b32 s11, s25, s13
	s_cselect_b32 s10, s24, s12
	s_add_i32 m0, s35, 0xc000
	ds_read_b128 v[158:161], v172
	ds_read_b128 v[162:165], v172 offset:1024
	ds_read_b128 v[166:169], v172 offset:2048
	ds_read_b128 v[174:177], v172 offset:3072
	ds_read_b128 v[178:181], v172 offset:4096
	ds_read_b128 v[182:185], v172 offset:5120
	ds_read_b128 v[204:207], v172 offset:6144
	ds_read_b128 v[208:211], v172 offset:7168
	global_load_lds_dwordx4 v138, s[0:1]
	s_add_i32 m0, s35, 0xe000
	s_nop 0
	global_load_lds_dwordx4 v140, s[0:1]
	s_waitcnt lgkmcnt(8)
	s_barrier
	s_waitcnt lgkmcnt(0)
	v_mfma_f32_16x16x32_bf16 v[126:129], v[142:145], v[158:161], 0
	v_mfma_f32_16x16x32_bf16 v[122:125], v[150:153], v[158:161], 0
	v_mfma_f32_16x16x32_bf16 v[110:113], v[142:145], v[166:169], 0
	v_mfma_f32_16x16x32_bf16 v[106:109], v[150:153], v[166:169], 0
	v_mfma_f32_16x16x32_bf16 v[94:97], v[142:145], v[178:181], 0
	v_mfma_f32_16x16x32_bf16 v[90:93], v[150:153], v[178:181], 0
	v_mfma_f32_16x16x32_bf16 v[78:81], v[142:145], v[204:207], 0
	v_mfma_f32_16x16x32_bf16 v[74:77], v[150:153], v[204:207], 0
	v_mfma_f32_16x16x32_bf16 v[126:129], v[146:149], v[162:165], v[126:129]
	v_mfma_f32_16x16x32_bf16 v[122:125], v[154:157], v[162:165], v[122:125]
	v_mfma_f32_16x16x32_bf16 v[110:113], v[146:149], v[174:177], v[110:113]
	v_mfma_f32_16x16x32_bf16 v[106:109], v[154:157], v[174:177], v[106:109]
	v_mfma_f32_16x16x32_bf16 v[94:97], v[146:149], v[182:185], v[94:97]
	v_mfma_f32_16x16x32_bf16 v[90:93], v[154:157], v[182:185], v[90:93]
	v_mfma_f32_16x16x32_bf16 v[78:81], v[146:149], v[208:211], v[78:81]
	v_mfma_f32_16x16x32_bf16 v[74:77], v[154:157], v[208:211], v[74:77]
	s_barrier
	s_add_i32 s29, 0, 0x14000
	s_add_i32 s28, s28, s34
	s_add_u32 s78, s10, s6
	s_addc_u32 s79, s11, s7
	s_mov_b32 m0, s28
	ds_read_b128 v[212:215], v248 offset:16384
	ds_read_b128 v[216:219], v248 offset:17408
	ds_read_b128 v[220:223], v248 offset:18432
	ds_read_b128 v[224:227], v248 offset:19456
	global_load_lds_dwordx4 v132, s[10:11]
	s_add_i32 m0, s28, 0x2000
	s_nop 0
	global_load_lds_dwordx4 v136, s[10:11]
	s_barrier
	s_waitcnt lgkmcnt(0)
	v_mfma_f32_16x16x32_bf16 v[118:121], v[212:215], v[158:161], 0
	v_mfma_f32_16x16x32_bf16 v[114:117], v[220:223], v[158:161], 0
	v_mfma_f32_16x16x32_bf16 v[102:105], v[212:215], v[166:169], 0
	v_mfma_f32_16x16x32_bf16 v[98:101], v[220:223], v[166:169], 0
	v_mfma_f32_16x16x32_bf16 v[86:89], v[212:215], v[178:181], 0
	v_mfma_f32_16x16x32_bf16 v[82:85], v[220:223], v[178:181], 0
	v_mfma_f32_16x16x32_bf16 v[70:73], v[212:215], v[204:207], 0
	v_mfma_f32_16x16x32_bf16 v[66:69], v[220:223], v[204:207], 0
	v_mfma_f32_16x16x32_bf16 v[118:121], v[216:219], v[162:165], v[118:121]
	v_mfma_f32_16x16x32_bf16 v[114:117], v[224:227], v[162:165], v[114:117]
	v_mfma_f32_16x16x32_bf16 v[102:105], v[216:219], v[174:177], v[102:105]
	v_mfma_f32_16x16x32_bf16 v[98:101], v[224:227], v[174:177], v[98:101]
	v_mfma_f32_16x16x32_bf16 v[86:89], v[216:219], v[182:185], v[86:89]
	v_mfma_f32_16x16x32_bf16 v[82:85], v[224:227], v[182:185], v[82:85]
	v_mfma_f32_16x16x32_bf16 v[70:73], v[216:219], v[208:211], v[70:73]
	v_mfma_f32_16x16x32_bf16 v[66:69], v[224:227], v[208:211], v[66:69]
	s_barrier
	s_mov_b32 m0, s35
	s_add_u32 s80, s4, s6
	s_addc_u32 s81, s5, s7
	ds_read_b128 v[158:161], v172 offset:16384
	ds_read_b128 v[162:165], v172 offset:17408
	ds_read_b128 v[166:169], v172 offset:18432
	ds_read_b128 v[174:177], v172 offset:19456
	ds_read_b128 v[178:181], v172 offset:20480
	ds_read_b128 v[182:185], v172 offset:21504
	ds_read_b128 v[204:207], v172 offset:22528
	ds_read_b128 v[208:211], v172 offset:23552
	global_load_lds_dwordx4 v130, s[4:5]
	s_mov_b32 m0, s40
	s_nop 0
	global_load_lds_dwordx4 v134, s[4:5]
	s_barrier
	s_waitcnt lgkmcnt(0)
	v_mfma_f32_16x16x32_bf16 v[62:65], v[142:145], v[158:161], 0
	v_mfma_f32_16x16x32_bf16 v[58:61], v[150:153], v[158:161], 0
	v_mfma_f32_16x16x32_bf16 v[46:49], v[142:145], v[166:169], 0
	v_mfma_f32_16x16x32_bf16 v[42:45], v[150:153], v[166:169], 0
	v_mfma_f32_16x16x32_bf16 v[30:33], v[142:145], v[178:181], 0
	v_mfma_f32_16x16x32_bf16 v[26:29], v[150:153], v[178:181], 0
	v_mfma_f32_16x16x32_bf16 v[14:17], v[142:145], v[204:207], 0
	v_mfma_f32_16x16x32_bf16 v[10:13], v[150:153], v[204:207], 0
	v_mfma_f32_16x16x32_bf16 v[62:65], v[146:149], v[162:165], v[62:65]
	v_mfma_f32_16x16x32_bf16 v[58:61], v[154:157], v[162:165], v[58:61]
	v_mfma_f32_16x16x32_bf16 v[46:49], v[146:149], v[174:177], v[46:49]
	v_mfma_f32_16x16x32_bf16 v[42:45], v[154:157], v[174:177], v[42:45]
	v_mfma_f32_16x16x32_bf16 v[30:33], v[146:149], v[182:185], v[30:33]
	v_mfma_f32_16x16x32_bf16 v[26:29], v[154:157], v[182:185], v[26:29]
	v_mfma_f32_16x16x32_bf16 v[14:17], v[146:149], v[208:211], v[14:17]
	v_mfma_f32_16x16x32_bf16 v[10:13], v[154:157], v[208:211], v[10:13]
	s_barrier
	s_add_u32 s10, s10, s92
	s_addc_u32 s11, s11, 0
	s_add_i32 s28, s29, s34
	s_add_u32 s58, s10, s6
	s_addc_u32 s59, s11, s7
	s_mov_b32 m0, s28
	s_nop 0
	global_load_lds_dwordx4 v132, s[10:11]
	s_add_i32 m0, s28, 0x2000
	s_nop 0
	global_load_lds_dwordx4 v136, s[10:11]
	s_waitcnt vmcnt(6)
	s_barrier
	v_mfma_f32_16x16x32_bf16 v[54:57], v[212:215], v[158:161], 0
	v_mfma_f32_16x16x32_bf16 v[50:53], v[220:223], v[158:161], 0
	v_mfma_f32_16x16x32_bf16 v[38:41], v[212:215], v[166:169], 0
	v_mfma_f32_16x16x32_bf16 v[34:37], v[220:223], v[166:169], 0
	v_mfma_f32_16x16x32_bf16 v[22:25], v[212:215], v[178:181], 0
	v_mfma_f32_16x16x32_bf16 v[18:21], v[220:223], v[178:181], 0
	v_mfma_f32_16x16x32_bf16 v[6:9], v[212:215], v[204:207], 0
	v_mfma_f32_16x16x32_bf16 v[2:5], v[220:223], v[204:207], 0
	v_mfma_f32_16x16x32_bf16 v[54:57], v[216:219], v[162:165], v[54:57]
	v_mfma_f32_16x16x32_bf16 v[50:53], v[224:227], v[162:165], v[50:53]
	v_mfma_f32_16x16x32_bf16 v[38:41], v[216:219], v[174:177], v[38:41]
	v_mfma_f32_16x16x32_bf16 v[34:37], v[224:227], v[174:177], v[34:37]
	v_mfma_f32_16x16x32_bf16 v[22:25], v[216:219], v[182:185], v[22:25]
	v_mfma_f32_16x16x32_bf16 v[18:21], v[224:227], v[182:185], v[18:21]
	v_mfma_f32_16x16x32_bf16 v[6:9], v[216:219], v[208:211], v[6:9]
	v_mfma_f32_16x16x32_bf16 v[2:5], v[224:227], v[208:211], v[2:5]
	s_barrier
	s_add_i32 s10, 0, 0x18000
	ds_read_b128 v[142:145], v248 offset:32768
	ds_read_b128 v[146:149], v248 offset:33792
	ds_read_b128 v[150:153], v248 offset:34816
	ds_read_b128 v[154:157], v248 offset:35840
	s_add_u32 s4, s4, s92
	s_addc_u32 s5, s5, 0
	s_mov_b32 m0, s41
	ds_read_b128 v[158:161], v172 offset:32768
	ds_read_b128 v[162:165], v172 offset:33792
	ds_read_b128 v[166:169], v172 offset:34816
	ds_read_b128 v[174:177], v172 offset:35840
	ds_read_b128 v[178:181], v172 offset:36864
	ds_read_b128 v[182:185], v172 offset:37888
	ds_read_b128 v[204:207], v172 offset:38912
	ds_read_b128 v[208:211], v172 offset:39936
	global_load_lds_dwordx4 v130, s[4:5]
	s_mov_b32 m0, s42
	s_nop 0
	global_load_lds_dwordx4 v134, s[4:5]
	s_waitcnt lgkmcnt(8)
	s_barrier
	s_waitcnt lgkmcnt(0)
	v_mfma_f32_16x16x32_bf16 v[126:129], v[142:145], v[158:161], v[126:129]
	v_mfma_f32_16x16x32_bf16 v[122:125], v[150:153], v[158:161], v[122:125]
	v_mfma_f32_16x16x32_bf16 v[110:113], v[142:145], v[166:169], v[110:113]
	v_mfma_f32_16x16x32_bf16 v[106:109], v[150:153], v[166:169], v[106:109]
	v_mfma_f32_16x16x32_bf16 v[94:97], v[142:145], v[178:181], v[94:97]
	v_mfma_f32_16x16x32_bf16 v[90:93], v[150:153], v[178:181], v[90:93]
	v_mfma_f32_16x16x32_bf16 v[78:81], v[142:145], v[204:207], v[78:81]
	v_mfma_f32_16x16x32_bf16 v[74:77], v[150:153], v[204:207], v[74:77]
	v_mfma_f32_16x16x32_bf16 v[126:129], v[146:149], v[162:165], v[126:129]
	v_mfma_f32_16x16x32_bf16 v[122:125], v[154:157], v[162:165], v[122:125]
	v_mfma_f32_16x16x32_bf16 v[110:113], v[146:149], v[174:177], v[110:113]
	v_mfma_f32_16x16x32_bf16 v[106:109], v[154:157], v[174:177], v[106:109]
	v_mfma_f32_16x16x32_bf16 v[94:97], v[146:149], v[182:185], v[94:97]
	v_mfma_f32_16x16x32_bf16 v[90:93], v[154:157], v[182:185], v[90:93]
	v_mfma_f32_16x16x32_bf16 v[78:81], v[146:149], v[208:211], v[78:81]
	v_mfma_f32_16x16x32_bf16 v[74:77], v[154:157], v[208:211], v[74:77]
	s_barrier
	s_add_i32 s4, 0, 0x1c000
	s_add_i32 s5, s10, s34
	s_mov_b32 m0, s5
	ds_read_b128 v[212:215], v248 offset:49152
	ds_read_b128 v[216:219], v248 offset:50176
	ds_read_b128 v[220:223], v248 offset:51200
	ds_read_b128 v[224:227], v248 offset:52224
	global_load_lds_dwordx4 v132, s[78:79]
	s_add_i32 m0, s5, 0x2000
	s_nop 0
	global_load_lds_dwordx4 v136, s[78:79]
	s_barrier
	s_waitcnt lgkmcnt(0)
	v_mfma_f32_16x16x32_bf16 v[118:121], v[212:215], v[158:161], v[118:121]
	v_mfma_f32_16x16x32_bf16 v[114:117], v[220:223], v[158:161], v[114:117]
	v_mfma_f32_16x16x32_bf16 v[102:105], v[212:215], v[166:169], v[102:105]
	v_mfma_f32_16x16x32_bf16 v[98:101], v[220:223], v[166:169], v[98:101]
	v_mfma_f32_16x16x32_bf16 v[86:89], v[212:215], v[178:181], v[86:89]
	v_mfma_f32_16x16x32_bf16 v[82:85], v[220:223], v[178:181], v[82:85]
	v_mfma_f32_16x16x32_bf16 v[70:73], v[212:215], v[204:207], v[70:73]
	v_mfma_f32_16x16x32_bf16 v[66:69], v[220:223], v[204:207], v[66:69]
	v_mfma_f32_16x16x32_bf16 v[118:121], v[216:219], v[162:165], v[118:121]
	v_mfma_f32_16x16x32_bf16 v[114:117], v[224:227], v[162:165], v[114:117]
	v_mfma_f32_16x16x32_bf16 v[102:105], v[216:219], v[174:177], v[102:105]
	v_mfma_f32_16x16x32_bf16 v[98:101], v[224:227], v[174:177], v[98:101]
	v_mfma_f32_16x16x32_bf16 v[86:89], v[216:219], v[182:185], v[86:89]
	v_mfma_f32_16x16x32_bf16 v[82:85], v[224:227], v[182:185], v[82:85]
	v_mfma_f32_16x16x32_bf16 v[70:73], v[216:219], v[208:211], v[70:73]
	v_mfma_f32_16x16x32_bf16 v[66:69], v[224:227], v[208:211], v[66:69]
	s_barrier
	s_mov_b32 m0, s46
	ds_read_b128 v[158:161], v172 offset:49152
	ds_read_b128 v[162:165], v172 offset:50176
	ds_read_b128 v[166:169], v172 offset:51200
	ds_read_b128 v[174:177], v172 offset:52224
	ds_read_b128 v[178:181], v172 offset:53248
	ds_read_b128 v[182:185], v172 offset:54272
	ds_read_b128 v[204:207], v172 offset:55296
	ds_read_b128 v[208:211], v172 offset:56320
	global_load_lds_dwordx4 v130, s[80:81]
	s_mov_b32 m0, s47
	s_nop 0
	global_load_lds_dwordx4 v134, s[80:81]
	s_barrier
	s_waitcnt lgkmcnt(0)
	v_mfma_f32_16x16x32_bf16 v[62:65], v[142:145], v[158:161], v[62:65]
	v_mfma_f32_16x16x32_bf16 v[58:61], v[150:153], v[158:161], v[58:61]
	v_mfma_f32_16x16x32_bf16 v[46:49], v[142:145], v[166:169], v[46:49]
	v_mfma_f32_16x16x32_bf16 v[42:45], v[150:153], v[166:169], v[42:45]
	v_mfma_f32_16x16x32_bf16 v[30:33], v[142:145], v[178:181], v[30:33]
	v_mfma_f32_16x16x32_bf16 v[26:29], v[150:153], v[178:181], v[26:29]
	v_mfma_f32_16x16x32_bf16 v[14:17], v[142:145], v[204:207], v[14:17]
	v_mfma_f32_16x16x32_bf16 v[10:13], v[150:153], v[204:207], v[10:13]
	v_mfma_f32_16x16x32_bf16 v[62:65], v[146:149], v[162:165], v[62:65]
	v_mfma_f32_16x16x32_bf16 v[58:61], v[154:157], v[162:165], v[58:61]
	v_mfma_f32_16x16x32_bf16 v[46:49], v[146:149], v[174:177], v[46:49]
	v_mfma_f32_16x16x32_bf16 v[42:45], v[154:157], v[174:177], v[42:45]
	v_mfma_f32_16x16x32_bf16 v[30:33], v[146:149], v[182:185], v[30:33]
	v_mfma_f32_16x16x32_bf16 v[26:29], v[154:157], v[182:185], v[26:29]
	v_mfma_f32_16x16x32_bf16 v[14:17], v[146:149], v[208:211], v[14:17]
	v_mfma_f32_16x16x32_bf16 v[10:13], v[154:157], v[208:211], v[10:13]
	s_barrier
	s_add_i32 s4, s4, s34
	s_mov_b32 m0, s4
	s_nop 0
	global_load_lds_dwordx4 v132, s[58:59]
	s_add_i32 m0, s4, 0x2000
	s_nop 0
	global_load_lds_dwordx4 v136, s[58:59]
	s_add_u32 s0, s0, 0x100
	s_addc_u32 s1, s1, 0
	s_add_u32 s12, s12, 0x100
	s_addc_u32 s13, s13, 0
	s_cmp_ge_u32 s27, s43
	s_mov_b32 s4, s27
	s_waitcnt vmcnt(6)
	s_barrier
	v_mfma_f32_16x16x32_bf16 v[54:57], v[212:215], v[158:161], v[54:57]
	v_mfma_f32_16x16x32_bf16 v[50:53], v[220:223], v[158:161], v[50:53]
	v_mfma_f32_16x16x32_bf16 v[38:41], v[212:215], v[166:169], v[38:41]
	v_mfma_f32_16x16x32_bf16 v[34:37], v[220:223], v[166:169], v[34:37]
	v_mfma_f32_16x16x32_bf16 v[22:25], v[212:215], v[178:181], v[22:25]
	v_mfma_f32_16x16x32_bf16 v[18:21], v[220:223], v[178:181], v[18:21]
	v_mfma_f32_16x16x32_bf16 v[6:9], v[212:215], v[204:207], v[6:9]
	v_mfma_f32_16x16x32_bf16 v[2:5], v[220:223], v[204:207], v[2:5]
	v_mfma_f32_16x16x32_bf16 v[54:57], v[216:219], v[162:165], v[54:57]
	v_mfma_f32_16x16x32_bf16 v[50:53], v[224:227], v[162:165], v[50:53]
	v_mfma_f32_16x16x32_bf16 v[38:41], v[216:219], v[174:177], v[38:41]
	v_mfma_f32_16x16x32_bf16 v[34:37], v[224:227], v[174:177], v[34:37]
	v_mfma_f32_16x16x32_bf16 v[22:25], v[216:219], v[182:185], v[22:25]
	v_mfma_f32_16x16x32_bf16 v[18:21], v[224:227], v[182:185], v[18:21]
	v_mfma_f32_16x16x32_bf16 v[6:9], v[216:219], v[208:211], v[6:9]
	v_mfma_f32_16x16x32_bf16 v[2:5], v[224:227], v[208:211], v[2:5]
	s_barrier
	s_cbranch_scc1 .Lkexit_806
.LBB0_806:
	s_add_i32 s27, s4, 2
	s_add_u32 s10, s0, 0x80
	s_addc_u32 s5, s1, 0
	s_add_i32 s28, 0, 0x10000
	ds_read_b128 v[142:145], v248
	ds_read_b128 v[146:149], v248 offset:1024
	ds_read_b128 v[150:153], v248 offset:2048
	ds_read_b128 v[154:157], v248 offset:3072
	s_cmp_eq_u32 s48, s4
	s_cselect_b32 s4, s22, s10
	s_cselect_b32 s5, s23, s5
	s_cselect_b32 s11, s25, s13
	s_cselect_b32 s10, s24, s12
	s_add_i32 m0, s35, 0xc000
	ds_read_b128 v[158:161], v172
	ds_read_b128 v[162:165], v172 offset:1024
	ds_read_b128 v[166:169], v172 offset:2048
	ds_read_b128 v[174:177], v172 offset:3072
	ds_read_b128 v[178:181], v172 offset:4096
	ds_read_b128 v[182:185], v172 offset:5120
	ds_read_b128 v[204:207], v172 offset:6144
	ds_read_b128 v[208:211], v172 offset:7168
	global_load_lds_dwordx4 v138, s[0:1]
	s_add_i32 m0, s35, 0xe000
	s_nop 0
	global_load_lds_dwordx4 v140, s[0:1]
	s_waitcnt lgkmcnt(8)
	s_barrier
	s_waitcnt lgkmcnt(0)
	v_mfma_f32_16x16x32_bf16 v[126:129], v[142:145], v[158:161], v[126:129]
	v_mfma_f32_16x16x32_bf16 v[122:125], v[150:153], v[158:161], v[122:125]
	v_mfma_f32_16x16x32_bf16 v[110:113], v[142:145], v[166:169], v[110:113]
	v_mfma_f32_16x16x32_bf16 v[106:109], v[150:153], v[166:169], v[106:109]
	v_mfma_f32_16x16x32_bf16 v[94:97], v[142:145], v[178:181], v[94:97]
	v_mfma_f32_16x16x32_bf16 v[90:93], v[150:153], v[178:181], v[90:93]
	v_mfma_f32_16x16x32_bf16 v[78:81], v[142:145], v[204:207], v[78:81]
	v_mfma_f32_16x16x32_bf16 v[74:77], v[150:153], v[204:207], v[74:77]
	v_mfma_f32_16x16x32_bf16 v[126:129], v[146:149], v[162:165], v[126:129]
	v_mfma_f32_16x16x32_bf16 v[122:125], v[154:157], v[162:165], v[122:125]
	v_mfma_f32_16x16x32_bf16 v[110:113], v[146:149], v[174:177], v[110:113]
	v_mfma_f32_16x16x32_bf16 v[106:109], v[154:157], v[174:177], v[106:109]
	v_mfma_f32_16x16x32_bf16 v[94:97], v[146:149], v[182:185], v[94:97]
	v_mfma_f32_16x16x32_bf16 v[90:93], v[154:157], v[182:185], v[90:93]
	v_mfma_f32_16x16x32_bf16 v[78:81], v[146:149], v[208:211], v[78:81]
	v_mfma_f32_16x16x32_bf16 v[74:77], v[154:157], v[208:211], v[74:77]
	s_barrier
	s_add_i32 s29, 0, 0x14000
	s_add_i32 s28, s28, s34
	s_add_u32 s78, s10, s6
	s_addc_u32 s79, s11, s7
	s_mov_b32 m0, s28
	ds_read_b128 v[212:215], v248 offset:16384
	ds_read_b128 v[216:219], v248 offset:17408
	ds_read_b128 v[220:223], v248 offset:18432
	ds_read_b128 v[224:227], v248 offset:19456
	global_load_lds_dwordx4 v132, s[10:11]
	s_add_i32 m0, s28, 0x2000
	s_nop 0
	global_load_lds_dwordx4 v136, s[10:11]
	s_barrier
	s_waitcnt lgkmcnt(0)
	v_mfma_f32_16x16x32_bf16 v[118:121], v[212:215], v[158:161], v[118:121]
	v_mfma_f32_16x16x32_bf16 v[114:117], v[220:223], v[158:161], v[114:117]
	v_mfma_f32_16x16x32_bf16 v[102:105], v[212:215], v[166:169], v[102:105]
	v_mfma_f32_16x16x32_bf16 v[98:101], v[220:223], v[166:169], v[98:101]
	v_mfma_f32_16x16x32_bf16 v[86:89], v[212:215], v[178:181], v[86:89]
	v_mfma_f32_16x16x32_bf16 v[82:85], v[220:223], v[178:181], v[82:85]
	v_mfma_f32_16x16x32_bf16 v[70:73], v[212:215], v[204:207], v[70:73]
	v_mfma_f32_16x16x32_bf16 v[66:69], v[220:223], v[204:207], v[66:69]
	v_mfma_f32_16x16x32_bf16 v[118:121], v[216:219], v[162:165], v[118:121]
	v_mfma_f32_16x16x32_bf16 v[114:117], v[224:227], v[162:165], v[114:117]
	v_mfma_f32_16x16x32_bf16 v[102:105], v[216:219], v[174:177], v[102:105]
	v_mfma_f32_16x16x32_bf16 v[98:101], v[224:227], v[174:177], v[98:101]
	v_mfma_f32_16x16x32_bf16 v[86:89], v[216:219], v[182:185], v[86:89]
	v_mfma_f32_16x16x32_bf16 v[82:85], v[224:227], v[182:185], v[82:85]
	v_mfma_f32_16x16x32_bf16 v[70:73], v[216:219], v[208:211], v[70:73]
	v_mfma_f32_16x16x32_bf16 v[66:69], v[224:227], v[208:211], v[66:69]
	s_barrier
	s_mov_b32 m0, s35
	s_add_u32 s80, s4, s6
	s_addc_u32 s81, s5, s7
	ds_read_b128 v[158:161], v172 offset:16384
	ds_read_b128 v[162:165], v172 offset:17408
	ds_read_b128 v[166:169], v172 offset:18432
	ds_read_b128 v[174:177], v172 offset:19456
	ds_read_b128 v[178:181], v172 offset:20480
	ds_read_b128 v[182:185], v172 offset:21504
	ds_read_b128 v[204:207], v172 offset:22528
	ds_read_b128 v[208:211], v172 offset:23552
	global_load_lds_dwordx4 v130, s[4:5]
	s_mov_b32 m0, s40
	s_nop 0
	global_load_lds_dwordx4 v134, s[4:5]
	s_barrier
	s_waitcnt lgkmcnt(0)
	v_mfma_f32_16x16x32_bf16 v[62:65], v[142:145], v[158:161], v[62:65]
	v_mfma_f32_16x16x32_bf16 v[58:61], v[150:153], v[158:161], v[58:61]
	v_mfma_f32_16x16x32_bf16 v[46:49], v[142:145], v[166:169], v[46:49]
	v_mfma_f32_16x16x32_bf16 v[42:45], v[150:153], v[166:169], v[42:45]
	v_mfma_f32_16x16x32_bf16 v[30:33], v[142:145], v[178:181], v[30:33]
	v_mfma_f32_16x16x32_bf16 v[26:29], v[150:153], v[178:181], v[26:29]
	v_mfma_f32_16x16x32_bf16 v[14:17], v[142:145], v[204:207], v[14:17]
	v_mfma_f32_16x16x32_bf16 v[10:13], v[150:153], v[204:207], v[10:13]
	v_mfma_f32_16x16x32_bf16 v[62:65], v[146:149], v[162:165], v[62:65]
	v_mfma_f32_16x16x32_bf16 v[58:61], v[154:157], v[162:165], v[58:61]
	v_mfma_f32_16x16x32_bf16 v[46:49], v[146:149], v[174:177], v[46:49]
	v_mfma_f32_16x16x32_bf16 v[42:45], v[154:157], v[174:177], v[42:45]
	v_mfma_f32_16x16x32_bf16 v[30:33], v[146:149], v[182:185], v[30:33]
	v_mfma_f32_16x16x32_bf16 v[26:29], v[154:157], v[182:185], v[26:29]
	v_mfma_f32_16x16x32_bf16 v[14:17], v[146:149], v[208:211], v[14:17]
	v_mfma_f32_16x16x32_bf16 v[10:13], v[154:157], v[208:211], v[10:13]
	s_barrier
	s_add_u32 s10, s10, s92
	s_addc_u32 s11, s11, 0
	s_add_i32 s28, s29, s34
	s_add_u32 s58, s10, s6
	s_addc_u32 s59, s11, s7
	s_mov_b32 m0, s28
	s_nop 0
	global_load_lds_dwordx4 v132, s[10:11]
	s_add_i32 m0, s28, 0x2000
	s_nop 0
	global_load_lds_dwordx4 v136, s[10:11]
	s_waitcnt vmcnt(6)
	s_barrier
	v_mfma_f32_16x16x32_bf16 v[54:57], v[212:215], v[158:161], v[54:57]
	v_mfma_f32_16x16x32_bf16 v[50:53], v[220:223], v[158:161], v[50:53]
	v_mfma_f32_16x16x32_bf16 v[38:41], v[212:215], v[166:169], v[38:41]
	v_mfma_f32_16x16x32_bf16 v[34:37], v[220:223], v[166:169], v[34:37]
	v_mfma_f32_16x16x32_bf16 v[22:25], v[212:215], v[178:181], v[22:25]
	v_mfma_f32_16x16x32_bf16 v[18:21], v[220:223], v[178:181], v[18:21]
	v_mfma_f32_16x16x32_bf16 v[6:9], v[212:215], v[204:207], v[6:9]
	v_mfma_f32_16x16x32_bf16 v[2:5], v[220:223], v[204:207], v[2:5]
	v_mfma_f32_16x16x32_bf16 v[54:57], v[216:219], v[162:165], v[54:57]
	v_mfma_f32_16x16x32_bf16 v[50:53], v[224:227], v[162:165], v[50:53]
	v_mfma_f32_16x16x32_bf16 v[38:41], v[216:219], v[174:177], v[38:41]
	v_mfma_f32_16x16x32_bf16 v[34:37], v[224:227], v[174:177], v[34:37]
	v_mfma_f32_16x16x32_bf16 v[22:25], v[216:219], v[182:185], v[22:25]
	v_mfma_f32_16x16x32_bf16 v[18:21], v[224:227], v[182:185], v[18:21]
	v_mfma_f32_16x16x32_bf16 v[6:9], v[216:219], v[208:211], v[6:9]
	v_mfma_f32_16x16x32_bf16 v[2:5], v[224:227], v[208:211], v[2:5]
	s_barrier
	s_add_i32 s10, 0, 0x18000
	ds_read_b128 v[142:145], v248 offset:32768
	ds_read_b128 v[146:149], v248 offset:33792
	ds_read_b128 v[150:153], v248 offset:34816
	ds_read_b128 v[154:157], v248 offset:35840
	s_add_u32 s4, s4, s92
	s_addc_u32 s5, s5, 0
	s_mov_b32 m0, s41
	ds_read_b128 v[158:161], v172 offset:32768
	ds_read_b128 v[162:165], v172 offset:33792
	ds_read_b128 v[166:169], v172 offset:34816
	ds_read_b128 v[174:177], v172 offset:35840
	ds_read_b128 v[178:181], v172 offset:36864
	ds_read_b128 v[182:185], v172 offset:37888
	ds_read_b128 v[204:207], v172 offset:38912
	ds_read_b128 v[208:211], v172 offset:39936
	global_load_lds_dwordx4 v130, s[4:5]
	s_mov_b32 m0, s42
	s_nop 0
	global_load_lds_dwordx4 v134, s[4:5]
	s_waitcnt lgkmcnt(8)
	s_barrier
	s_waitcnt lgkmcnt(0)
	v_mfma_f32_16x16x32_bf16 v[126:129], v[142:145], v[158:161], v[126:129]
	v_mfma_f32_16x16x32_bf16 v[122:125], v[150:153], v[158:161], v[122:125]
	v_mfma_f32_16x16x32_bf16 v[110:113], v[142:145], v[166:169], v[110:113]
	v_mfma_f32_16x16x32_bf16 v[106:109], v[150:153], v[166:169], v[106:109]
	v_mfma_f32_16x16x32_bf16 v[94:97], v[142:145], v[178:181], v[94:97]
	v_mfma_f32_16x16x32_bf16 v[90:93], v[150:153], v[178:181], v[90:93]
	v_mfma_f32_16x16x32_bf16 v[78:81], v[142:145], v[204:207], v[78:81]
	v_mfma_f32_16x16x32_bf16 v[74:77], v[150:153], v[204:207], v[74:77]
	v_mfma_f32_16x16x32_bf16 v[126:129], v[146:149], v[162:165], v[126:129]
	v_mfma_f32_16x16x32_bf16 v[122:125], v[154:157], v[162:165], v[122:125]
	v_mfma_f32_16x16x32_bf16 v[110:113], v[146:149], v[174:177], v[110:113]
	v_mfma_f32_16x16x32_bf16 v[106:109], v[154:157], v[174:177], v[106:109]
	v_mfma_f32_16x16x32_bf16 v[94:97], v[146:149], v[182:185], v[94:97]
	v_mfma_f32_16x16x32_bf16 v[90:93], v[154:157], v[182:185], v[90:93]
	v_mfma_f32_16x16x32_bf16 v[78:81], v[146:149], v[208:211], v[78:81]
	v_mfma_f32_16x16x32_bf16 v[74:77], v[154:157], v[208:211], v[74:77]
	s_barrier
	s_add_i32 s4, 0, 0x1c000
	s_add_i32 s5, s10, s34
	s_mov_b32 m0, s5
	ds_read_b128 v[212:215], v248 offset:49152
	ds_read_b128 v[216:219], v248 offset:50176
	ds_read_b128 v[220:223], v248 offset:51200
	ds_read_b128 v[224:227], v248 offset:52224
	global_load_lds_dwordx4 v132, s[78:79]
	s_add_i32 m0, s5, 0x2000
	s_nop 0
	global_load_lds_dwordx4 v136, s[78:79]
	s_barrier
	s_waitcnt lgkmcnt(0)
	v_mfma_f32_16x16x32_bf16 v[118:121], v[212:215], v[158:161], v[118:121]
	v_mfma_f32_16x16x32_bf16 v[114:117], v[220:223], v[158:161], v[114:117]
	v_mfma_f32_16x16x32_bf16 v[102:105], v[212:215], v[166:169], v[102:105]
	v_mfma_f32_16x16x32_bf16 v[98:101], v[220:223], v[166:169], v[98:101]
	v_mfma_f32_16x16x32_bf16 v[86:89], v[212:215], v[178:181], v[86:89]
	v_mfma_f32_16x16x32_bf16 v[82:85], v[220:223], v[178:181], v[82:85]
	v_mfma_f32_16x16x32_bf16 v[70:73], v[212:215], v[204:207], v[70:73]
	v_mfma_f32_16x16x32_bf16 v[66:69], v[220:223], v[204:207], v[66:69]
	v_mfma_f32_16x16x32_bf16 v[118:121], v[216:219], v[162:165], v[118:121]
	v_mfma_f32_16x16x32_bf16 v[114:117], v[224:227], v[162:165], v[114:117]
	v_mfma_f32_16x16x32_bf16 v[102:105], v[216:219], v[174:177], v[102:105]
	v_mfma_f32_16x16x32_bf16 v[98:101], v[224:227], v[174:177], v[98:101]
	v_mfma_f32_16x16x32_bf16 v[86:89], v[216:219], v[182:185], v[86:89]
	v_mfma_f32_16x16x32_bf16 v[82:85], v[224:227], v[182:185], v[82:85]
	v_mfma_f32_16x16x32_bf16 v[70:73], v[216:219], v[208:211], v[70:73]
	v_mfma_f32_16x16x32_bf16 v[66:69], v[224:227], v[208:211], v[66:69]
	s_barrier
	s_mov_b32 m0, s46
	ds_read_b128 v[158:161], v172 offset:49152
	ds_read_b128 v[162:165], v172 offset:50176
	ds_read_b128 v[166:169], v172 offset:51200
	ds_read_b128 v[174:177], v172 offset:52224
	ds_read_b128 v[178:181], v172 offset:53248
	ds_read_b128 v[182:185], v172 offset:54272
	ds_read_b128 v[204:207], v172 offset:55296
	ds_read_b128 v[208:211], v172 offset:56320
	global_load_lds_dwordx4 v130, s[80:81]
	s_mov_b32 m0, s47
	s_nop 0
	global_load_lds_dwordx4 v134, s[80:81]
	s_barrier
	s_waitcnt lgkmcnt(0)
	v_mfma_f32_16x16x32_bf16 v[62:65], v[142:145], v[158:161], v[62:65]
	v_mfma_f32_16x16x32_bf16 v[58:61], v[150:153], v[158:161], v[58:61]
	v_mfma_f32_16x16x32_bf16 v[46:49], v[142:145], v[166:169], v[46:49]
	v_mfma_f32_16x16x32_bf16 v[42:45], v[150:153], v[166:169], v[42:45]
	v_mfma_f32_16x16x32_bf16 v[30:33], v[142:145], v[178:181], v[30:33]
	v_mfma_f32_16x16x32_bf16 v[26:29], v[150:153], v[178:181], v[26:29]
	v_mfma_f32_16x16x32_bf16 v[14:17], v[142:145], v[204:207], v[14:17]
	v_mfma_f32_16x16x32_bf16 v[10:13], v[150:153], v[204:207], v[10:13]
	v_mfma_f32_16x16x32_bf16 v[62:65], v[146:149], v[162:165], v[62:65]
	v_mfma_f32_16x16x32_bf16 v[58:61], v[154:157], v[162:165], v[58:61]
	v_mfma_f32_16x16x32_bf16 v[46:49], v[146:149], v[174:177], v[46:49]
	v_mfma_f32_16x16x32_bf16 v[42:45], v[154:157], v[174:177], v[42:45]
	v_mfma_f32_16x16x32_bf16 v[30:33], v[146:149], v[182:185], v[30:33]
	v_mfma_f32_16x16x32_bf16 v[26:29], v[154:157], v[182:185], v[26:29]
	v_mfma_f32_16x16x32_bf16 v[14:17], v[146:149], v[208:211], v[14:17]
	v_mfma_f32_16x16x32_bf16 v[10:13], v[154:157], v[208:211], v[10:13]
	s_barrier
	s_add_i32 s4, s4, s34
	s_mov_b32 m0, s4
	s_nop 0
	global_load_lds_dwordx4 v132, s[58:59]
	s_add_i32 m0, s4, 0x2000
	s_nop 0
	global_load_lds_dwordx4 v136, s[58:59]
	s_add_u32 s0, s0, 0x100
	s_addc_u32 s1, s1, 0
	s_add_u32 s12, s12, 0x100
	s_addc_u32 s13, s13, 0
	s_cmp_ge_u32 s27, s43
	s_mov_b32 s4, s27
	s_waitcnt vmcnt(6)
	s_barrier
	v_mfma_f32_16x16x32_bf16 v[54:57], v[212:215], v[158:161], v[54:57]
	v_mfma_f32_16x16x32_bf16 v[50:53], v[220:223], v[158:161], v[50:53]
	v_mfma_f32_16x16x32_bf16 v[38:41], v[212:215], v[166:169], v[38:41]
	v_mfma_f32_16x16x32_bf16 v[34:37], v[220:223], v[166:169], v[34:37]
	v_mfma_f32_16x16x32_bf16 v[22:25], v[212:215], v[178:181], v[22:25]
	v_mfma_f32_16x16x32_bf16 v[18:21], v[220:223], v[178:181], v[18:21]
	v_mfma_f32_16x16x32_bf16 v[6:9], v[212:215], v[204:207], v[6:9]
	v_mfma_f32_16x16x32_bf16 v[2:5], v[220:223], v[204:207], v[2:5]
	v_mfma_f32_16x16x32_bf16 v[54:57], v[216:219], v[162:165], v[54:57]
	v_mfma_f32_16x16x32_bf16 v[50:53], v[224:227], v[162:165], v[50:53]
	v_mfma_f32_16x16x32_bf16 v[38:41], v[216:219], v[174:177], v[38:41]
	v_mfma_f32_16x16x32_bf16 v[34:37], v[224:227], v[174:177], v[34:37]
	v_mfma_f32_16x16x32_bf16 v[22:25], v[216:219], v[182:185], v[22:25]
	v_mfma_f32_16x16x32_bf16 v[18:21], v[224:227], v[182:185], v[18:21]
	v_mfma_f32_16x16x32_bf16 v[6:9], v[216:219], v[208:211], v[6:9]
	v_mfma_f32_16x16x32_bf16 v[2:5], v[224:227], v[208:211], v[2:5]
	s_barrier
	s_cbranch_scc0 .LBB0_806
